# adds: P2 forward substitution without inline-asm pads and with three accumulation chains
# speedup vs baseline: 1.0163x; 1.0025x over previous
; template <int J> __device__ __forceinline__ void macb(float& s, int Lq, float x) { asm volatile("v_fmac_f32_dpp %0, %1, %2 row_newbcast:%3 row_mask:0xf bank_mask:0xf" : "+v"(s) : "v"(Lq), "v"(x), "n"(J)); }
; __device__ __forceinline__ void gdn_prep_item(const Params& p, unsigned char* lds, int item, u32x4 (&raw)[3][2][4], float& gpre, float& bpre, int next_item) {
;     ...
;     if (tid < 256 && !(p.flags & 16)) {
;         float* base = (tid < 128) ? (rhsK + tid) : (rhsV + (tid - 128));
;         float xs[64];
; #pragma unroll
;         for (int i = 0; i < 64; ++i) xs[i] = 0.f;
;         { const int L0[4] = {0, 0, 0, 0}; SolveRow<0>::run(Lm, base, xs, L0, base[0], lane & 15); }
; #pragma unroll
;         for (int i = 0; i < 64; ++i) base[i * RS] = xs[i];
.LBB0_198:
	s_andn2_saveexec_b64 s[20:21], s[20:21]
	s_cbranch_execz .LBB0_102
	ds_read2_b32 v[0:1], v154 offset1:132
	ds_read_b32 v2, v157 offset:256
	s_waitcnt lgkmcnt(1)
	v_add_f32_e32 v8, 0, v0
	ds_read_b32 v0, v157 offset:512
	ds_read_b32 v3, v154 offset:1056
	s_waitcnt lgkmcnt(2)
	v_fmac_f32_dpp v1, v2, v8 row_newbcast:0 row_mask:0xf bank_mask:0xf
	s_nop 0
	v_add_f32_e32 v9, 0, v1
	ds_read_b32 v1, v157 offset:768
	ds_read_b32 v2, v154 offset:1584
	v_mov_b32_e32 v4, v16
	s_waitcnt lgkmcnt(2)
	v_fmac_f32_dpp v3, v0, v8 row_newbcast:0 row_mask:0xf bank_mask:0xf
	v_fmac_f32_dpp v4, v0, v9 row_newbcast:1 row_mask:0xf bank_mask:0xf
	s_nop 0
	v_add_f32_e32 v10, v3, v4
	ds_read_b32 v0, v157 offset:1024
	ds_read_b32 v3, v154 offset:2112
	s_waitcnt lgkmcnt(2)
	v_mov_b32_e32 v231, v16
	v_fmac_f32_dpp v2, v1, v8 row_newbcast:0 row_mask:0xf bank_mask:0xf
	v_mov_b32_e32 v4, v16
	v_fmac_f32_dpp v4, v1, v9 row_newbcast:1 row_mask:0xf bank_mask:0xf
	v_fmac_f32_dpp v231, v1, v10 row_newbcast:2 row_mask:0xf bank_mask:0xf
	s_nop 0
	v_add_f32_e32 v11, v4, v2
	v_add_f32_e32 v11, v11, v231
	ds_read_b32 v1, v157 offset:1280
	ds_read_b32 v2, v154 offset:2640
	v_mov_b32_e32 v4, v16
	s_waitcnt lgkmcnt(2)
	v_mov_b32_e32 v231, v16
	v_fmac_f32_dpp v3, v0, v8 row_newbcast:0 row_mask:0xf bank_mask:0xf
	v_fmac_f32_dpp v4, v0, v9 row_newbcast:1 row_mask:0xf bank_mask:0xf
	v_fmac_f32_dpp v231, v0, v10 row_newbcast:2 row_mask:0xf bank_mask:0xf
	v_fmac_f32_dpp v3, v0, v11 row_newbcast:3 row_mask:0xf bank_mask:0xf
	s_nop 0
	v_add_f32_e32 v12, v3, v4
	v_add_f32_e32 v12, v12, v231
	ds_read_b32 v0, v157 offset:1536
	ds_read_b32 v3, v154 offset:3168
	s_waitcnt lgkmcnt(2)
	v_mov_b32_e32 v231, v16
	v_fmac_f32_dpp v2, v1, v8 row_newbcast:0 row_mask:0xf bank_mask:0xf
	v_mov_b32_e32 v4, v16
	v_fmac_f32_dpp v4, v1, v9 row_newbcast:1 row_mask:0xf bank_mask:0xf
	v_fmac_f32_dpp v231, v1, v10 row_newbcast:2 row_mask:0xf bank_mask:0xf
	v_fmac_f32_dpp v2, v1, v11 row_newbcast:3 row_mask:0xf bank_mask:0xf
	v_fmac_f32_dpp v4, v1, v12 row_newbcast:4 row_mask:0xf bank_mask:0xf
	s_nop 0
	v_add_f32_e32 v13, v4, v2
	v_add_f32_e32 v13, v13, v231
	ds_read_b32 v1, v157 offset:1792
	ds_read_b32 v2, v154 offset:3696
	v_mov_b32_e32 v4, v16
	s_waitcnt lgkmcnt(2)
	v_mov_b32_e32 v231, v16
	v_fmac_f32_dpp v3, v0, v8 row_newbcast:0 row_mask:0xf bank_mask:0xf
	v_fmac_f32_dpp v4, v0, v9 row_newbcast:1 row_mask:0xf bank_mask:0xf
	v_fmac_f32_dpp v231, v0, v10 row_newbcast:2 row_mask:0xf bank_mask:0xf
	v_fmac_f32_dpp v3, v0, v11 row_newbcast:3 row_mask:0xf bank_mask:0xf
	v_fmac_f32_dpp v4, v0, v12 row_newbcast:4 row_mask:0xf bank_mask:0xf
	v_fmac_f32_dpp v231, v0, v13 row_newbcast:5 row_mask:0xf bank_mask:0xf
	s_nop 0
	v_add_f32_e32 v14, v3, v4
	v_add_f32_e32 v14, v14, v231
	ds_read_b32 v0, v157 offset:2048
	ds_read_b32 v3, v154 offset:4224
	s_waitcnt lgkmcnt(2)
	v_mov_b32_e32 v231, v16
	v_fmac_f32_dpp v2, v1, v8 row_newbcast:0 row_mask:0xf bank_mask:0xf
	v_mov_b32_e32 v4, v16
	v_fmac_f32_dpp v4, v1, v9 row_newbcast:1 row_mask:0xf bank_mask:0xf
	v_fmac_f32_dpp v231, v1, v10 row_newbcast:2 row_mask:0xf bank_mask:0xf
	v_fmac_f32_dpp v2, v1, v11 row_newbcast:3 row_mask:0xf bank_mask:0xf
	v_fmac_f32_dpp v4, v1, v12 row_newbcast:4 row_mask:0xf bank_mask:0xf
	v_fmac_f32_dpp v231, v1, v13 row_newbcast:5 row_mask:0xf bank_mask:0xf
	v_fmac_f32_dpp v2, v1, v14 row_newbcast:6 row_mask:0xf bank_mask:0xf
	s_nop 0
	v_add_f32_e32 v15, v4, v2
	v_add_f32_e32 v15, v15, v231
	ds_read_b32 v1, v157 offset:2304
	ds_read_b32 v2, v154 offset:4752
	v_mov_b32_e32 v4, v16
	s_waitcnt lgkmcnt(2)
	v_mov_b32_e32 v231, v16
	v_fmac_f32_dpp v3, v0, v8 row_newbcast:0 row_mask:0xf bank_mask:0xf
	v_fmac_f32_dpp v4, v0, v9 row_newbcast:1 row_mask:0xf bank_mask:0xf
	v_fmac_f32_dpp v231, v0, v10 row_newbcast:2 row_mask:0xf bank_mask:0xf
	v_fmac_f32_dpp v3, v0, v11 row_newbcast:3 row_mask:0xf bank_mask:0xf
	v_fmac_f32_dpp v4, v0, v12 row_newbcast:4 row_mask:0xf bank_mask:0xf
	v_fmac_f32_dpp v231, v0, v13 row_newbcast:5 row_mask:0xf bank_mask:0xf
	v_fmac_f32_dpp v3, v0, v14 row_newbcast:6 row_mask:0xf bank_mask:0xf
	v_fmac_f32_dpp v4, v0, v15 row_newbcast:7 row_mask:0xf bank_mask:0xf
	s_nop 0
	v_add_f32_e32 v17, v3, v4
	v_add_f32_e32 v17, v17, v231
	ds_read_b32 v0, v157 offset:2560
	ds_read_b32 v3, v154 offset:5280
	s_waitcnt lgkmcnt(2)
	v_mov_b32_e32 v231, v16
	v_fmac_f32_dpp v2, v1, v8 row_newbcast:0 row_mask:0xf bank_mask:0xf
	v_mov_b32_e32 v4, v16
	v_fmac_f32_dpp v4, v1, v9 row_newbcast:1 row_mask:0xf bank_mask:0xf
	v_fmac_f32_dpp v231, v1, v10 row_newbcast:2 row_mask:0xf bank_mask:0xf
	v_fmac_f32_dpp v2, v1, v11 row_newbcast:3 row_mask:0xf bank_mask:0xf
	v_fmac_f32_dpp v4, v1, v12 row_newbcast:4 row_mask:0xf bank_mask:0xf
	v_fmac_f32_dpp v231, v1, v13 row_newbcast:5 row_mask:0xf bank_mask:0xf
	v_fmac_f32_dpp v2, v1, v14 row_newbcast:6 row_mask:0xf bank_mask:0xf
	v_fmac_f32_dpp v4, v1, v15 row_newbcast:7 row_mask:0xf bank_mask:0xf
	v_fmac_f32_dpp v231, v1, v17 row_newbcast:8 row_mask:0xf bank_mask:0xf
	s_nop 0
	v_add_f32_e32 v18, v4, v2
	v_add_f32_e32 v18, v18, v231
	ds_read_b32 v1, v157 offset:2816
	ds_read_b32 v2, v154 offset:5808
	v_mov_b32_e32 v4, v16
	s_waitcnt lgkmcnt(2)
	v_mov_b32_e32 v231, v16
	v_fmac_f32_dpp v3, v0, v8 row_newbcast:0 row_mask:0xf bank_mask:0xf
	v_fmac_f32_dpp v4, v0, v9 row_newbcast:1 row_mask:0xf bank_mask:0xf
	v_fmac_f32_dpp v231, v0, v10 row_newbcast:2 row_mask:0xf bank_mask:0xf
	v_fmac_f32_dpp v3, v0, v11 row_newbcast:3 row_mask:0xf bank_mask:0xf
	v_fmac_f32_dpp v4, v0, v12 row_newbcast:4 row_mask:0xf bank_mask:0xf
	v_fmac_f32_dpp v231, v0, v13 row_newbcast:5 row_mask:0xf bank_mask:0xf
	v_fmac_f32_dpp v3, v0, v14 row_newbcast:6 row_mask:0xf bank_mask:0xf
	v_fmac_f32_dpp v4, v0, v15 row_newbcast:7 row_mask:0xf bank_mask:0xf
	v_fmac_f32_dpp v231, v0, v17 row_newbcast:8 row_mask:0xf bank_mask:0xf
	v_fmac_f32_dpp v3, v0, v18 row_newbcast:9 row_mask:0xf bank_mask:0xf
	s_nop 0
	v_add_f32_e32 v19, v3, v4
	v_add_f32_e32 v19, v19, v231
	ds_read_b32 v0, v157 offset:3072
	ds_read_b32 v3, v154 offset:6336
	s_waitcnt lgkmcnt(2)
; template <int J> __device__ __forceinline__ void macb(float& s, int Lq, float x) { asm volatile("v_fmac_f32_dpp %0, %1, %2 row_newbcast:%3 row_mask:0xf bank_mask:0xf" : "+v"(s) : "v"(Lq), "v"(x), "n"(J)); }
; __device__ __forceinline__ void gdn_prep_item(const Params& p, unsigned char* lds, int item, u32x4 (&raw)[3][2][4], float& gpre, float& bpre, int next_item) {
;     ...
;     if (tid < 256 && !(p.flags & 16)) {
;         float* base = (tid < 128) ? (rhsK + tid) : (rhsV + (tid - 128));
;         float xs[64];
; #pragma unroll
;         for (int i = 0; i < 64; ++i) xs[i] = 0.f;
;         { const int L0[4] = {0, 0, 0, 0}; SolveRow<0>::run(Lm, base, xs, L0, base[0], lane & 15); }
; #pragma unroll
;         for (int i = 0; i < 64; ++i) base[i * RS] = xs[i];
	v_mov_b32_e32 v231, v16
	v_fmac_f32_dpp v2, v1, v8 row_newbcast:0 row_mask:0xf bank_mask:0xf
	v_mov_b32_e32 v4, v16
	v_fmac_f32_dpp v4, v1, v9 row_newbcast:1 row_mask:0xf bank_mask:0xf
	v_fmac_f32_dpp v231, v1, v10 row_newbcast:2 row_mask:0xf bank_mask:0xf
	v_fmac_f32_dpp v2, v1, v11 row_newbcast:3 row_mask:0xf bank_mask:0xf
	v_fmac_f32_dpp v4, v1, v12 row_newbcast:4 row_mask:0xf bank_mask:0xf
	v_fmac_f32_dpp v231, v1, v13 row_newbcast:5 row_mask:0xf bank_mask:0xf
	v_fmac_f32_dpp v2, v1, v14 row_newbcast:6 row_mask:0xf bank_mask:0xf
	v_fmac_f32_dpp v4, v1, v15 row_newbcast:7 row_mask:0xf bank_mask:0xf
	v_fmac_f32_dpp v231, v1, v17 row_newbcast:8 row_mask:0xf bank_mask:0xf
	v_fmac_f32_dpp v2, v1, v18 row_newbcast:9 row_mask:0xf bank_mask:0xf
	v_fmac_f32_dpp v4, v1, v19 row_newbcast:10 row_mask:0xf bank_mask:0xf
	s_nop 0
	v_add_f32_e32 v174, v4, v2
	v_add_f32_e32 v174, v174, v231
	v_mov_b32_e32 v4, v16
	ds_read_b32 v1, v157 offset:3328
	ds_read_b32 v2, v154 offset:6864
	s_waitcnt lgkmcnt(2)
	v_mov_b32_e32 v231, v16
	v_fmac_f32_dpp v3, v0, v8 row_newbcast:0 row_mask:0xf bank_mask:0xf
	v_fmac_f32_dpp v4, v0, v9 row_newbcast:1 row_mask:0xf bank_mask:0xf
	v_fmac_f32_dpp v231, v0, v10 row_newbcast:2 row_mask:0xf bank_mask:0xf
	v_fmac_f32_dpp v3, v0, v11 row_newbcast:3 row_mask:0xf bank_mask:0xf
	v_fmac_f32_dpp v4, v0, v12 row_newbcast:4 row_mask:0xf bank_mask:0xf
	v_fmac_f32_dpp v231, v0, v13 row_newbcast:5 row_mask:0xf bank_mask:0xf
	v_fmac_f32_dpp v3, v0, v14 row_newbcast:6 row_mask:0xf bank_mask:0xf
	v_fmac_f32_dpp v4, v0, v15 row_newbcast:7 row_mask:0xf bank_mask:0xf
	v_fmac_f32_dpp v231, v0, v17 row_newbcast:8 row_mask:0xf bank_mask:0xf
	v_fmac_f32_dpp v3, v0, v18 row_newbcast:9 row_mask:0xf bank_mask:0xf
	v_fmac_f32_dpp v4, v0, v19 row_newbcast:10 row_mask:0xf bank_mask:0xf
	v_fmac_f32_dpp v231, v0, v174 row_newbcast:11 row_mask:0xf bank_mask:0xf
	s_nop 0
	v_add_f32_e32 v175, v3, v4
	v_add_f32_e32 v175, v175, v231
	ds_read_b32 v0, v157 offset:3584
	ds_read_b32 v3, v154 offset:7392
	s_waitcnt lgkmcnt(2)
	v_mov_b32_e32 v231, v16
	v_fmac_f32_dpp v2, v1, v8 row_newbcast:0 row_mask:0xf bank_mask:0xf
	v_mov_b32_e32 v4, v16
	v_fmac_f32_dpp v4, v1, v9 row_newbcast:1 row_mask:0xf bank_mask:0xf
	v_fmac_f32_dpp v231, v1, v10 row_newbcast:2 row_mask:0xf bank_mask:0xf
	v_fmac_f32_dpp v2, v1, v11 row_newbcast:3 row_mask:0xf bank_mask:0xf
	v_fmac_f32_dpp v4, v1, v12 row_newbcast:4 row_mask:0xf bank_mask:0xf
	v_fmac_f32_dpp v231, v1, v13 row_newbcast:5 row_mask:0xf bank_mask:0xf
	v_fmac_f32_dpp v2, v1, v14 row_newbcast:6 row_mask:0xf bank_mask:0xf
	v_fmac_f32_dpp v4, v1, v15 row_newbcast:7 row_mask:0xf bank_mask:0xf
	v_fmac_f32_dpp v231, v1, v17 row_newbcast:8 row_mask:0xf bank_mask:0xf
	v_fmac_f32_dpp v2, v1, v18 row_newbcast:9 row_mask:0xf bank_mask:0xf
	v_fmac_f32_dpp v4, v1, v19 row_newbcast:10 row_mask:0xf bank_mask:0xf
	v_fmac_f32_dpp v231, v1, v174 row_newbcast:11 row_mask:0xf bank_mask:0xf
	v_fmac_f32_dpp v2, v1, v175 row_newbcast:12 row_mask:0xf bank_mask:0xf
	s_nop 0
	v_add_f32_e32 v176, v4, v2
	v_add_f32_e32 v176, v176, v231
	v_mov_b32_e32 v4, v16
	ds_read_b32 v1, v157 offset:3840
	ds_read_b32 v2, v154 offset:7920
	s_waitcnt lgkmcnt(2)
	v_mov_b32_e32 v231, v16
	v_fmac_f32_dpp v3, v0, v8 row_newbcast:0 row_mask:0xf bank_mask:0xf
	v_fmac_f32_dpp v4, v0, v9 row_newbcast:1 row_mask:0xf bank_mask:0xf
	v_fmac_f32_dpp v231, v0, v10 row_newbcast:2 row_mask:0xf bank_mask:0xf
	v_fmac_f32_dpp v3, v0, v11 row_newbcast:3 row_mask:0xf bank_mask:0xf
	v_fmac_f32_dpp v4, v0, v12 row_newbcast:4 row_mask:0xf bank_mask:0xf
	v_fmac_f32_dpp v231, v0, v13 row_newbcast:5 row_mask:0xf bank_mask:0xf
	v_fmac_f32_dpp v3, v0, v14 row_newbcast:6 row_mask:0xf bank_mask:0xf
	v_fmac_f32_dpp v4, v0, v15 row_newbcast:7 row_mask:0xf bank_mask:0xf
	v_fmac_f32_dpp v231, v0, v17 row_newbcast:8 row_mask:0xf bank_mask:0xf
	v_fmac_f32_dpp v3, v0, v18 row_newbcast:9 row_mask:0xf bank_mask:0xf
	v_fmac_f32_dpp v4, v0, v19 row_newbcast:10 row_mask:0xf bank_mask:0xf
	v_fmac_f32_dpp v231, v0, v174 row_newbcast:11 row_mask:0xf bank_mask:0xf
	v_fmac_f32_dpp v3, v0, v175 row_newbcast:12 row_mask:0xf bank_mask:0xf
	v_fmac_f32_dpp v4, v0, v176 row_newbcast:13 row_mask:0xf bank_mask:0xf
	s_nop 0
	v_add_f32_e32 v177, v3, v4
	v_add_f32_e32 v177, v177, v231
	ds_read_b32 v3, v157 offset:4096
	ds_read_b32 v4, v154 offset:8448
	s_waitcnt lgkmcnt(2)
	v_mov_b32_e32 v231, v16
	v_fmac_f32_dpp v2, v1, v8 row_newbcast:0 row_mask:0xf bank_mask:0xf
	v_mov_b32_e32 v0, v16
	v_fmac_f32_dpp v0, v1, v9 row_newbcast:1 row_mask:0xf bank_mask:0xf
	v_fmac_f32_dpp v231, v1, v10 row_newbcast:2 row_mask:0xf bank_mask:0xf
	v_fmac_f32_dpp v2, v1, v11 row_newbcast:3 row_mask:0xf bank_mask:0xf
	v_fmac_f32_dpp v0, v1, v12 row_newbcast:4 row_mask:0xf bank_mask:0xf
	v_fmac_f32_dpp v231, v1, v13 row_newbcast:5 row_mask:0xf bank_mask:0xf
	v_fmac_f32_dpp v2, v1, v14 row_newbcast:6 row_mask:0xf bank_mask:0xf
	v_fmac_f32_dpp v0, v1, v15 row_newbcast:7 row_mask:0xf bank_mask:0xf
	v_fmac_f32_dpp v231, v1, v17 row_newbcast:8 row_mask:0xf bank_mask:0xf
	v_fmac_f32_dpp v2, v1, v18 row_newbcast:9 row_mask:0xf bank_mask:0xf
	v_fmac_f32_dpp v0, v1, v19 row_newbcast:10 row_mask:0xf bank_mask:0xf
	v_fmac_f32_dpp v231, v1, v174 row_newbcast:11 row_mask:0xf bank_mask:0xf
	v_fmac_f32_dpp v2, v1, v175 row_newbcast:12 row_mask:0xf bank_mask:0xf
	v_fmac_f32_dpp v0, v1, v176 row_newbcast:13 row_mask:0xf bank_mask:0xf
	v_fmac_f32_dpp v231, v1, v177 row_newbcast:14 row_mask:0xf bank_mask:0xf
	s_nop 0
	v_add_f32_e32 v178, v0, v2
	v_add_f32_e32 v178, v178, v231
	v_add_u32_e32 v5, 0x1000, v157
	v_mov_b32_e32 v2, v16
	ds_read2_b32 v[0:1], v5 offset0:64 offset1:80
	ds_read_b32 v6, v154 offset:8976
	s_waitcnt lgkmcnt(2)
; template <int J> __device__ __forceinline__ void macb(float& s, int Lq, float x) { asm volatile("v_fmac_f32_dpp %0, %1, %2 row_newbcast:%3 row_mask:0xf bank_mask:0xf" : "+v"(s) : "v"(Lq), "v"(x), "n"(J)); }
; __device__ __forceinline__ void gdn_prep_item(const Params& p, unsigned char* lds, int item, u32x4 (&raw)[3][2][4], float& gpre, float& bpre, int next_item) {
;     ...
;     if (tid < 256 && !(p.flags & 16)) {
;         float* base = (tid < 128) ? (rhsK + tid) : (rhsV + (tid - 128));
;         float xs[64];
; #pragma unroll
;         for (int i = 0; i < 64; ++i) xs[i] = 0.f;
;         { const int L0[4] = {0, 0, 0, 0}; SolveRow<0>::run(Lm, base, xs, L0, base[0], lane & 15); }
; #pragma unroll
;         for (int i = 0; i < 64; ++i) base[i * RS] = xs[i];
	v_mov_b32_e32 v231, v16
	v_fmac_f32_dpp v4, v3, v8 row_newbcast:0 row_mask:0xf bank_mask:0xf
	v_fmac_f32_dpp v2, v3, v9 row_newbcast:1 row_mask:0xf bank_mask:0xf
	v_fmac_f32_dpp v231, v3, v10 row_newbcast:2 row_mask:0xf bank_mask:0xf
	v_fmac_f32_dpp v4, v3, v11 row_newbcast:3 row_mask:0xf bank_mask:0xf
	v_fmac_f32_dpp v2, v3, v12 row_newbcast:4 row_mask:0xf bank_mask:0xf
	v_fmac_f32_dpp v231, v3, v13 row_newbcast:5 row_mask:0xf bank_mask:0xf
	v_fmac_f32_dpp v4, v3, v14 row_newbcast:6 row_mask:0xf bank_mask:0xf
	v_fmac_f32_dpp v2, v3, v15 row_newbcast:7 row_mask:0xf bank_mask:0xf
	v_fmac_f32_dpp v231, v3, v17 row_newbcast:8 row_mask:0xf bank_mask:0xf
	v_fmac_f32_dpp v4, v3, v18 row_newbcast:9 row_mask:0xf bank_mask:0xf
	v_fmac_f32_dpp v2, v3, v19 row_newbcast:10 row_mask:0xf bank_mask:0xf
	v_fmac_f32_dpp v231, v3, v174 row_newbcast:11 row_mask:0xf bank_mask:0xf
	v_fmac_f32_dpp v4, v3, v175 row_newbcast:12 row_mask:0xf bank_mask:0xf
	v_fmac_f32_dpp v2, v3, v176 row_newbcast:13 row_mask:0xf bank_mask:0xf
	v_fmac_f32_dpp v231, v3, v177 row_newbcast:14 row_mask:0xf bank_mask:0xf
	v_fmac_f32_dpp v4, v3, v178 row_newbcast:15 row_mask:0xf bank_mask:0xf
	s_nop 0
	v_add_f32_e32 v179, v4, v2
	v_add_f32_e32 v179, v179, v231
	ds_read2_b32 v[2:3], v5 offset0:128 offset1:144
	ds_read_b32 v4, v154 offset:9504
	s_waitcnt lgkmcnt(2)
	v_mov_b32_e32 v231, v16
	v_fmac_f32_dpp v6, v0, v8 row_newbcast:0 row_mask:0xf bank_mask:0xf
	v_mov_b32_e32 v7, v16
	v_fmac_f32_dpp v7, v0, v9 row_newbcast:1 row_mask:0xf bank_mask:0xf
	v_fmac_f32_dpp v231, v0, v10 row_newbcast:2 row_mask:0xf bank_mask:0xf
	v_fmac_f32_dpp v6, v0, v11 row_newbcast:3 row_mask:0xf bank_mask:0xf
	v_fmac_f32_dpp v7, v0, v12 row_newbcast:4 row_mask:0xf bank_mask:0xf
	v_fmac_f32_dpp v231, v0, v13 row_newbcast:5 row_mask:0xf bank_mask:0xf
	v_fmac_f32_dpp v6, v0, v14 row_newbcast:6 row_mask:0xf bank_mask:0xf
	v_fmac_f32_dpp v7, v0, v15 row_newbcast:7 row_mask:0xf bank_mask:0xf
	v_fmac_f32_dpp v231, v0, v17 row_newbcast:8 row_mask:0xf bank_mask:0xf
	v_fmac_f32_dpp v6, v0, v18 row_newbcast:9 row_mask:0xf bank_mask:0xf
	v_fmac_f32_dpp v7, v0, v19 row_newbcast:10 row_mask:0xf bank_mask:0xf
	v_fmac_f32_dpp v231, v0, v174 row_newbcast:11 row_mask:0xf bank_mask:0xf
	v_fmac_f32_dpp v6, v0, v175 row_newbcast:12 row_mask:0xf bank_mask:0xf
	v_fmac_f32_dpp v7, v0, v176 row_newbcast:13 row_mask:0xf bank_mask:0xf
	v_fmac_f32_dpp v231, v0, v177 row_newbcast:14 row_mask:0xf bank_mask:0xf
	v_fmac_f32_dpp v6, v0, v178 row_newbcast:15 row_mask:0xf bank_mask:0xf
	v_fmac_f32_dpp v7, v1, v179 row_newbcast:0 row_mask:0xf bank_mask:0xf
	s_nop 0
	v_add_f32_e32 v180, v7, v6
	v_add_f32_e32 v180, v180, v231
	v_mov_b32_e32 v6, v16
	ds_read2_b32 v[0:1], v5 offset0:192 offset1:208
	ds_read_b32 v5, v154 offset:10032
	s_waitcnt lgkmcnt(2)
	v_mov_b32_e32 v231, v16
	v_fmac_f32_dpp v4, v2, v8 row_newbcast:0 row_mask:0xf bank_mask:0xf
	v_fmac_f32_dpp v6, v2, v9 row_newbcast:1 row_mask:0xf bank_mask:0xf
	v_fmac_f32_dpp v231, v2, v10 row_newbcast:2 row_mask:0xf bank_mask:0xf
	v_fmac_f32_dpp v4, v2, v11 row_newbcast:3 row_mask:0xf bank_mask:0xf
	v_fmac_f32_dpp v6, v2, v12 row_newbcast:4 row_mask:0xf bank_mask:0xf
	v_fmac_f32_dpp v231, v2, v13 row_newbcast:5 row_mask:0xf bank_mask:0xf
	v_fmac_f32_dpp v4, v2, v14 row_newbcast:6 row_mask:0xf bank_mask:0xf
	v_fmac_f32_dpp v6, v2, v15 row_newbcast:7 row_mask:0xf bank_mask:0xf
	v_fmac_f32_dpp v231, v2, v17 row_newbcast:8 row_mask:0xf bank_mask:0xf
	v_fmac_f32_dpp v4, v2, v18 row_newbcast:9 row_mask:0xf bank_mask:0xf
	v_fmac_f32_dpp v6, v2, v19 row_newbcast:10 row_mask:0xf bank_mask:0xf
	v_fmac_f32_dpp v231, v2, v174 row_newbcast:11 row_mask:0xf bank_mask:0xf
	v_fmac_f32_dpp v4, v2, v175 row_newbcast:12 row_mask:0xf bank_mask:0xf
	v_fmac_f32_dpp v6, v2, v176 row_newbcast:13 row_mask:0xf bank_mask:0xf
	v_fmac_f32_dpp v231, v2, v177 row_newbcast:14 row_mask:0xf bank_mask:0xf
	v_fmac_f32_dpp v4, v2, v178 row_newbcast:15 row_mask:0xf bank_mask:0xf
	v_fmac_f32_dpp v6, v3, v179 row_newbcast:0 row_mask:0xf bank_mask:0xf
	v_fmac_f32_dpp v231, v3, v180 row_newbcast:1 row_mask:0xf bank_mask:0xf
	s_nop 0
	v_add_f32_e32 v181, v4, v6
	v_add_f32_e32 v181, v181, v231
	v_add_u32_e32 v4, 0x1400, v157
	ds_read2_b32 v[2:3], v4 offset1:16
	ds_read_b32 v6, v154 offset:10560
	s_waitcnt lgkmcnt(2)
	v_mov_b32_e32 v231, v16
	v_fmac_f32_dpp v5, v0, v8 row_newbcast:0 row_mask:0xf bank_mask:0xf
	v_mov_b32_e32 v7, v16
	v_fmac_f32_dpp v7, v0, v9 row_newbcast:1 row_mask:0xf bank_mask:0xf
	v_fmac_f32_dpp v231, v0, v10 row_newbcast:2 row_mask:0xf bank_mask:0xf
	v_fmac_f32_dpp v5, v0, v11 row_newbcast:3 row_mask:0xf bank_mask:0xf
	v_fmac_f32_dpp v7, v0, v12 row_newbcast:4 row_mask:0xf bank_mask:0xf
	v_fmac_f32_dpp v231, v0, v13 row_newbcast:5 row_mask:0xf bank_mask:0xf
	v_fmac_f32_dpp v5, v0, v14 row_newbcast:6 row_mask:0xf bank_mask:0xf
	v_fmac_f32_dpp v7, v0, v15 row_newbcast:7 row_mask:0xf bank_mask:0xf
	v_fmac_f32_dpp v231, v0, v17 row_newbcast:8 row_mask:0xf bank_mask:0xf
	v_fmac_f32_dpp v5, v0, v18 row_newbcast:9 row_mask:0xf bank_mask:0xf
	v_fmac_f32_dpp v7, v0, v19 row_newbcast:10 row_mask:0xf bank_mask:0xf
	v_fmac_f32_dpp v231, v0, v174 row_newbcast:11 row_mask:0xf bank_mask:0xf
	v_fmac_f32_dpp v5, v0, v175 row_newbcast:12 row_mask:0xf bank_mask:0xf
	v_fmac_f32_dpp v7, v0, v176 row_newbcast:13 row_mask:0xf bank_mask:0xf
	v_fmac_f32_dpp v231, v0, v177 row_newbcast:14 row_mask:0xf bank_mask:0xf
	v_fmac_f32_dpp v5, v0, v178 row_newbcast:15 row_mask:0xf bank_mask:0xf
	v_fmac_f32_dpp v7, v1, v179 row_newbcast:0 row_mask:0xf bank_mask:0xf
	v_fmac_f32_dpp v231, v1, v180 row_newbcast:1 row_mask:0xf bank_mask:0xf
	v_fmac_f32_dpp v5, v1, v181 row_newbcast:2 row_mask:0xf bank_mask:0xf
	s_nop 0
	v_add_f32_e32 v182, v7, v5
	v_add_f32_e32 v182, v182, v231
	v_mov_b32_e32 v7, v16
	ds_read2_b32 v[0:1], v4 offset0:64 offset1:80
	ds_read_b32 v5, v154 offset:11088
	s_waitcnt lgkmcnt(2)
; template <int J> __device__ __forceinline__ void macb(float& s, int Lq, float x) { asm volatile("v_fmac_f32_dpp %0, %1, %2 row_newbcast:%3 row_mask:0xf bank_mask:0xf" : "+v"(s) : "v"(Lq), "v"(x), "n"(J)); }
	v_mov_b32_e32 v231, v16
	v_fmac_f32_dpp v6, v2, v8 row_newbcast:0 row_mask:0xf bank_mask:0xf
	v_fmac_f32_dpp v7, v2, v9 row_newbcast:1 row_mask:0xf bank_mask:0xf
	v_fmac_f32_dpp v231, v2, v10 row_newbcast:2 row_mask:0xf bank_mask:0xf
	v_fmac_f32_dpp v6, v2, v11 row_newbcast:3 row_mask:0xf bank_mask:0xf
	v_fmac_f32_dpp v7, v2, v12 row_newbcast:4 row_mask:0xf bank_mask:0xf
	v_fmac_f32_dpp v231, v2, v13 row_newbcast:5 row_mask:0xf bank_mask:0xf
	v_fmac_f32_dpp v6, v2, v14 row_newbcast:6 row_mask:0xf bank_mask:0xf
	v_fmac_f32_dpp v7, v2, v15 row_newbcast:7 row_mask:0xf bank_mask:0xf
	v_fmac_f32_dpp v231, v2, v17 row_newbcast:8 row_mask:0xf bank_mask:0xf
	v_fmac_f32_dpp v6, v2, v18 row_newbcast:9 row_mask:0xf bank_mask:0xf
	v_fmac_f32_dpp v7, v2, v19 row_newbcast:10 row_mask:0xf bank_mask:0xf
	v_fmac_f32_dpp v231, v2, v174 row_newbcast:11 row_mask:0xf bank_mask:0xf
	v_fmac_f32_dpp v6, v2, v175 row_newbcast:12 row_mask:0xf bank_mask:0xf
	v_fmac_f32_dpp v7, v2, v176 row_newbcast:13 row_mask:0xf bank_mask:0xf
	v_fmac_f32_dpp v231, v2, v177 row_newbcast:14 row_mask:0xf bank_mask:0xf
	v_fmac_f32_dpp v6, v2, v178 row_newbcast:15 row_mask:0xf bank_mask:0xf
	v_fmac_f32_dpp v7, v3, v179 row_newbcast:0 row_mask:0xf bank_mask:0xf
	v_fmac_f32_dpp v231, v3, v180 row_newbcast:1 row_mask:0xf bank_mask:0xf
	v_fmac_f32_dpp v6, v3, v181 row_newbcast:2 row_mask:0xf bank_mask:0xf
	v_fmac_f32_dpp v7, v3, v182 row_newbcast:3 row_mask:0xf bank_mask:0xf
	s_nop 0
	v_add_f32_e32 v183, v6, v7
	v_add_f32_e32 v183, v183, v231
	ds_read2_b32 v[2:3], v4 offset0:128 offset1:144
	ds_read_b32 v6, v154 offset:11616
	s_waitcnt lgkmcnt(2)
	v_mov_b32_e32 v231, v16
	v_fmac_f32_dpp v5, v0, v8 row_newbcast:0 row_mask:0xf bank_mask:0xf
	v_mov_b32_e32 v7, v16
	v_fmac_f32_dpp v7, v0, v9 row_newbcast:1 row_mask:0xf bank_mask:0xf
	v_fmac_f32_dpp v231, v0, v10 row_newbcast:2 row_mask:0xf bank_mask:0xf
	v_fmac_f32_dpp v5, v0, v11 row_newbcast:3 row_mask:0xf bank_mask:0xf
	v_fmac_f32_dpp v7, v0, v12 row_newbcast:4 row_mask:0xf bank_mask:0xf
	v_fmac_f32_dpp v231, v0, v13 row_newbcast:5 row_mask:0xf bank_mask:0xf
	v_fmac_f32_dpp v5, v0, v14 row_newbcast:6 row_mask:0xf bank_mask:0xf
	v_fmac_f32_dpp v7, v0, v15 row_newbcast:7 row_mask:0xf bank_mask:0xf
	v_fmac_f32_dpp v231, v0, v17 row_newbcast:8 row_mask:0xf bank_mask:0xf
	v_fmac_f32_dpp v5, v0, v18 row_newbcast:9 row_mask:0xf bank_mask:0xf
	v_fmac_f32_dpp v7, v0, v19 row_newbcast:10 row_mask:0xf bank_mask:0xf
	v_fmac_f32_dpp v231, v0, v174 row_newbcast:11 row_mask:0xf bank_mask:0xf
	v_fmac_f32_dpp v5, v0, v175 row_newbcast:12 row_mask:0xf bank_mask:0xf
	v_fmac_f32_dpp v7, v0, v176 row_newbcast:13 row_mask:0xf bank_mask:0xf
	v_fmac_f32_dpp v231, v0, v177 row_newbcast:14 row_mask:0xf bank_mask:0xf
	v_fmac_f32_dpp v5, v0, v178 row_newbcast:15 row_mask:0xf bank_mask:0xf
	v_fmac_f32_dpp v7, v1, v179 row_newbcast:0 row_mask:0xf bank_mask:0xf
	v_fmac_f32_dpp v231, v1, v180 row_newbcast:1 row_mask:0xf bank_mask:0xf
	v_fmac_f32_dpp v5, v1, v181 row_newbcast:2 row_mask:0xf bank_mask:0xf
	v_fmac_f32_dpp v7, v1, v182 row_newbcast:3 row_mask:0xf bank_mask:0xf
	v_fmac_f32_dpp v231, v1, v183 row_newbcast:4 row_mask:0xf bank_mask:0xf
	s_nop 0
	v_add_f32_e32 v184, v7, v5
	v_add_f32_e32 v184, v184, v231
	v_mov_b32_e32 v5, v16
	ds_read2_b32 v[0:1], v4 offset0:192 offset1:208
	ds_read_b32 v4, v154 offset:12144
	s_waitcnt lgkmcnt(2)
	v_mov_b32_e32 v231, v16
	v_fmac_f32_dpp v6, v2, v8 row_newbcast:0 row_mask:0xf bank_mask:0xf
	v_fmac_f32_dpp v5, v2, v9 row_newbcast:1 row_mask:0xf bank_mask:0xf
	v_fmac_f32_dpp v231, v2, v10 row_newbcast:2 row_mask:0xf bank_mask:0xf
	v_fmac_f32_dpp v6, v2, v11 row_newbcast:3 row_mask:0xf bank_mask:0xf
	v_fmac_f32_dpp v5, v2, v12 row_newbcast:4 row_mask:0xf bank_mask:0xf
	v_fmac_f32_dpp v231, v2, v13 row_newbcast:5 row_mask:0xf bank_mask:0xf
	v_fmac_f32_dpp v6, v2, v14 row_newbcast:6 row_mask:0xf bank_mask:0xf
	v_fmac_f32_dpp v5, v2, v15 row_newbcast:7 row_mask:0xf bank_mask:0xf
	v_fmac_f32_dpp v231, v2, v17 row_newbcast:8 row_mask:0xf bank_mask:0xf
	v_fmac_f32_dpp v6, v2, v18 row_newbcast:9 row_mask:0xf bank_mask:0xf
	v_fmac_f32_dpp v5, v2, v19 row_newbcast:10 row_mask:0xf bank_mask:0xf
	v_fmac_f32_dpp v231, v2, v174 row_newbcast:11 row_mask:0xf bank_mask:0xf
	v_fmac_f32_dpp v6, v2, v175 row_newbcast:12 row_mask:0xf bank_mask:0xf
	v_fmac_f32_dpp v5, v2, v176 row_newbcast:13 row_mask:0xf bank_mask:0xf
	v_fmac_f32_dpp v231, v2, v177 row_newbcast:14 row_mask:0xf bank_mask:0xf
	v_fmac_f32_dpp v6, v2, v178 row_newbcast:15 row_mask:0xf bank_mask:0xf
	v_fmac_f32_dpp v5, v3, v179 row_newbcast:0 row_mask:0xf bank_mask:0xf
	v_fmac_f32_dpp v231, v3, v180 row_newbcast:1 row_mask:0xf bank_mask:0xf
	v_fmac_f32_dpp v6, v3, v181 row_newbcast:2 row_mask:0xf bank_mask:0xf
	v_fmac_f32_dpp v5, v3, v182 row_newbcast:3 row_mask:0xf bank_mask:0xf
	v_fmac_f32_dpp v231, v3, v183 row_newbcast:4 row_mask:0xf bank_mask:0xf
	v_fmac_f32_dpp v6, v3, v184 row_newbcast:5 row_mask:0xf bank_mask:0xf
	s_nop 0
	v_add_f32_e32 v185, v6, v5
	v_add_f32_e32 v185, v185, v231
	v_add_u32_e32 v5, 0x1800, v157
	ds_read2_b32 v[2:3], v5 offset1:16
	ds_read_b32 v6, v154 offset:12672
	s_waitcnt lgkmcnt(2)
; template <int J> __device__ __forceinline__ void macb(float& s, int Lq, float x) { asm volatile("v_fmac_f32_dpp %0, %1, %2 row_newbcast:%3 row_mask:0xf bank_mask:0xf" : "+v"(s) : "v"(Lq), "v"(x), "n"(J)); }
	v_mov_b32_e32 v231, v16
	v_fmac_f32_dpp v4, v0, v8 row_newbcast:0 row_mask:0xf bank_mask:0xf
	v_mov_b32_e32 v7, v16
	v_fmac_f32_dpp v7, v0, v9 row_newbcast:1 row_mask:0xf bank_mask:0xf
	v_fmac_f32_dpp v231, v0, v10 row_newbcast:2 row_mask:0xf bank_mask:0xf
	v_fmac_f32_dpp v4, v0, v11 row_newbcast:3 row_mask:0xf bank_mask:0xf
	v_fmac_f32_dpp v7, v0, v12 row_newbcast:4 row_mask:0xf bank_mask:0xf
	v_fmac_f32_dpp v231, v0, v13 row_newbcast:5 row_mask:0xf bank_mask:0xf
	v_fmac_f32_dpp v4, v0, v14 row_newbcast:6 row_mask:0xf bank_mask:0xf
	v_fmac_f32_dpp v7, v0, v15 row_newbcast:7 row_mask:0xf bank_mask:0xf
	v_fmac_f32_dpp v231, v0, v17 row_newbcast:8 row_mask:0xf bank_mask:0xf
	v_fmac_f32_dpp v4, v0, v18 row_newbcast:9 row_mask:0xf bank_mask:0xf
	v_fmac_f32_dpp v7, v0, v19 row_newbcast:10 row_mask:0xf bank_mask:0xf
	v_fmac_f32_dpp v231, v0, v174 row_newbcast:11 row_mask:0xf bank_mask:0xf
	v_fmac_f32_dpp v4, v0, v175 row_newbcast:12 row_mask:0xf bank_mask:0xf
	v_fmac_f32_dpp v7, v0, v176 row_newbcast:13 row_mask:0xf bank_mask:0xf
	v_fmac_f32_dpp v231, v0, v177 row_newbcast:14 row_mask:0xf bank_mask:0xf
	v_fmac_f32_dpp v4, v0, v178 row_newbcast:15 row_mask:0xf bank_mask:0xf
	v_fmac_f32_dpp v7, v1, v179 row_newbcast:0 row_mask:0xf bank_mask:0xf
	v_fmac_f32_dpp v231, v1, v180 row_newbcast:1 row_mask:0xf bank_mask:0xf
	v_fmac_f32_dpp v4, v1, v181 row_newbcast:2 row_mask:0xf bank_mask:0xf
	v_fmac_f32_dpp v7, v1, v182 row_newbcast:3 row_mask:0xf bank_mask:0xf
	v_fmac_f32_dpp v231, v1, v183 row_newbcast:4 row_mask:0xf bank_mask:0xf
	v_fmac_f32_dpp v4, v1, v184 row_newbcast:5 row_mask:0xf bank_mask:0xf
	v_fmac_f32_dpp v7, v1, v185 row_newbcast:6 row_mask:0xf bank_mask:0xf
	s_nop 0
	v_add_f32_e32 v186, v7, v4
	v_add_f32_e32 v186, v186, v231
	v_mov_b32_e32 v7, v16
	ds_read2_b32 v[0:1], v5 offset0:64 offset1:80
	ds_read_b32 v4, v154 offset:13200
	s_waitcnt lgkmcnt(2)
	v_mov_b32_e32 v231, v16
	v_fmac_f32_dpp v6, v2, v8 row_newbcast:0 row_mask:0xf bank_mask:0xf
	v_fmac_f32_dpp v7, v2, v9 row_newbcast:1 row_mask:0xf bank_mask:0xf
	v_fmac_f32_dpp v231, v2, v10 row_newbcast:2 row_mask:0xf bank_mask:0xf
	v_fmac_f32_dpp v6, v2, v11 row_newbcast:3 row_mask:0xf bank_mask:0xf
	v_fmac_f32_dpp v7, v2, v12 row_newbcast:4 row_mask:0xf bank_mask:0xf
	v_fmac_f32_dpp v231, v2, v13 row_newbcast:5 row_mask:0xf bank_mask:0xf
	v_fmac_f32_dpp v6, v2, v14 row_newbcast:6 row_mask:0xf bank_mask:0xf
	v_fmac_f32_dpp v7, v2, v15 row_newbcast:7 row_mask:0xf bank_mask:0xf
	v_fmac_f32_dpp v231, v2, v17 row_newbcast:8 row_mask:0xf bank_mask:0xf
	v_fmac_f32_dpp v6, v2, v18 row_newbcast:9 row_mask:0xf bank_mask:0xf
	v_fmac_f32_dpp v7, v2, v19 row_newbcast:10 row_mask:0xf bank_mask:0xf
	v_fmac_f32_dpp v231, v2, v174 row_newbcast:11 row_mask:0xf bank_mask:0xf
	v_fmac_f32_dpp v6, v2, v175 row_newbcast:12 row_mask:0xf bank_mask:0xf
	v_fmac_f32_dpp v7, v2, v176 row_newbcast:13 row_mask:0xf bank_mask:0xf
	v_fmac_f32_dpp v231, v2, v177 row_newbcast:14 row_mask:0xf bank_mask:0xf
	v_fmac_f32_dpp v6, v2, v178 row_newbcast:15 row_mask:0xf bank_mask:0xf
	v_fmac_f32_dpp v7, v3, v179 row_newbcast:0 row_mask:0xf bank_mask:0xf
	v_fmac_f32_dpp v231, v3, v180 row_newbcast:1 row_mask:0xf bank_mask:0xf
	v_fmac_f32_dpp v6, v3, v181 row_newbcast:2 row_mask:0xf bank_mask:0xf
	v_fmac_f32_dpp v7, v3, v182 row_newbcast:3 row_mask:0xf bank_mask:0xf
	v_fmac_f32_dpp v231, v3, v183 row_newbcast:4 row_mask:0xf bank_mask:0xf
	v_fmac_f32_dpp v6, v3, v184 row_newbcast:5 row_mask:0xf bank_mask:0xf
	v_fmac_f32_dpp v7, v3, v185 row_newbcast:6 row_mask:0xf bank_mask:0xf
	v_fmac_f32_dpp v231, v3, v186 row_newbcast:7 row_mask:0xf bank_mask:0xf
	s_nop 0
	v_add_f32_e32 v187, v6, v7
	v_add_f32_e32 v187, v187, v231
	ds_read2_b32 v[2:3], v5 offset0:128 offset1:144
	ds_read_b32 v6, v154 offset:13728
	s_waitcnt lgkmcnt(2)
	v_mov_b32_e32 v231, v16
	v_fmac_f32_dpp v4, v0, v8 row_newbcast:0 row_mask:0xf bank_mask:0xf
	v_mov_b32_e32 v7, v16
	v_fmac_f32_dpp v7, v0, v9 row_newbcast:1 row_mask:0xf bank_mask:0xf
	v_fmac_f32_dpp v231, v0, v10 row_newbcast:2 row_mask:0xf bank_mask:0xf
	v_fmac_f32_dpp v4, v0, v11 row_newbcast:3 row_mask:0xf bank_mask:0xf
	v_fmac_f32_dpp v7, v0, v12 row_newbcast:4 row_mask:0xf bank_mask:0xf
	v_fmac_f32_dpp v231, v0, v13 row_newbcast:5 row_mask:0xf bank_mask:0xf
	v_fmac_f32_dpp v4, v0, v14 row_newbcast:6 row_mask:0xf bank_mask:0xf
	v_fmac_f32_dpp v7, v0, v15 row_newbcast:7 row_mask:0xf bank_mask:0xf
	v_fmac_f32_dpp v231, v0, v17 row_newbcast:8 row_mask:0xf bank_mask:0xf
	v_fmac_f32_dpp v4, v0, v18 row_newbcast:9 row_mask:0xf bank_mask:0xf
	v_fmac_f32_dpp v7, v0, v19 row_newbcast:10 row_mask:0xf bank_mask:0xf
	v_fmac_f32_dpp v231, v0, v174 row_newbcast:11 row_mask:0xf bank_mask:0xf
	v_fmac_f32_dpp v4, v0, v175 row_newbcast:12 row_mask:0xf bank_mask:0xf
	v_fmac_f32_dpp v7, v0, v176 row_newbcast:13 row_mask:0xf bank_mask:0xf
	v_fmac_f32_dpp v231, v0, v177 row_newbcast:14 row_mask:0xf bank_mask:0xf
	v_fmac_f32_dpp v4, v0, v178 row_newbcast:15 row_mask:0xf bank_mask:0xf
	v_fmac_f32_dpp v7, v1, v179 row_newbcast:0 row_mask:0xf bank_mask:0xf
	v_fmac_f32_dpp v231, v1, v180 row_newbcast:1 row_mask:0xf bank_mask:0xf
	v_fmac_f32_dpp v4, v1, v181 row_newbcast:2 row_mask:0xf bank_mask:0xf
	v_fmac_f32_dpp v7, v1, v182 row_newbcast:3 row_mask:0xf bank_mask:0xf
	v_fmac_f32_dpp v231, v1, v183 row_newbcast:4 row_mask:0xf bank_mask:0xf
	v_fmac_f32_dpp v4, v1, v184 row_newbcast:5 row_mask:0xf bank_mask:0xf
	v_fmac_f32_dpp v7, v1, v185 row_newbcast:6 row_mask:0xf bank_mask:0xf
	v_fmac_f32_dpp v231, v1, v186 row_newbcast:7 row_mask:0xf bank_mask:0xf
	v_fmac_f32_dpp v4, v1, v187 row_newbcast:8 row_mask:0xf bank_mask:0xf
	s_nop 0
	v_add_f32_e32 v188, v7, v4
	v_add_f32_e32 v188, v188, v231
	ds_read2_b32 v[0:1], v5 offset0:192 offset1:208
	ds_read_b32 v4, v154 offset:14256
	v_mov_b32_e32 v5, v16
	s_waitcnt lgkmcnt(2)
; template <int J> __device__ __forceinline__ void macb(float& s, int Lq, float x) { asm volatile("v_fmac_f32_dpp %0, %1, %2 row_newbcast:%3 row_mask:0xf bank_mask:0xf" : "+v"(s) : "v"(Lq), "v"(x), "n"(J)); }
	v_mov_b32_e32 v231, v16
	v_fmac_f32_dpp v6, v2, v8 row_newbcast:0 row_mask:0xf bank_mask:0xf
	v_fmac_f32_dpp v5, v2, v9 row_newbcast:1 row_mask:0xf bank_mask:0xf
	v_fmac_f32_dpp v231, v2, v10 row_newbcast:2 row_mask:0xf bank_mask:0xf
	v_fmac_f32_dpp v6, v2, v11 row_newbcast:3 row_mask:0xf bank_mask:0xf
	v_fmac_f32_dpp v5, v2, v12 row_newbcast:4 row_mask:0xf bank_mask:0xf
	v_fmac_f32_dpp v231, v2, v13 row_newbcast:5 row_mask:0xf bank_mask:0xf
	v_fmac_f32_dpp v6, v2, v14 row_newbcast:6 row_mask:0xf bank_mask:0xf
	v_fmac_f32_dpp v5, v2, v15 row_newbcast:7 row_mask:0xf bank_mask:0xf
	v_fmac_f32_dpp v231, v2, v17 row_newbcast:8 row_mask:0xf bank_mask:0xf
	v_fmac_f32_dpp v6, v2, v18 row_newbcast:9 row_mask:0xf bank_mask:0xf
	v_fmac_f32_dpp v5, v2, v19 row_newbcast:10 row_mask:0xf bank_mask:0xf
	v_fmac_f32_dpp v231, v2, v174 row_newbcast:11 row_mask:0xf bank_mask:0xf
	v_fmac_f32_dpp v6, v2, v175 row_newbcast:12 row_mask:0xf bank_mask:0xf
	v_fmac_f32_dpp v5, v2, v176 row_newbcast:13 row_mask:0xf bank_mask:0xf
	v_fmac_f32_dpp v231, v2, v177 row_newbcast:14 row_mask:0xf bank_mask:0xf
	v_fmac_f32_dpp v6, v2, v178 row_newbcast:15 row_mask:0xf bank_mask:0xf
	v_fmac_f32_dpp v5, v3, v179 row_newbcast:0 row_mask:0xf bank_mask:0xf
	v_fmac_f32_dpp v231, v3, v180 row_newbcast:1 row_mask:0xf bank_mask:0xf
	v_fmac_f32_dpp v6, v3, v181 row_newbcast:2 row_mask:0xf bank_mask:0xf
	v_fmac_f32_dpp v5, v3, v182 row_newbcast:3 row_mask:0xf bank_mask:0xf
	v_fmac_f32_dpp v231, v3, v183 row_newbcast:4 row_mask:0xf bank_mask:0xf
	v_fmac_f32_dpp v6, v3, v184 row_newbcast:5 row_mask:0xf bank_mask:0xf
	v_fmac_f32_dpp v5, v3, v185 row_newbcast:6 row_mask:0xf bank_mask:0xf
	v_fmac_f32_dpp v231, v3, v186 row_newbcast:7 row_mask:0xf bank_mask:0xf
	v_fmac_f32_dpp v6, v3, v187 row_newbcast:8 row_mask:0xf bank_mask:0xf
	v_fmac_f32_dpp v5, v3, v188 row_newbcast:9 row_mask:0xf bank_mask:0xf
	s_nop 0
	v_add_f32_e32 v189, v6, v5
	v_add_f32_e32 v189, v189, v231
	v_add_u32_e32 v5, 0x1c00, v157
	ds_read2_b32 v[2:3], v5 offset1:16
	ds_read_b32 v6, v154 offset:14784
	s_waitcnt lgkmcnt(2)
	v_mov_b32_e32 v231, v16
	v_fmac_f32_dpp v4, v0, v8 row_newbcast:0 row_mask:0xf bank_mask:0xf
	v_mov_b32_e32 v7, v16
	v_fmac_f32_dpp v7, v0, v9 row_newbcast:1 row_mask:0xf bank_mask:0xf
	v_fmac_f32_dpp v231, v0, v10 row_newbcast:2 row_mask:0xf bank_mask:0xf
	v_fmac_f32_dpp v4, v0, v11 row_newbcast:3 row_mask:0xf bank_mask:0xf
	v_fmac_f32_dpp v7, v0, v12 row_newbcast:4 row_mask:0xf bank_mask:0xf
	v_fmac_f32_dpp v231, v0, v13 row_newbcast:5 row_mask:0xf bank_mask:0xf
	v_fmac_f32_dpp v4, v0, v14 row_newbcast:6 row_mask:0xf bank_mask:0xf
	v_fmac_f32_dpp v7, v0, v15 row_newbcast:7 row_mask:0xf bank_mask:0xf
	v_fmac_f32_dpp v231, v0, v17 row_newbcast:8 row_mask:0xf bank_mask:0xf
	v_fmac_f32_dpp v4, v0, v18 row_newbcast:9 row_mask:0xf bank_mask:0xf
	v_fmac_f32_dpp v7, v0, v19 row_newbcast:10 row_mask:0xf bank_mask:0xf
	v_fmac_f32_dpp v231, v0, v174 row_newbcast:11 row_mask:0xf bank_mask:0xf
	v_fmac_f32_dpp v4, v0, v175 row_newbcast:12 row_mask:0xf bank_mask:0xf
	v_fmac_f32_dpp v7, v0, v176 row_newbcast:13 row_mask:0xf bank_mask:0xf
	v_fmac_f32_dpp v231, v0, v177 row_newbcast:14 row_mask:0xf bank_mask:0xf
	v_fmac_f32_dpp v4, v0, v178 row_newbcast:15 row_mask:0xf bank_mask:0xf
	v_fmac_f32_dpp v7, v1, v179 row_newbcast:0 row_mask:0xf bank_mask:0xf
	v_fmac_f32_dpp v231, v1, v180 row_newbcast:1 row_mask:0xf bank_mask:0xf
	v_fmac_f32_dpp v4, v1, v181 row_newbcast:2 row_mask:0xf bank_mask:0xf
	v_fmac_f32_dpp v7, v1, v182 row_newbcast:3 row_mask:0xf bank_mask:0xf
	v_fmac_f32_dpp v231, v1, v183 row_newbcast:4 row_mask:0xf bank_mask:0xf
	v_fmac_f32_dpp v4, v1, v184 row_newbcast:5 row_mask:0xf bank_mask:0xf
	v_fmac_f32_dpp v7, v1, v185 row_newbcast:6 row_mask:0xf bank_mask:0xf
	v_fmac_f32_dpp v231, v1, v186 row_newbcast:7 row_mask:0xf bank_mask:0xf
	v_fmac_f32_dpp v4, v1, v187 row_newbcast:8 row_mask:0xf bank_mask:0xf
	v_fmac_f32_dpp v7, v1, v188 row_newbcast:9 row_mask:0xf bank_mask:0xf
	v_fmac_f32_dpp v231, v1, v189 row_newbcast:10 row_mask:0xf bank_mask:0xf
	s_nop 0
	v_add_f32_e32 v190, v7, v4
	v_add_f32_e32 v190, v190, v231
	v_mov_b32_e32 v7, v16
	ds_read2_b32 v[0:1], v5 offset0:64 offset1:80
	ds_read_b32 v4, v154 offset:15312
	s_waitcnt lgkmcnt(2)
	v_mov_b32_e32 v231, v16
	v_fmac_f32_dpp v6, v2, v8 row_newbcast:0 row_mask:0xf bank_mask:0xf
	v_fmac_f32_dpp v7, v2, v9 row_newbcast:1 row_mask:0xf bank_mask:0xf
	v_fmac_f32_dpp v231, v2, v10 row_newbcast:2 row_mask:0xf bank_mask:0xf
	v_fmac_f32_dpp v6, v2, v11 row_newbcast:3 row_mask:0xf bank_mask:0xf
	v_fmac_f32_dpp v7, v2, v12 row_newbcast:4 row_mask:0xf bank_mask:0xf
	v_fmac_f32_dpp v231, v2, v13 row_newbcast:5 row_mask:0xf bank_mask:0xf
	v_fmac_f32_dpp v6, v2, v14 row_newbcast:6 row_mask:0xf bank_mask:0xf
	v_fmac_f32_dpp v7, v2, v15 row_newbcast:7 row_mask:0xf bank_mask:0xf
	v_fmac_f32_dpp v231, v2, v17 row_newbcast:8 row_mask:0xf bank_mask:0xf
	v_fmac_f32_dpp v6, v2, v18 row_newbcast:9 row_mask:0xf bank_mask:0xf
	v_fmac_f32_dpp v7, v2, v19 row_newbcast:10 row_mask:0xf bank_mask:0xf
	v_fmac_f32_dpp v231, v2, v174 row_newbcast:11 row_mask:0xf bank_mask:0xf
	v_fmac_f32_dpp v6, v2, v175 row_newbcast:12 row_mask:0xf bank_mask:0xf
	v_fmac_f32_dpp v7, v2, v176 row_newbcast:13 row_mask:0xf bank_mask:0xf
	v_fmac_f32_dpp v231, v2, v177 row_newbcast:14 row_mask:0xf bank_mask:0xf
	v_fmac_f32_dpp v6, v2, v178 row_newbcast:15 row_mask:0xf bank_mask:0xf
	v_fmac_f32_dpp v7, v3, v179 row_newbcast:0 row_mask:0xf bank_mask:0xf
	v_fmac_f32_dpp v231, v3, v180 row_newbcast:1 row_mask:0xf bank_mask:0xf
	v_fmac_f32_dpp v6, v3, v181 row_newbcast:2 row_mask:0xf bank_mask:0xf
	v_fmac_f32_dpp v7, v3, v182 row_newbcast:3 row_mask:0xf bank_mask:0xf
	v_fmac_f32_dpp v231, v3, v183 row_newbcast:4 row_mask:0xf bank_mask:0xf
	v_fmac_f32_dpp v6, v3, v184 row_newbcast:5 row_mask:0xf bank_mask:0xf
	v_fmac_f32_dpp v7, v3, v185 row_newbcast:6 row_mask:0xf bank_mask:0xf
	v_fmac_f32_dpp v231, v3, v186 row_newbcast:7 row_mask:0xf bank_mask:0xf
	v_fmac_f32_dpp v6, v3, v187 row_newbcast:8 row_mask:0xf bank_mask:0xf
	v_fmac_f32_dpp v7, v3, v188 row_newbcast:9 row_mask:0xf bank_mask:0xf
	v_fmac_f32_dpp v231, v3, v189 row_newbcast:10 row_mask:0xf bank_mask:0xf
	v_fmac_f32_dpp v6, v3, v190 row_newbcast:11 row_mask:0xf bank_mask:0xf
	s_nop 0
	v_add_f32_e32 v191, v6, v7
	v_add_f32_e32 v191, v191, v231
	ds_read2_b32 v[2:3], v5 offset0:128 offset1:144
	ds_read_b32 v6, v154 offset:15840
	s_waitcnt lgkmcnt(2)
; template <int J> __device__ __forceinline__ void macb(float& s, int Lq, float x) { asm volatile("v_fmac_f32_dpp %0, %1, %2 row_newbcast:%3 row_mask:0xf bank_mask:0xf" : "+v"(s) : "v"(Lq), "v"(x), "n"(J)); }
	v_mov_b32_e32 v231, v16
	v_fmac_f32_dpp v4, v0, v8 row_newbcast:0 row_mask:0xf bank_mask:0xf
	v_mov_b32_e32 v7, v16
	v_fmac_f32_dpp v7, v0, v9 row_newbcast:1 row_mask:0xf bank_mask:0xf
	v_fmac_f32_dpp v231, v0, v10 row_newbcast:2 row_mask:0xf bank_mask:0xf
	v_fmac_f32_dpp v4, v0, v11 row_newbcast:3 row_mask:0xf bank_mask:0xf
	v_fmac_f32_dpp v7, v0, v12 row_newbcast:4 row_mask:0xf bank_mask:0xf
	v_fmac_f32_dpp v231, v0, v13 row_newbcast:5 row_mask:0xf bank_mask:0xf
	v_fmac_f32_dpp v4, v0, v14 row_newbcast:6 row_mask:0xf bank_mask:0xf
	v_fmac_f32_dpp v7, v0, v15 row_newbcast:7 row_mask:0xf bank_mask:0xf
	v_fmac_f32_dpp v231, v0, v17 row_newbcast:8 row_mask:0xf bank_mask:0xf
	v_fmac_f32_dpp v4, v0, v18 row_newbcast:9 row_mask:0xf bank_mask:0xf
	v_fmac_f32_dpp v7, v0, v19 row_newbcast:10 row_mask:0xf bank_mask:0xf
	v_fmac_f32_dpp v231, v0, v174 row_newbcast:11 row_mask:0xf bank_mask:0xf
	v_fmac_f32_dpp v4, v0, v175 row_newbcast:12 row_mask:0xf bank_mask:0xf
	v_fmac_f32_dpp v7, v0, v176 row_newbcast:13 row_mask:0xf bank_mask:0xf
	v_fmac_f32_dpp v231, v0, v177 row_newbcast:14 row_mask:0xf bank_mask:0xf
	v_fmac_f32_dpp v4, v0, v178 row_newbcast:15 row_mask:0xf bank_mask:0xf
	v_fmac_f32_dpp v7, v1, v179 row_newbcast:0 row_mask:0xf bank_mask:0xf
	v_fmac_f32_dpp v231, v1, v180 row_newbcast:1 row_mask:0xf bank_mask:0xf
	v_fmac_f32_dpp v4, v1, v181 row_newbcast:2 row_mask:0xf bank_mask:0xf
	v_fmac_f32_dpp v7, v1, v182 row_newbcast:3 row_mask:0xf bank_mask:0xf
	v_fmac_f32_dpp v231, v1, v183 row_newbcast:4 row_mask:0xf bank_mask:0xf
	v_fmac_f32_dpp v4, v1, v184 row_newbcast:5 row_mask:0xf bank_mask:0xf
	v_fmac_f32_dpp v7, v1, v185 row_newbcast:6 row_mask:0xf bank_mask:0xf
	v_fmac_f32_dpp v231, v1, v186 row_newbcast:7 row_mask:0xf bank_mask:0xf
	v_fmac_f32_dpp v4, v1, v187 row_newbcast:8 row_mask:0xf bank_mask:0xf
	v_fmac_f32_dpp v7, v1, v188 row_newbcast:9 row_mask:0xf bank_mask:0xf
	v_fmac_f32_dpp v231, v1, v189 row_newbcast:10 row_mask:0xf bank_mask:0xf
	v_fmac_f32_dpp v4, v1, v190 row_newbcast:11 row_mask:0xf bank_mask:0xf
	v_fmac_f32_dpp v7, v1, v191 row_newbcast:12 row_mask:0xf bank_mask:0xf
	s_nop 0
	v_add_f32_e32 v192, v7, v4
	v_add_f32_e32 v192, v192, v231
	ds_read2_b32 v[0:1], v5 offset0:192 offset1:208
	ds_read_b32 v4, v154 offset:16368
	v_mov_b32_e32 v5, v16
	s_waitcnt lgkmcnt(2)
	v_mov_b32_e32 v231, v16
	v_fmac_f32_dpp v6, v2, v8 row_newbcast:0 row_mask:0xf bank_mask:0xf
	v_fmac_f32_dpp v5, v2, v9 row_newbcast:1 row_mask:0xf bank_mask:0xf
	v_fmac_f32_dpp v231, v2, v10 row_newbcast:2 row_mask:0xf bank_mask:0xf
	v_fmac_f32_dpp v6, v2, v11 row_newbcast:3 row_mask:0xf bank_mask:0xf
	v_fmac_f32_dpp v5, v2, v12 row_newbcast:4 row_mask:0xf bank_mask:0xf
	v_fmac_f32_dpp v231, v2, v13 row_newbcast:5 row_mask:0xf bank_mask:0xf
	v_fmac_f32_dpp v6, v2, v14 row_newbcast:6 row_mask:0xf bank_mask:0xf
	v_fmac_f32_dpp v5, v2, v15 row_newbcast:7 row_mask:0xf bank_mask:0xf
	v_fmac_f32_dpp v231, v2, v17 row_newbcast:8 row_mask:0xf bank_mask:0xf
	v_fmac_f32_dpp v6, v2, v18 row_newbcast:9 row_mask:0xf bank_mask:0xf
	v_fmac_f32_dpp v5, v2, v19 row_newbcast:10 row_mask:0xf bank_mask:0xf
	v_fmac_f32_dpp v231, v2, v174 row_newbcast:11 row_mask:0xf bank_mask:0xf
	v_fmac_f32_dpp v6, v2, v175 row_newbcast:12 row_mask:0xf bank_mask:0xf
	v_fmac_f32_dpp v5, v2, v176 row_newbcast:13 row_mask:0xf bank_mask:0xf
	v_fmac_f32_dpp v231, v2, v177 row_newbcast:14 row_mask:0xf bank_mask:0xf
	v_fmac_f32_dpp v6, v2, v178 row_newbcast:15 row_mask:0xf bank_mask:0xf
	v_fmac_f32_dpp v5, v3, v179 row_newbcast:0 row_mask:0xf bank_mask:0xf
	v_fmac_f32_dpp v231, v3, v180 row_newbcast:1 row_mask:0xf bank_mask:0xf
	v_fmac_f32_dpp v6, v3, v181 row_newbcast:2 row_mask:0xf bank_mask:0xf
	v_fmac_f32_dpp v5, v3, v182 row_newbcast:3 row_mask:0xf bank_mask:0xf
	v_fmac_f32_dpp v231, v3, v183 row_newbcast:4 row_mask:0xf bank_mask:0xf
	v_fmac_f32_dpp v6, v3, v184 row_newbcast:5 row_mask:0xf bank_mask:0xf
	v_fmac_f32_dpp v5, v3, v185 row_newbcast:6 row_mask:0xf bank_mask:0xf
	v_fmac_f32_dpp v231, v3, v186 row_newbcast:7 row_mask:0xf bank_mask:0xf
	v_fmac_f32_dpp v6, v3, v187 row_newbcast:8 row_mask:0xf bank_mask:0xf
	v_fmac_f32_dpp v5, v3, v188 row_newbcast:9 row_mask:0xf bank_mask:0xf
	v_fmac_f32_dpp v231, v3, v189 row_newbcast:10 row_mask:0xf bank_mask:0xf
	v_fmac_f32_dpp v6, v3, v190 row_newbcast:11 row_mask:0xf bank_mask:0xf
	v_fmac_f32_dpp v5, v3, v191 row_newbcast:12 row_mask:0xf bank_mask:0xf
	v_fmac_f32_dpp v231, v3, v192 row_newbcast:13 row_mask:0xf bank_mask:0xf
	s_nop 0
	v_add_f32_e32 v193, v6, v5
	v_add_f32_e32 v193, v193, v231
	v_add_u32_e32 v5, 0x2000, v157
	ds_read2_b32 v[2:3], v5 offset1:16
	ds_read_b32 v6, v154 offset:16896
	s_waitcnt lgkmcnt(2)
; template <int J> __device__ __forceinline__ void macb(float& s, int Lq, float x) { asm volatile("v_fmac_f32_dpp %0, %1, %2 row_newbcast:%3 row_mask:0xf bank_mask:0xf" : "+v"(s) : "v"(Lq), "v"(x), "n"(J)); }
	v_mov_b32_e32 v231, v16
	v_fmac_f32_dpp v4, v0, v8 row_newbcast:0 row_mask:0xf bank_mask:0xf
	v_mov_b32_e32 v7, v16
	v_fmac_f32_dpp v7, v0, v9 row_newbcast:1 row_mask:0xf bank_mask:0xf
	v_fmac_f32_dpp v231, v0, v10 row_newbcast:2 row_mask:0xf bank_mask:0xf
	v_fmac_f32_dpp v4, v0, v11 row_newbcast:3 row_mask:0xf bank_mask:0xf
	v_fmac_f32_dpp v7, v0, v12 row_newbcast:4 row_mask:0xf bank_mask:0xf
	v_fmac_f32_dpp v231, v0, v13 row_newbcast:5 row_mask:0xf bank_mask:0xf
	v_fmac_f32_dpp v4, v0, v14 row_newbcast:6 row_mask:0xf bank_mask:0xf
	v_fmac_f32_dpp v7, v0, v15 row_newbcast:7 row_mask:0xf bank_mask:0xf
	v_fmac_f32_dpp v231, v0, v17 row_newbcast:8 row_mask:0xf bank_mask:0xf
	v_fmac_f32_dpp v4, v0, v18 row_newbcast:9 row_mask:0xf bank_mask:0xf
	v_fmac_f32_dpp v7, v0, v19 row_newbcast:10 row_mask:0xf bank_mask:0xf
	v_fmac_f32_dpp v231, v0, v174 row_newbcast:11 row_mask:0xf bank_mask:0xf
	v_fmac_f32_dpp v4, v0, v175 row_newbcast:12 row_mask:0xf bank_mask:0xf
	v_fmac_f32_dpp v7, v0, v176 row_newbcast:13 row_mask:0xf bank_mask:0xf
	v_fmac_f32_dpp v231, v0, v177 row_newbcast:14 row_mask:0xf bank_mask:0xf
	v_fmac_f32_dpp v4, v0, v178 row_newbcast:15 row_mask:0xf bank_mask:0xf
	v_fmac_f32_dpp v7, v1, v179 row_newbcast:0 row_mask:0xf bank_mask:0xf
	v_fmac_f32_dpp v231, v1, v180 row_newbcast:1 row_mask:0xf bank_mask:0xf
	v_fmac_f32_dpp v4, v1, v181 row_newbcast:2 row_mask:0xf bank_mask:0xf
	v_fmac_f32_dpp v7, v1, v182 row_newbcast:3 row_mask:0xf bank_mask:0xf
	v_fmac_f32_dpp v231, v1, v183 row_newbcast:4 row_mask:0xf bank_mask:0xf
	v_fmac_f32_dpp v4, v1, v184 row_newbcast:5 row_mask:0xf bank_mask:0xf
	v_fmac_f32_dpp v7, v1, v185 row_newbcast:6 row_mask:0xf bank_mask:0xf
	v_fmac_f32_dpp v231, v1, v186 row_newbcast:7 row_mask:0xf bank_mask:0xf
	v_fmac_f32_dpp v4, v1, v187 row_newbcast:8 row_mask:0xf bank_mask:0xf
	v_fmac_f32_dpp v7, v1, v188 row_newbcast:9 row_mask:0xf bank_mask:0xf
	v_fmac_f32_dpp v231, v1, v189 row_newbcast:10 row_mask:0xf bank_mask:0xf
	v_fmac_f32_dpp v4, v1, v190 row_newbcast:11 row_mask:0xf bank_mask:0xf
	v_fmac_f32_dpp v7, v1, v191 row_newbcast:12 row_mask:0xf bank_mask:0xf
	v_fmac_f32_dpp v231, v1, v192 row_newbcast:13 row_mask:0xf bank_mask:0xf
	v_fmac_f32_dpp v4, v1, v193 row_newbcast:14 row_mask:0xf bank_mask:0xf
	s_nop 0
	v_add_f32_e32 v194, v7, v4
	v_add_f32_e32 v194, v194, v231
	v_mov_b32_e32 v195, v16
	ds_read2_b32 v[0:1], v5 offset0:64 offset1:80
	ds_read_b32 v4, v157 offset:8576
	ds_read_b32 v7, v154 offset:17424
	s_waitcnt lgkmcnt(3)
	v_mov_b32_e32 v231, v16
	v_fmac_f32_dpp v6, v2, v8 row_newbcast:0 row_mask:0xf bank_mask:0xf
	v_fmac_f32_dpp v195, v2, v9 row_newbcast:1 row_mask:0xf bank_mask:0xf
	v_fmac_f32_dpp v231, v2, v10 row_newbcast:2 row_mask:0xf bank_mask:0xf
	v_fmac_f32_dpp v6, v2, v11 row_newbcast:3 row_mask:0xf bank_mask:0xf
	v_fmac_f32_dpp v195, v2, v12 row_newbcast:4 row_mask:0xf bank_mask:0xf
	v_fmac_f32_dpp v231, v2, v13 row_newbcast:5 row_mask:0xf bank_mask:0xf
	v_fmac_f32_dpp v6, v2, v14 row_newbcast:6 row_mask:0xf bank_mask:0xf
	v_fmac_f32_dpp v195, v2, v15 row_newbcast:7 row_mask:0xf bank_mask:0xf
	v_fmac_f32_dpp v231, v2, v17 row_newbcast:8 row_mask:0xf bank_mask:0xf
	v_fmac_f32_dpp v6, v2, v18 row_newbcast:9 row_mask:0xf bank_mask:0xf
	v_fmac_f32_dpp v195, v2, v19 row_newbcast:10 row_mask:0xf bank_mask:0xf
	v_fmac_f32_dpp v231, v2, v174 row_newbcast:11 row_mask:0xf bank_mask:0xf
	v_fmac_f32_dpp v6, v2, v175 row_newbcast:12 row_mask:0xf bank_mask:0xf
	v_fmac_f32_dpp v195, v2, v176 row_newbcast:13 row_mask:0xf bank_mask:0xf
	v_fmac_f32_dpp v231, v2, v177 row_newbcast:14 row_mask:0xf bank_mask:0xf
	v_fmac_f32_dpp v6, v2, v178 row_newbcast:15 row_mask:0xf bank_mask:0xf
	v_fmac_f32_dpp v195, v3, v179 row_newbcast:0 row_mask:0xf bank_mask:0xf
	v_fmac_f32_dpp v231, v3, v180 row_newbcast:1 row_mask:0xf bank_mask:0xf
	v_fmac_f32_dpp v6, v3, v181 row_newbcast:2 row_mask:0xf bank_mask:0xf
	v_fmac_f32_dpp v195, v3, v182 row_newbcast:3 row_mask:0xf bank_mask:0xf
	v_fmac_f32_dpp v231, v3, v183 row_newbcast:4 row_mask:0xf bank_mask:0xf
	v_fmac_f32_dpp v6, v3, v184 row_newbcast:5 row_mask:0xf bank_mask:0xf
	v_fmac_f32_dpp v195, v3, v185 row_newbcast:6 row_mask:0xf bank_mask:0xf
	v_fmac_f32_dpp v231, v3, v186 row_newbcast:7 row_mask:0xf bank_mask:0xf
	v_fmac_f32_dpp v6, v3, v187 row_newbcast:8 row_mask:0xf bank_mask:0xf
	v_fmac_f32_dpp v195, v3, v188 row_newbcast:9 row_mask:0xf bank_mask:0xf
	v_fmac_f32_dpp v231, v3, v189 row_newbcast:10 row_mask:0xf bank_mask:0xf
	v_fmac_f32_dpp v6, v3, v190 row_newbcast:11 row_mask:0xf bank_mask:0xf
	v_fmac_f32_dpp v195, v3, v191 row_newbcast:12 row_mask:0xf bank_mask:0xf
	v_fmac_f32_dpp v231, v3, v192 row_newbcast:13 row_mask:0xf bank_mask:0xf
	v_fmac_f32_dpp v6, v3, v193 row_newbcast:14 row_mask:0xf bank_mask:0xf
	v_fmac_f32_dpp v195, v3, v194 row_newbcast:15 row_mask:0xf bank_mask:0xf
	s_nop 0
	v_add_f32_e32 v195, v6, v195
	v_add_f32_e32 v195, v195, v231
	v_mov_b32_e32 v196, v16
	ds_read2_b32 v[2:3], v5 offset0:128 offset1:144
	ds_read_b32 v6, v157 offset:8832
	ds_read_b32 v197, v154 offset:17952
	s_waitcnt lgkmcnt(3)
; template <int J> __device__ __forceinline__ void macb(float& s, int Lq, float x) { asm volatile("v_fmac_f32_dpp %0, %1, %2 row_newbcast:%3 row_mask:0xf bank_mask:0xf" : "+v"(s) : "v"(Lq), "v"(x), "n"(J)); }
	v_mov_b32_e32 v231, v16
	v_fmac_f32_dpp v7, v0, v8 row_newbcast:0 row_mask:0xf bank_mask:0xf
	v_fmac_f32_dpp v196, v0, v9 row_newbcast:1 row_mask:0xf bank_mask:0xf
	v_fmac_f32_dpp v231, v0, v10 row_newbcast:2 row_mask:0xf bank_mask:0xf
	v_fmac_f32_dpp v7, v0, v11 row_newbcast:3 row_mask:0xf bank_mask:0xf
	v_fmac_f32_dpp v196, v0, v12 row_newbcast:4 row_mask:0xf bank_mask:0xf
	v_fmac_f32_dpp v231, v0, v13 row_newbcast:5 row_mask:0xf bank_mask:0xf
	v_fmac_f32_dpp v7, v0, v14 row_newbcast:6 row_mask:0xf bank_mask:0xf
	v_fmac_f32_dpp v196, v0, v15 row_newbcast:7 row_mask:0xf bank_mask:0xf
	v_fmac_f32_dpp v231, v0, v17 row_newbcast:8 row_mask:0xf bank_mask:0xf
	v_fmac_f32_dpp v7, v0, v18 row_newbcast:9 row_mask:0xf bank_mask:0xf
	v_fmac_f32_dpp v196, v0, v19 row_newbcast:10 row_mask:0xf bank_mask:0xf
	v_fmac_f32_dpp v231, v0, v174 row_newbcast:11 row_mask:0xf bank_mask:0xf
	v_fmac_f32_dpp v7, v0, v175 row_newbcast:12 row_mask:0xf bank_mask:0xf
	v_fmac_f32_dpp v196, v0, v176 row_newbcast:13 row_mask:0xf bank_mask:0xf
	v_fmac_f32_dpp v231, v0, v177 row_newbcast:14 row_mask:0xf bank_mask:0xf
	v_fmac_f32_dpp v7, v0, v178 row_newbcast:15 row_mask:0xf bank_mask:0xf
	v_fmac_f32_dpp v196, v1, v179 row_newbcast:0 row_mask:0xf bank_mask:0xf
	v_fmac_f32_dpp v231, v1, v180 row_newbcast:1 row_mask:0xf bank_mask:0xf
	v_fmac_f32_dpp v7, v1, v181 row_newbcast:2 row_mask:0xf bank_mask:0xf
	v_fmac_f32_dpp v196, v1, v182 row_newbcast:3 row_mask:0xf bank_mask:0xf
	v_fmac_f32_dpp v231, v1, v183 row_newbcast:4 row_mask:0xf bank_mask:0xf
	v_fmac_f32_dpp v7, v1, v184 row_newbcast:5 row_mask:0xf bank_mask:0xf
	v_fmac_f32_dpp v196, v1, v185 row_newbcast:6 row_mask:0xf bank_mask:0xf
	v_fmac_f32_dpp v231, v1, v186 row_newbcast:7 row_mask:0xf bank_mask:0xf
	v_fmac_f32_dpp v7, v1, v187 row_newbcast:8 row_mask:0xf bank_mask:0xf
	v_fmac_f32_dpp v196, v1, v188 row_newbcast:9 row_mask:0xf bank_mask:0xf
	v_fmac_f32_dpp v231, v1, v189 row_newbcast:10 row_mask:0xf bank_mask:0xf
	v_fmac_f32_dpp v7, v1, v190 row_newbcast:11 row_mask:0xf bank_mask:0xf
	v_fmac_f32_dpp v196, v1, v191 row_newbcast:12 row_mask:0xf bank_mask:0xf
	v_fmac_f32_dpp v231, v1, v192 row_newbcast:13 row_mask:0xf bank_mask:0xf
	v_fmac_f32_dpp v7, v1, v193 row_newbcast:14 row_mask:0xf bank_mask:0xf
	v_fmac_f32_dpp v196, v1, v194 row_newbcast:15 row_mask:0xf bank_mask:0xf
	v_fmac_f32_dpp v231, v4, v195 row_newbcast:0 row_mask:0xf bank_mask:0xf
	s_nop 0
	v_add_f32_e32 v196, v196, v7
	v_add_f32_e32 v196, v196, v231
	ds_read2_b32 v[0:1], v5 offset0:192 offset1:208
	ds_read_b32 v4, v157 offset:9088
	ds_read_b32 v5, v154 offset:18480
	s_waitcnt lgkmcnt(3)
	v_mov_b32_e32 v231, v16
	v_fmac_f32_dpp v197, v2, v8 row_newbcast:0 row_mask:0xf bank_mask:0xf
	v_mov_b32_e32 v7, v16
	v_fmac_f32_dpp v7, v2, v9 row_newbcast:1 row_mask:0xf bank_mask:0xf
	v_fmac_f32_dpp v231, v2, v10 row_newbcast:2 row_mask:0xf bank_mask:0xf
	v_fmac_f32_dpp v197, v2, v11 row_newbcast:3 row_mask:0xf bank_mask:0xf
	v_fmac_f32_dpp v7, v2, v12 row_newbcast:4 row_mask:0xf bank_mask:0xf
	v_fmac_f32_dpp v231, v2, v13 row_newbcast:5 row_mask:0xf bank_mask:0xf
	v_fmac_f32_dpp v197, v2, v14 row_newbcast:6 row_mask:0xf bank_mask:0xf
	v_fmac_f32_dpp v7, v2, v15 row_newbcast:7 row_mask:0xf bank_mask:0xf
	v_fmac_f32_dpp v231, v2, v17 row_newbcast:8 row_mask:0xf bank_mask:0xf
	v_fmac_f32_dpp v197, v2, v18 row_newbcast:9 row_mask:0xf bank_mask:0xf
	v_fmac_f32_dpp v7, v2, v19 row_newbcast:10 row_mask:0xf bank_mask:0xf
	v_fmac_f32_dpp v231, v2, v174 row_newbcast:11 row_mask:0xf bank_mask:0xf
	v_fmac_f32_dpp v197, v2, v175 row_newbcast:12 row_mask:0xf bank_mask:0xf
	v_fmac_f32_dpp v7, v2, v176 row_newbcast:13 row_mask:0xf bank_mask:0xf
	v_fmac_f32_dpp v231, v2, v177 row_newbcast:14 row_mask:0xf bank_mask:0xf
	v_fmac_f32_dpp v197, v2, v178 row_newbcast:15 row_mask:0xf bank_mask:0xf
	v_fmac_f32_dpp v7, v3, v179 row_newbcast:0 row_mask:0xf bank_mask:0xf
	v_fmac_f32_dpp v231, v3, v180 row_newbcast:1 row_mask:0xf bank_mask:0xf
	v_fmac_f32_dpp v197, v3, v181 row_newbcast:2 row_mask:0xf bank_mask:0xf
	v_fmac_f32_dpp v7, v3, v182 row_newbcast:3 row_mask:0xf bank_mask:0xf
	v_fmac_f32_dpp v231, v3, v183 row_newbcast:4 row_mask:0xf bank_mask:0xf
	v_fmac_f32_dpp v197, v3, v184 row_newbcast:5 row_mask:0xf bank_mask:0xf
	v_fmac_f32_dpp v7, v3, v185 row_newbcast:6 row_mask:0xf bank_mask:0xf
	v_fmac_f32_dpp v231, v3, v186 row_newbcast:7 row_mask:0xf bank_mask:0xf
	v_fmac_f32_dpp v197, v3, v187 row_newbcast:8 row_mask:0xf bank_mask:0xf
	v_fmac_f32_dpp v7, v3, v188 row_newbcast:9 row_mask:0xf bank_mask:0xf
	v_fmac_f32_dpp v231, v3, v189 row_newbcast:10 row_mask:0xf bank_mask:0xf
	v_fmac_f32_dpp v197, v3, v190 row_newbcast:11 row_mask:0xf bank_mask:0xf
	v_fmac_f32_dpp v7, v3, v191 row_newbcast:12 row_mask:0xf bank_mask:0xf
	v_fmac_f32_dpp v231, v3, v192 row_newbcast:13 row_mask:0xf bank_mask:0xf
	v_fmac_f32_dpp v197, v3, v193 row_newbcast:14 row_mask:0xf bank_mask:0xf
	v_fmac_f32_dpp v7, v3, v194 row_newbcast:15 row_mask:0xf bank_mask:0xf
	v_fmac_f32_dpp v231, v6, v195 row_newbcast:0 row_mask:0xf bank_mask:0xf
	v_fmac_f32_dpp v197, v6, v196 row_newbcast:1 row_mask:0xf bank_mask:0xf
	s_nop 0
	v_add_f32_e32 v197, v197, v7
	v_add_f32_e32 v197, v197, v231
	v_add_u32_e32 v6, 0x2400, v157
	v_mov_b32_e32 v198, v16
	ds_read2_b32 v[2:3], v6 offset1:16
	ds_read_b32 v7, v157 offset:9344
	ds_read_b32 v199, v154 offset:19008
	s_waitcnt lgkmcnt(3)
; template <int J> __device__ __forceinline__ void macb(float& s, int Lq, float x) { asm volatile("v_fmac_f32_dpp %0, %1, %2 row_newbcast:%3 row_mask:0xf bank_mask:0xf" : "+v"(s) : "v"(Lq), "v"(x), "n"(J)); }
	v_mov_b32_e32 v231, v16
	v_fmac_f32_dpp v5, v0, v8 row_newbcast:0 row_mask:0xf bank_mask:0xf
	v_fmac_f32_dpp v198, v0, v9 row_newbcast:1 row_mask:0xf bank_mask:0xf
	v_fmac_f32_dpp v231, v0, v10 row_newbcast:2 row_mask:0xf bank_mask:0xf
	v_fmac_f32_dpp v5, v0, v11 row_newbcast:3 row_mask:0xf bank_mask:0xf
	v_fmac_f32_dpp v198, v0, v12 row_newbcast:4 row_mask:0xf bank_mask:0xf
	v_fmac_f32_dpp v231, v0, v13 row_newbcast:5 row_mask:0xf bank_mask:0xf
	v_fmac_f32_dpp v5, v0, v14 row_newbcast:6 row_mask:0xf bank_mask:0xf
	v_fmac_f32_dpp v198, v0, v15 row_newbcast:7 row_mask:0xf bank_mask:0xf
	v_fmac_f32_dpp v231, v0, v17 row_newbcast:8 row_mask:0xf bank_mask:0xf
	v_fmac_f32_dpp v5, v0, v18 row_newbcast:9 row_mask:0xf bank_mask:0xf
	v_fmac_f32_dpp v198, v0, v19 row_newbcast:10 row_mask:0xf bank_mask:0xf
	v_fmac_f32_dpp v231, v0, v174 row_newbcast:11 row_mask:0xf bank_mask:0xf
	v_fmac_f32_dpp v5, v0, v175 row_newbcast:12 row_mask:0xf bank_mask:0xf
	v_fmac_f32_dpp v198, v0, v176 row_newbcast:13 row_mask:0xf bank_mask:0xf
	v_fmac_f32_dpp v231, v0, v177 row_newbcast:14 row_mask:0xf bank_mask:0xf
	v_fmac_f32_dpp v5, v0, v178 row_newbcast:15 row_mask:0xf bank_mask:0xf
	v_fmac_f32_dpp v198, v1, v179 row_newbcast:0 row_mask:0xf bank_mask:0xf
	v_fmac_f32_dpp v231, v1, v180 row_newbcast:1 row_mask:0xf bank_mask:0xf
	v_fmac_f32_dpp v5, v1, v181 row_newbcast:2 row_mask:0xf bank_mask:0xf
	v_fmac_f32_dpp v198, v1, v182 row_newbcast:3 row_mask:0xf bank_mask:0xf
	v_fmac_f32_dpp v231, v1, v183 row_newbcast:4 row_mask:0xf bank_mask:0xf
	v_fmac_f32_dpp v5, v1, v184 row_newbcast:5 row_mask:0xf bank_mask:0xf
	v_fmac_f32_dpp v198, v1, v185 row_newbcast:6 row_mask:0xf bank_mask:0xf
	v_fmac_f32_dpp v231, v1, v186 row_newbcast:7 row_mask:0xf bank_mask:0xf
	v_fmac_f32_dpp v5, v1, v187 row_newbcast:8 row_mask:0xf bank_mask:0xf
	v_fmac_f32_dpp v198, v1, v188 row_newbcast:9 row_mask:0xf bank_mask:0xf
	v_fmac_f32_dpp v231, v1, v189 row_newbcast:10 row_mask:0xf bank_mask:0xf
	v_fmac_f32_dpp v5, v1, v190 row_newbcast:11 row_mask:0xf bank_mask:0xf
	v_fmac_f32_dpp v198, v1, v191 row_newbcast:12 row_mask:0xf bank_mask:0xf
	v_fmac_f32_dpp v231, v1, v192 row_newbcast:13 row_mask:0xf bank_mask:0xf
	v_fmac_f32_dpp v5, v1, v193 row_newbcast:14 row_mask:0xf bank_mask:0xf
	v_fmac_f32_dpp v198, v1, v194 row_newbcast:15 row_mask:0xf bank_mask:0xf
	v_fmac_f32_dpp v231, v4, v195 row_newbcast:0 row_mask:0xf bank_mask:0xf
	v_fmac_f32_dpp v5, v4, v196 row_newbcast:1 row_mask:0xf bank_mask:0xf
	v_fmac_f32_dpp v198, v4, v197 row_newbcast:2 row_mask:0xf bank_mask:0xf
	s_nop 0
	v_add_f32_e32 v198, v198, v5
	v_add_f32_e32 v198, v198, v231
	ds_read2_b32 v[0:1], v6 offset0:64 offset1:80
	ds_read_b32 v4, v157 offset:9600
	ds_read_b32 v5, v154 offset:19536
	s_waitcnt lgkmcnt(3)
	v_mov_b32_e32 v231, v16
	v_fmac_f32_dpp v199, v2, v8 row_newbcast:0 row_mask:0xf bank_mask:0xf
	v_mov_b32_e32 v200, v16
	v_fmac_f32_dpp v200, v2, v9 row_newbcast:1 row_mask:0xf bank_mask:0xf
	v_fmac_f32_dpp v231, v2, v10 row_newbcast:2 row_mask:0xf bank_mask:0xf
	v_fmac_f32_dpp v199, v2, v11 row_newbcast:3 row_mask:0xf bank_mask:0xf
	v_fmac_f32_dpp v200, v2, v12 row_newbcast:4 row_mask:0xf bank_mask:0xf
	v_fmac_f32_dpp v231, v2, v13 row_newbcast:5 row_mask:0xf bank_mask:0xf
	v_fmac_f32_dpp v199, v2, v14 row_newbcast:6 row_mask:0xf bank_mask:0xf
	v_fmac_f32_dpp v200, v2, v15 row_newbcast:7 row_mask:0xf bank_mask:0xf
	v_fmac_f32_dpp v231, v2, v17 row_newbcast:8 row_mask:0xf bank_mask:0xf
	v_fmac_f32_dpp v199, v2, v18 row_newbcast:9 row_mask:0xf bank_mask:0xf
	v_fmac_f32_dpp v200, v2, v19 row_newbcast:10 row_mask:0xf bank_mask:0xf
	v_fmac_f32_dpp v231, v2, v174 row_newbcast:11 row_mask:0xf bank_mask:0xf
	v_fmac_f32_dpp v199, v2, v175 row_newbcast:12 row_mask:0xf bank_mask:0xf
	v_fmac_f32_dpp v200, v2, v176 row_newbcast:13 row_mask:0xf bank_mask:0xf
	v_fmac_f32_dpp v231, v2, v177 row_newbcast:14 row_mask:0xf bank_mask:0xf
	v_fmac_f32_dpp v199, v2, v178 row_newbcast:15 row_mask:0xf bank_mask:0xf
	v_fmac_f32_dpp v200, v3, v179 row_newbcast:0 row_mask:0xf bank_mask:0xf
	v_fmac_f32_dpp v231, v3, v180 row_newbcast:1 row_mask:0xf bank_mask:0xf
	v_fmac_f32_dpp v199, v3, v181 row_newbcast:2 row_mask:0xf bank_mask:0xf
	v_fmac_f32_dpp v200, v3, v182 row_newbcast:3 row_mask:0xf bank_mask:0xf
	v_fmac_f32_dpp v231, v3, v183 row_newbcast:4 row_mask:0xf bank_mask:0xf
	v_fmac_f32_dpp v199, v3, v184 row_newbcast:5 row_mask:0xf bank_mask:0xf
	v_fmac_f32_dpp v200, v3, v185 row_newbcast:6 row_mask:0xf bank_mask:0xf
	v_fmac_f32_dpp v231, v3, v186 row_newbcast:7 row_mask:0xf bank_mask:0xf
	v_fmac_f32_dpp v199, v3, v187 row_newbcast:8 row_mask:0xf bank_mask:0xf
	v_fmac_f32_dpp v200, v3, v188 row_newbcast:9 row_mask:0xf bank_mask:0xf
	v_fmac_f32_dpp v231, v3, v189 row_newbcast:10 row_mask:0xf bank_mask:0xf
	v_fmac_f32_dpp v199, v3, v190 row_newbcast:11 row_mask:0xf bank_mask:0xf
	v_fmac_f32_dpp v200, v3, v191 row_newbcast:12 row_mask:0xf bank_mask:0xf
	v_fmac_f32_dpp v231, v3, v192 row_newbcast:13 row_mask:0xf bank_mask:0xf
	v_fmac_f32_dpp v199, v3, v193 row_newbcast:14 row_mask:0xf bank_mask:0xf
	v_fmac_f32_dpp v200, v3, v194 row_newbcast:15 row_mask:0xf bank_mask:0xf
	v_fmac_f32_dpp v231, v7, v195 row_newbcast:0 row_mask:0xf bank_mask:0xf
	v_fmac_f32_dpp v199, v7, v196 row_newbcast:1 row_mask:0xf bank_mask:0xf
	v_fmac_f32_dpp v200, v7, v197 row_newbcast:2 row_mask:0xf bank_mask:0xf
	v_fmac_f32_dpp v231, v7, v198 row_newbcast:3 row_mask:0xf bank_mask:0xf
	s_nop 0
	v_add_f32_e32 v199, v199, v200
	v_add_f32_e32 v199, v199, v231
	v_mov_b32_e32 v200, v16
	ds_read2_b32 v[2:3], v6 offset0:128 offset1:144
	ds_read_b32 v7, v157 offset:9856
	ds_read_b32 v201, v154 offset:20064
	s_waitcnt lgkmcnt(3)
; template <int J> __device__ __forceinline__ void macb(float& s, int Lq, float x) { asm volatile("v_fmac_f32_dpp %0, %1, %2 row_newbcast:%3 row_mask:0xf bank_mask:0xf" : "+v"(s) : "v"(Lq), "v"(x), "n"(J)); }
	v_mov_b32_e32 v231, v16
	v_fmac_f32_dpp v5, v0, v8 row_newbcast:0 row_mask:0xf bank_mask:0xf
	v_fmac_f32_dpp v200, v0, v9 row_newbcast:1 row_mask:0xf bank_mask:0xf
	v_fmac_f32_dpp v231, v0, v10 row_newbcast:2 row_mask:0xf bank_mask:0xf
	v_fmac_f32_dpp v5, v0, v11 row_newbcast:3 row_mask:0xf bank_mask:0xf
	v_fmac_f32_dpp v200, v0, v12 row_newbcast:4 row_mask:0xf bank_mask:0xf
	v_fmac_f32_dpp v231, v0, v13 row_newbcast:5 row_mask:0xf bank_mask:0xf
	v_fmac_f32_dpp v5, v0, v14 row_newbcast:6 row_mask:0xf bank_mask:0xf
	v_fmac_f32_dpp v200, v0, v15 row_newbcast:7 row_mask:0xf bank_mask:0xf
	v_fmac_f32_dpp v231, v0, v17 row_newbcast:8 row_mask:0xf bank_mask:0xf
	v_fmac_f32_dpp v5, v0, v18 row_newbcast:9 row_mask:0xf bank_mask:0xf
	v_fmac_f32_dpp v200, v0, v19 row_newbcast:10 row_mask:0xf bank_mask:0xf
	v_fmac_f32_dpp v231, v0, v174 row_newbcast:11 row_mask:0xf bank_mask:0xf
	v_fmac_f32_dpp v5, v0, v175 row_newbcast:12 row_mask:0xf bank_mask:0xf
	v_fmac_f32_dpp v200, v0, v176 row_newbcast:13 row_mask:0xf bank_mask:0xf
	v_fmac_f32_dpp v231, v0, v177 row_newbcast:14 row_mask:0xf bank_mask:0xf
	v_fmac_f32_dpp v5, v0, v178 row_newbcast:15 row_mask:0xf bank_mask:0xf
	v_fmac_f32_dpp v200, v1, v179 row_newbcast:0 row_mask:0xf bank_mask:0xf
	v_fmac_f32_dpp v231, v1, v180 row_newbcast:1 row_mask:0xf bank_mask:0xf
	v_fmac_f32_dpp v5, v1, v181 row_newbcast:2 row_mask:0xf bank_mask:0xf
	v_fmac_f32_dpp v200, v1, v182 row_newbcast:3 row_mask:0xf bank_mask:0xf
	v_fmac_f32_dpp v231, v1, v183 row_newbcast:4 row_mask:0xf bank_mask:0xf
	v_fmac_f32_dpp v5, v1, v184 row_newbcast:5 row_mask:0xf bank_mask:0xf
	v_fmac_f32_dpp v200, v1, v185 row_newbcast:6 row_mask:0xf bank_mask:0xf
	v_fmac_f32_dpp v231, v1, v186 row_newbcast:7 row_mask:0xf bank_mask:0xf
	v_fmac_f32_dpp v5, v1, v187 row_newbcast:8 row_mask:0xf bank_mask:0xf
	v_fmac_f32_dpp v200, v1, v188 row_newbcast:9 row_mask:0xf bank_mask:0xf
	v_fmac_f32_dpp v231, v1, v189 row_newbcast:10 row_mask:0xf bank_mask:0xf
	v_fmac_f32_dpp v5, v1, v190 row_newbcast:11 row_mask:0xf bank_mask:0xf
	v_fmac_f32_dpp v200, v1, v191 row_newbcast:12 row_mask:0xf bank_mask:0xf
	v_fmac_f32_dpp v231, v1, v192 row_newbcast:13 row_mask:0xf bank_mask:0xf
	v_fmac_f32_dpp v5, v1, v193 row_newbcast:14 row_mask:0xf bank_mask:0xf
	v_fmac_f32_dpp v200, v1, v194 row_newbcast:15 row_mask:0xf bank_mask:0xf
	v_fmac_f32_dpp v231, v4, v195 row_newbcast:0 row_mask:0xf bank_mask:0xf
	v_fmac_f32_dpp v5, v4, v196 row_newbcast:1 row_mask:0xf bank_mask:0xf
	v_fmac_f32_dpp v200, v4, v197 row_newbcast:2 row_mask:0xf bank_mask:0xf
	v_fmac_f32_dpp v231, v4, v198 row_newbcast:3 row_mask:0xf bank_mask:0xf
	v_fmac_f32_dpp v5, v4, v199 row_newbcast:4 row_mask:0xf bank_mask:0xf
	s_nop 0
	v_add_f32_e32 v200, v200, v5
	v_add_f32_e32 v200, v200, v231
	ds_read2_b32 v[0:1], v6 offset0:192 offset1:208
	ds_read_b32 v4, v157 offset:10112
	ds_read_b32 v5, v154 offset:20592
	s_waitcnt lgkmcnt(3)
	v_mov_b32_e32 v231, v16
	v_fmac_f32_dpp v201, v2, v8 row_newbcast:0 row_mask:0xf bank_mask:0xf
	v_mov_b32_e32 v6, v16
	v_fmac_f32_dpp v6, v2, v9 row_newbcast:1 row_mask:0xf bank_mask:0xf
	v_fmac_f32_dpp v231, v2, v10 row_newbcast:2 row_mask:0xf bank_mask:0xf
	v_fmac_f32_dpp v201, v2, v11 row_newbcast:3 row_mask:0xf bank_mask:0xf
	v_fmac_f32_dpp v6, v2, v12 row_newbcast:4 row_mask:0xf bank_mask:0xf
	v_fmac_f32_dpp v231, v2, v13 row_newbcast:5 row_mask:0xf bank_mask:0xf
	v_fmac_f32_dpp v201, v2, v14 row_newbcast:6 row_mask:0xf bank_mask:0xf
	v_fmac_f32_dpp v6, v2, v15 row_newbcast:7 row_mask:0xf bank_mask:0xf
	v_fmac_f32_dpp v231, v2, v17 row_newbcast:8 row_mask:0xf bank_mask:0xf
	v_fmac_f32_dpp v201, v2, v18 row_newbcast:9 row_mask:0xf bank_mask:0xf
	v_fmac_f32_dpp v6, v2, v19 row_newbcast:10 row_mask:0xf bank_mask:0xf
	v_fmac_f32_dpp v231, v2, v174 row_newbcast:11 row_mask:0xf bank_mask:0xf
	v_fmac_f32_dpp v201, v2, v175 row_newbcast:12 row_mask:0xf bank_mask:0xf
	v_fmac_f32_dpp v6, v2, v176 row_newbcast:13 row_mask:0xf bank_mask:0xf
	v_fmac_f32_dpp v231, v2, v177 row_newbcast:14 row_mask:0xf bank_mask:0xf
	v_fmac_f32_dpp v201, v2, v178 row_newbcast:15 row_mask:0xf bank_mask:0xf
	v_fmac_f32_dpp v6, v3, v179 row_newbcast:0 row_mask:0xf bank_mask:0xf
	v_fmac_f32_dpp v231, v3, v180 row_newbcast:1 row_mask:0xf bank_mask:0xf
	v_fmac_f32_dpp v201, v3, v181 row_newbcast:2 row_mask:0xf bank_mask:0xf
	v_fmac_f32_dpp v6, v3, v182 row_newbcast:3 row_mask:0xf bank_mask:0xf
	v_fmac_f32_dpp v231, v3, v183 row_newbcast:4 row_mask:0xf bank_mask:0xf
	v_fmac_f32_dpp v201, v3, v184 row_newbcast:5 row_mask:0xf bank_mask:0xf
	v_fmac_f32_dpp v6, v3, v185 row_newbcast:6 row_mask:0xf bank_mask:0xf
	v_fmac_f32_dpp v231, v3, v186 row_newbcast:7 row_mask:0xf bank_mask:0xf
	v_fmac_f32_dpp v201, v3, v187 row_newbcast:8 row_mask:0xf bank_mask:0xf
	v_fmac_f32_dpp v6, v3, v188 row_newbcast:9 row_mask:0xf bank_mask:0xf
	v_fmac_f32_dpp v231, v3, v189 row_newbcast:10 row_mask:0xf bank_mask:0xf
	v_fmac_f32_dpp v201, v3, v190 row_newbcast:11 row_mask:0xf bank_mask:0xf
	v_fmac_f32_dpp v6, v3, v191 row_newbcast:12 row_mask:0xf bank_mask:0xf
	v_fmac_f32_dpp v231, v3, v192 row_newbcast:13 row_mask:0xf bank_mask:0xf
	v_fmac_f32_dpp v201, v3, v193 row_newbcast:14 row_mask:0xf bank_mask:0xf
	v_fmac_f32_dpp v6, v3, v194 row_newbcast:15 row_mask:0xf bank_mask:0xf
	v_fmac_f32_dpp v231, v7, v195 row_newbcast:0 row_mask:0xf bank_mask:0xf
	v_fmac_f32_dpp v201, v7, v196 row_newbcast:1 row_mask:0xf bank_mask:0xf
	v_fmac_f32_dpp v6, v7, v197 row_newbcast:2 row_mask:0xf bank_mask:0xf
	v_fmac_f32_dpp v231, v7, v198 row_newbcast:3 row_mask:0xf bank_mask:0xf
	v_fmac_f32_dpp v201, v7, v199 row_newbcast:4 row_mask:0xf bank_mask:0xf
	v_fmac_f32_dpp v6, v7, v200 row_newbcast:5 row_mask:0xf bank_mask:0xf
	s_nop 0
	v_add_f32_e32 v201, v201, v6
	v_add_f32_e32 v201, v201, v231
	v_add_u32_e32 v6, 0x2800, v157
	v_mov_b32_e32 v202, v16
	ds_read2_b32 v[2:3], v6 offset1:16
	ds_read_b32 v7, v157 offset:10368
	ds_read_b32 v203, v154 offset:21120
	s_waitcnt lgkmcnt(3)
; template <int J> __device__ __forceinline__ void macb(float& s, int Lq, float x) { asm volatile("v_fmac_f32_dpp %0, %1, %2 row_newbcast:%3 row_mask:0xf bank_mask:0xf" : "+v"(s) : "v"(Lq), "v"(x), "n"(J)); }
	v_mov_b32_e32 v231, v16
	v_fmac_f32_dpp v5, v0, v8 row_newbcast:0 row_mask:0xf bank_mask:0xf
	v_fmac_f32_dpp v202, v0, v9 row_newbcast:1 row_mask:0xf bank_mask:0xf
	v_fmac_f32_dpp v231, v0, v10 row_newbcast:2 row_mask:0xf bank_mask:0xf
	v_fmac_f32_dpp v5, v0, v11 row_newbcast:3 row_mask:0xf bank_mask:0xf
	v_fmac_f32_dpp v202, v0, v12 row_newbcast:4 row_mask:0xf bank_mask:0xf
	v_fmac_f32_dpp v231, v0, v13 row_newbcast:5 row_mask:0xf bank_mask:0xf
	v_fmac_f32_dpp v5, v0, v14 row_newbcast:6 row_mask:0xf bank_mask:0xf
	v_fmac_f32_dpp v202, v0, v15 row_newbcast:7 row_mask:0xf bank_mask:0xf
	v_fmac_f32_dpp v231, v0, v17 row_newbcast:8 row_mask:0xf bank_mask:0xf
	v_fmac_f32_dpp v5, v0, v18 row_newbcast:9 row_mask:0xf bank_mask:0xf
	v_fmac_f32_dpp v202, v0, v19 row_newbcast:10 row_mask:0xf bank_mask:0xf
	v_fmac_f32_dpp v231, v0, v174 row_newbcast:11 row_mask:0xf bank_mask:0xf
	v_fmac_f32_dpp v5, v0, v175 row_newbcast:12 row_mask:0xf bank_mask:0xf
	v_fmac_f32_dpp v202, v0, v176 row_newbcast:13 row_mask:0xf bank_mask:0xf
	v_fmac_f32_dpp v231, v0, v177 row_newbcast:14 row_mask:0xf bank_mask:0xf
	v_fmac_f32_dpp v5, v0, v178 row_newbcast:15 row_mask:0xf bank_mask:0xf
	v_fmac_f32_dpp v202, v1, v179 row_newbcast:0 row_mask:0xf bank_mask:0xf
	v_fmac_f32_dpp v231, v1, v180 row_newbcast:1 row_mask:0xf bank_mask:0xf
	v_fmac_f32_dpp v5, v1, v181 row_newbcast:2 row_mask:0xf bank_mask:0xf
	v_fmac_f32_dpp v202, v1, v182 row_newbcast:3 row_mask:0xf bank_mask:0xf
	v_fmac_f32_dpp v231, v1, v183 row_newbcast:4 row_mask:0xf bank_mask:0xf
	v_fmac_f32_dpp v5, v1, v184 row_newbcast:5 row_mask:0xf bank_mask:0xf
	v_fmac_f32_dpp v202, v1, v185 row_newbcast:6 row_mask:0xf bank_mask:0xf
	v_fmac_f32_dpp v231, v1, v186 row_newbcast:7 row_mask:0xf bank_mask:0xf
	v_fmac_f32_dpp v5, v1, v187 row_newbcast:8 row_mask:0xf bank_mask:0xf
	v_fmac_f32_dpp v202, v1, v188 row_newbcast:9 row_mask:0xf bank_mask:0xf
	v_fmac_f32_dpp v231, v1, v189 row_newbcast:10 row_mask:0xf bank_mask:0xf
	v_fmac_f32_dpp v5, v1, v190 row_newbcast:11 row_mask:0xf bank_mask:0xf
	v_fmac_f32_dpp v202, v1, v191 row_newbcast:12 row_mask:0xf bank_mask:0xf
	v_fmac_f32_dpp v231, v1, v192 row_newbcast:13 row_mask:0xf bank_mask:0xf
	v_fmac_f32_dpp v5, v1, v193 row_newbcast:14 row_mask:0xf bank_mask:0xf
	v_fmac_f32_dpp v202, v1, v194 row_newbcast:15 row_mask:0xf bank_mask:0xf
	v_fmac_f32_dpp v231, v4, v195 row_newbcast:0 row_mask:0xf bank_mask:0xf
	v_fmac_f32_dpp v5, v4, v196 row_newbcast:1 row_mask:0xf bank_mask:0xf
	v_fmac_f32_dpp v202, v4, v197 row_newbcast:2 row_mask:0xf bank_mask:0xf
	v_fmac_f32_dpp v231, v4, v198 row_newbcast:3 row_mask:0xf bank_mask:0xf
	v_fmac_f32_dpp v5, v4, v199 row_newbcast:4 row_mask:0xf bank_mask:0xf
	v_fmac_f32_dpp v202, v4, v200 row_newbcast:5 row_mask:0xf bank_mask:0xf
	v_fmac_f32_dpp v231, v4, v201 row_newbcast:6 row_mask:0xf bank_mask:0xf
	s_nop 0
	v_add_f32_e32 v202, v202, v5
	v_add_f32_e32 v202, v202, v231
	ds_read2_b32 v[0:1], v6 offset0:64 offset1:80
	ds_read_b32 v4, v157 offset:10624
	ds_read_b32 v5, v154 offset:21648
	s_waitcnt lgkmcnt(3)
	v_mov_b32_e32 v231, v16
	v_fmac_f32_dpp v203, v2, v8 row_newbcast:0 row_mask:0xf bank_mask:0xf
	v_mov_b32_e32 v204, v16
	v_fmac_f32_dpp v204, v2, v9 row_newbcast:1 row_mask:0xf bank_mask:0xf
	v_fmac_f32_dpp v231, v2, v10 row_newbcast:2 row_mask:0xf bank_mask:0xf
	v_fmac_f32_dpp v203, v2, v11 row_newbcast:3 row_mask:0xf bank_mask:0xf
	v_fmac_f32_dpp v204, v2, v12 row_newbcast:4 row_mask:0xf bank_mask:0xf
	v_fmac_f32_dpp v231, v2, v13 row_newbcast:5 row_mask:0xf bank_mask:0xf
	v_fmac_f32_dpp v203, v2, v14 row_newbcast:6 row_mask:0xf bank_mask:0xf
	v_fmac_f32_dpp v204, v2, v15 row_newbcast:7 row_mask:0xf bank_mask:0xf
	v_fmac_f32_dpp v231, v2, v17 row_newbcast:8 row_mask:0xf bank_mask:0xf
	v_fmac_f32_dpp v203, v2, v18 row_newbcast:9 row_mask:0xf bank_mask:0xf
	v_fmac_f32_dpp v204, v2, v19 row_newbcast:10 row_mask:0xf bank_mask:0xf
	v_fmac_f32_dpp v231, v2, v174 row_newbcast:11 row_mask:0xf bank_mask:0xf
	v_fmac_f32_dpp v203, v2, v175 row_newbcast:12 row_mask:0xf bank_mask:0xf
	v_fmac_f32_dpp v204, v2, v176 row_newbcast:13 row_mask:0xf bank_mask:0xf
	v_fmac_f32_dpp v231, v2, v177 row_newbcast:14 row_mask:0xf bank_mask:0xf
	v_fmac_f32_dpp v203, v2, v178 row_newbcast:15 row_mask:0xf bank_mask:0xf
	v_fmac_f32_dpp v204, v3, v179 row_newbcast:0 row_mask:0xf bank_mask:0xf
	v_fmac_f32_dpp v231, v3, v180 row_newbcast:1 row_mask:0xf bank_mask:0xf
	v_fmac_f32_dpp v203, v3, v181 row_newbcast:2 row_mask:0xf bank_mask:0xf
	v_fmac_f32_dpp v204, v3, v182 row_newbcast:3 row_mask:0xf bank_mask:0xf
	v_fmac_f32_dpp v231, v3, v183 row_newbcast:4 row_mask:0xf bank_mask:0xf
	v_fmac_f32_dpp v203, v3, v184 row_newbcast:5 row_mask:0xf bank_mask:0xf
	v_fmac_f32_dpp v204, v3, v185 row_newbcast:6 row_mask:0xf bank_mask:0xf
	v_fmac_f32_dpp v231, v3, v186 row_newbcast:7 row_mask:0xf bank_mask:0xf
	v_fmac_f32_dpp v203, v3, v187 row_newbcast:8 row_mask:0xf bank_mask:0xf
	v_fmac_f32_dpp v204, v3, v188 row_newbcast:9 row_mask:0xf bank_mask:0xf
	v_fmac_f32_dpp v231, v3, v189 row_newbcast:10 row_mask:0xf bank_mask:0xf
	v_fmac_f32_dpp v203, v3, v190 row_newbcast:11 row_mask:0xf bank_mask:0xf
	v_fmac_f32_dpp v204, v3, v191 row_newbcast:12 row_mask:0xf bank_mask:0xf
	v_fmac_f32_dpp v231, v3, v192 row_newbcast:13 row_mask:0xf bank_mask:0xf
	v_fmac_f32_dpp v203, v3, v193 row_newbcast:14 row_mask:0xf bank_mask:0xf
	v_fmac_f32_dpp v204, v3, v194 row_newbcast:15 row_mask:0xf bank_mask:0xf
	v_fmac_f32_dpp v231, v7, v195 row_newbcast:0 row_mask:0xf bank_mask:0xf
	v_fmac_f32_dpp v203, v7, v196 row_newbcast:1 row_mask:0xf bank_mask:0xf
	v_fmac_f32_dpp v204, v7, v197 row_newbcast:2 row_mask:0xf bank_mask:0xf
	v_fmac_f32_dpp v231, v7, v198 row_newbcast:3 row_mask:0xf bank_mask:0xf
	v_fmac_f32_dpp v203, v7, v199 row_newbcast:4 row_mask:0xf bank_mask:0xf
	v_fmac_f32_dpp v204, v7, v200 row_newbcast:5 row_mask:0xf bank_mask:0xf
	v_fmac_f32_dpp v231, v7, v201 row_newbcast:6 row_mask:0xf bank_mask:0xf
	v_fmac_f32_dpp v203, v7, v202 row_newbcast:7 row_mask:0xf bank_mask:0xf
	s_nop 0
	v_add_f32_e32 v203, v203, v204
	v_add_f32_e32 v203, v203, v231
	v_mov_b32_e32 v204, v16
	ds_read2_b32 v[2:3], v6 offset0:128 offset1:144
	ds_read_b32 v7, v157 offset:10880
	ds_read_b32 v205, v154 offset:22176
	s_waitcnt lgkmcnt(3)
; template <int J> __device__ __forceinline__ void macb(float& s, int Lq, float x) { asm volatile("v_fmac_f32_dpp %0, %1, %2 row_newbcast:%3 row_mask:0xf bank_mask:0xf" : "+v"(s) : "v"(Lq), "v"(x), "n"(J)); }
	v_mov_b32_e32 v231, v16
	v_fmac_f32_dpp v5, v0, v8 row_newbcast:0 row_mask:0xf bank_mask:0xf
	v_fmac_f32_dpp v204, v0, v9 row_newbcast:1 row_mask:0xf bank_mask:0xf
	v_fmac_f32_dpp v231, v0, v10 row_newbcast:2 row_mask:0xf bank_mask:0xf
	v_fmac_f32_dpp v5, v0, v11 row_newbcast:3 row_mask:0xf bank_mask:0xf
	v_fmac_f32_dpp v204, v0, v12 row_newbcast:4 row_mask:0xf bank_mask:0xf
	v_fmac_f32_dpp v231, v0, v13 row_newbcast:5 row_mask:0xf bank_mask:0xf
	v_fmac_f32_dpp v5, v0, v14 row_newbcast:6 row_mask:0xf bank_mask:0xf
	v_fmac_f32_dpp v204, v0, v15 row_newbcast:7 row_mask:0xf bank_mask:0xf
	v_fmac_f32_dpp v231, v0, v17 row_newbcast:8 row_mask:0xf bank_mask:0xf
	v_fmac_f32_dpp v5, v0, v18 row_newbcast:9 row_mask:0xf bank_mask:0xf
	v_fmac_f32_dpp v204, v0, v19 row_newbcast:10 row_mask:0xf bank_mask:0xf
	v_fmac_f32_dpp v231, v0, v174 row_newbcast:11 row_mask:0xf bank_mask:0xf
	v_fmac_f32_dpp v5, v0, v175 row_newbcast:12 row_mask:0xf bank_mask:0xf
	v_fmac_f32_dpp v204, v0, v176 row_newbcast:13 row_mask:0xf bank_mask:0xf
	v_fmac_f32_dpp v231, v0, v177 row_newbcast:14 row_mask:0xf bank_mask:0xf
	v_fmac_f32_dpp v5, v0, v178 row_newbcast:15 row_mask:0xf bank_mask:0xf
	v_fmac_f32_dpp v204, v1, v179 row_newbcast:0 row_mask:0xf bank_mask:0xf
	v_fmac_f32_dpp v231, v1, v180 row_newbcast:1 row_mask:0xf bank_mask:0xf
	v_fmac_f32_dpp v5, v1, v181 row_newbcast:2 row_mask:0xf bank_mask:0xf
	v_fmac_f32_dpp v204, v1, v182 row_newbcast:3 row_mask:0xf bank_mask:0xf
	v_fmac_f32_dpp v231, v1, v183 row_newbcast:4 row_mask:0xf bank_mask:0xf
	v_fmac_f32_dpp v5, v1, v184 row_newbcast:5 row_mask:0xf bank_mask:0xf
	v_fmac_f32_dpp v204, v1, v185 row_newbcast:6 row_mask:0xf bank_mask:0xf
	v_fmac_f32_dpp v231, v1, v186 row_newbcast:7 row_mask:0xf bank_mask:0xf
	v_fmac_f32_dpp v5, v1, v187 row_newbcast:8 row_mask:0xf bank_mask:0xf
	v_fmac_f32_dpp v204, v1, v188 row_newbcast:9 row_mask:0xf bank_mask:0xf
	v_fmac_f32_dpp v231, v1, v189 row_newbcast:10 row_mask:0xf bank_mask:0xf
	v_fmac_f32_dpp v5, v1, v190 row_newbcast:11 row_mask:0xf bank_mask:0xf
	v_fmac_f32_dpp v204, v1, v191 row_newbcast:12 row_mask:0xf bank_mask:0xf
	v_fmac_f32_dpp v231, v1, v192 row_newbcast:13 row_mask:0xf bank_mask:0xf
	v_fmac_f32_dpp v5, v1, v193 row_newbcast:14 row_mask:0xf bank_mask:0xf
	v_fmac_f32_dpp v204, v1, v194 row_newbcast:15 row_mask:0xf bank_mask:0xf
	v_fmac_f32_dpp v231, v4, v195 row_newbcast:0 row_mask:0xf bank_mask:0xf
	v_fmac_f32_dpp v5, v4, v196 row_newbcast:1 row_mask:0xf bank_mask:0xf
	v_fmac_f32_dpp v204, v4, v197 row_newbcast:2 row_mask:0xf bank_mask:0xf
	v_fmac_f32_dpp v231, v4, v198 row_newbcast:3 row_mask:0xf bank_mask:0xf
	v_fmac_f32_dpp v5, v4, v199 row_newbcast:4 row_mask:0xf bank_mask:0xf
	v_fmac_f32_dpp v204, v4, v200 row_newbcast:5 row_mask:0xf bank_mask:0xf
	v_fmac_f32_dpp v231, v4, v201 row_newbcast:6 row_mask:0xf bank_mask:0xf
	v_fmac_f32_dpp v5, v4, v202 row_newbcast:7 row_mask:0xf bank_mask:0xf
	v_fmac_f32_dpp v204, v4, v203 row_newbcast:8 row_mask:0xf bank_mask:0xf
	s_nop 0
	v_add_f32_e32 v204, v204, v5
	v_add_f32_e32 v204, v204, v231
	ds_read2_b32 v[0:1], v6 offset0:192 offset1:208
	ds_read_b32 v4, v157 offset:11136
	ds_read_b32 v5, v154 offset:22704
	s_waitcnt lgkmcnt(3)
	v_mov_b32_e32 v231, v16
	v_fmac_f32_dpp v205, v2, v8 row_newbcast:0 row_mask:0xf bank_mask:0xf
	v_mov_b32_e32 v6, v16
	v_fmac_f32_dpp v6, v2, v9 row_newbcast:1 row_mask:0xf bank_mask:0xf
	v_fmac_f32_dpp v231, v2, v10 row_newbcast:2 row_mask:0xf bank_mask:0xf
	v_fmac_f32_dpp v205, v2, v11 row_newbcast:3 row_mask:0xf bank_mask:0xf
	v_fmac_f32_dpp v6, v2, v12 row_newbcast:4 row_mask:0xf bank_mask:0xf
	v_fmac_f32_dpp v231, v2, v13 row_newbcast:5 row_mask:0xf bank_mask:0xf
	v_fmac_f32_dpp v205, v2, v14 row_newbcast:6 row_mask:0xf bank_mask:0xf
	v_fmac_f32_dpp v6, v2, v15 row_newbcast:7 row_mask:0xf bank_mask:0xf
	v_fmac_f32_dpp v231, v2, v17 row_newbcast:8 row_mask:0xf bank_mask:0xf
	v_fmac_f32_dpp v205, v2, v18 row_newbcast:9 row_mask:0xf bank_mask:0xf
	v_fmac_f32_dpp v6, v2, v19 row_newbcast:10 row_mask:0xf bank_mask:0xf
	v_fmac_f32_dpp v231, v2, v174 row_newbcast:11 row_mask:0xf bank_mask:0xf
	v_fmac_f32_dpp v205, v2, v175 row_newbcast:12 row_mask:0xf bank_mask:0xf
	v_fmac_f32_dpp v6, v2, v176 row_newbcast:13 row_mask:0xf bank_mask:0xf
	v_fmac_f32_dpp v231, v2, v177 row_newbcast:14 row_mask:0xf bank_mask:0xf
	v_fmac_f32_dpp v205, v2, v178 row_newbcast:15 row_mask:0xf bank_mask:0xf
	v_fmac_f32_dpp v6, v3, v179 row_newbcast:0 row_mask:0xf bank_mask:0xf
	v_fmac_f32_dpp v231, v3, v180 row_newbcast:1 row_mask:0xf bank_mask:0xf
	v_fmac_f32_dpp v205, v3, v181 row_newbcast:2 row_mask:0xf bank_mask:0xf
	v_fmac_f32_dpp v6, v3, v182 row_newbcast:3 row_mask:0xf bank_mask:0xf
	v_fmac_f32_dpp v231, v3, v183 row_newbcast:4 row_mask:0xf bank_mask:0xf
	v_fmac_f32_dpp v205, v3, v184 row_newbcast:5 row_mask:0xf bank_mask:0xf
	v_fmac_f32_dpp v6, v3, v185 row_newbcast:6 row_mask:0xf bank_mask:0xf
	v_fmac_f32_dpp v231, v3, v186 row_newbcast:7 row_mask:0xf bank_mask:0xf
	v_fmac_f32_dpp v205, v3, v187 row_newbcast:8 row_mask:0xf bank_mask:0xf
	v_fmac_f32_dpp v6, v3, v188 row_newbcast:9 row_mask:0xf bank_mask:0xf
	v_fmac_f32_dpp v231, v3, v189 row_newbcast:10 row_mask:0xf bank_mask:0xf
	v_fmac_f32_dpp v205, v3, v190 row_newbcast:11 row_mask:0xf bank_mask:0xf
	v_fmac_f32_dpp v6, v3, v191 row_newbcast:12 row_mask:0xf bank_mask:0xf
	v_fmac_f32_dpp v231, v3, v192 row_newbcast:13 row_mask:0xf bank_mask:0xf
	v_fmac_f32_dpp v205, v3, v193 row_newbcast:14 row_mask:0xf bank_mask:0xf
	v_fmac_f32_dpp v6, v3, v194 row_newbcast:15 row_mask:0xf bank_mask:0xf
	v_fmac_f32_dpp v231, v7, v195 row_newbcast:0 row_mask:0xf bank_mask:0xf
	v_fmac_f32_dpp v205, v7, v196 row_newbcast:1 row_mask:0xf bank_mask:0xf
	v_fmac_f32_dpp v6, v7, v197 row_newbcast:2 row_mask:0xf bank_mask:0xf
	v_fmac_f32_dpp v231, v7, v198 row_newbcast:3 row_mask:0xf bank_mask:0xf
	v_fmac_f32_dpp v205, v7, v199 row_newbcast:4 row_mask:0xf bank_mask:0xf
	v_fmac_f32_dpp v6, v7, v200 row_newbcast:5 row_mask:0xf bank_mask:0xf
	v_fmac_f32_dpp v231, v7, v201 row_newbcast:6 row_mask:0xf bank_mask:0xf
	v_fmac_f32_dpp v205, v7, v202 row_newbcast:7 row_mask:0xf bank_mask:0xf
	v_fmac_f32_dpp v6, v7, v203 row_newbcast:8 row_mask:0xf bank_mask:0xf
	v_fmac_f32_dpp v231, v7, v204 row_newbcast:9 row_mask:0xf bank_mask:0xf
	s_nop 0
	v_add_f32_e32 v205, v205, v6
	v_add_f32_e32 v205, v205, v231
	v_add_u32_e32 v6, 0x2c00, v157
	v_mov_b32_e32 v206, v16
	ds_read2_b32 v[2:3], v6 offset1:16
	ds_read_b32 v7, v157 offset:11392
	ds_read_b32 v207, v154 offset:23232
	s_waitcnt lgkmcnt(3)
; template <int J> __device__ __forceinline__ void macb(float& s, int Lq, float x) { asm volatile("v_fmac_f32_dpp %0, %1, %2 row_newbcast:%3 row_mask:0xf bank_mask:0xf" : "+v"(s) : "v"(Lq), "v"(x), "n"(J)); }
	v_mov_b32_e32 v231, v16
	v_fmac_f32_dpp v5, v0, v8 row_newbcast:0 row_mask:0xf bank_mask:0xf
	v_fmac_f32_dpp v206, v0, v9 row_newbcast:1 row_mask:0xf bank_mask:0xf
	v_fmac_f32_dpp v231, v0, v10 row_newbcast:2 row_mask:0xf bank_mask:0xf
	v_fmac_f32_dpp v5, v0, v11 row_newbcast:3 row_mask:0xf bank_mask:0xf
	v_fmac_f32_dpp v206, v0, v12 row_newbcast:4 row_mask:0xf bank_mask:0xf
	v_fmac_f32_dpp v231, v0, v13 row_newbcast:5 row_mask:0xf bank_mask:0xf
	v_fmac_f32_dpp v5, v0, v14 row_newbcast:6 row_mask:0xf bank_mask:0xf
	v_fmac_f32_dpp v206, v0, v15 row_newbcast:7 row_mask:0xf bank_mask:0xf
	v_fmac_f32_dpp v231, v0, v17 row_newbcast:8 row_mask:0xf bank_mask:0xf
	v_fmac_f32_dpp v5, v0, v18 row_newbcast:9 row_mask:0xf bank_mask:0xf
	v_fmac_f32_dpp v206, v0, v19 row_newbcast:10 row_mask:0xf bank_mask:0xf
	v_fmac_f32_dpp v231, v0, v174 row_newbcast:11 row_mask:0xf bank_mask:0xf
	v_fmac_f32_dpp v5, v0, v175 row_newbcast:12 row_mask:0xf bank_mask:0xf
	v_fmac_f32_dpp v206, v0, v176 row_newbcast:13 row_mask:0xf bank_mask:0xf
	v_fmac_f32_dpp v231, v0, v177 row_newbcast:14 row_mask:0xf bank_mask:0xf
	v_fmac_f32_dpp v5, v0, v178 row_newbcast:15 row_mask:0xf bank_mask:0xf
	v_fmac_f32_dpp v206, v1, v179 row_newbcast:0 row_mask:0xf bank_mask:0xf
	v_fmac_f32_dpp v231, v1, v180 row_newbcast:1 row_mask:0xf bank_mask:0xf
	v_fmac_f32_dpp v5, v1, v181 row_newbcast:2 row_mask:0xf bank_mask:0xf
	v_fmac_f32_dpp v206, v1, v182 row_newbcast:3 row_mask:0xf bank_mask:0xf
	v_fmac_f32_dpp v231, v1, v183 row_newbcast:4 row_mask:0xf bank_mask:0xf
	v_fmac_f32_dpp v5, v1, v184 row_newbcast:5 row_mask:0xf bank_mask:0xf
	v_fmac_f32_dpp v206, v1, v185 row_newbcast:6 row_mask:0xf bank_mask:0xf
	v_fmac_f32_dpp v231, v1, v186 row_newbcast:7 row_mask:0xf bank_mask:0xf
	v_fmac_f32_dpp v5, v1, v187 row_newbcast:8 row_mask:0xf bank_mask:0xf
	v_fmac_f32_dpp v206, v1, v188 row_newbcast:9 row_mask:0xf bank_mask:0xf
	v_fmac_f32_dpp v231, v1, v189 row_newbcast:10 row_mask:0xf bank_mask:0xf
	v_fmac_f32_dpp v5, v1, v190 row_newbcast:11 row_mask:0xf bank_mask:0xf
	v_fmac_f32_dpp v206, v1, v191 row_newbcast:12 row_mask:0xf bank_mask:0xf
	v_fmac_f32_dpp v231, v1, v192 row_newbcast:13 row_mask:0xf bank_mask:0xf
	v_fmac_f32_dpp v5, v1, v193 row_newbcast:14 row_mask:0xf bank_mask:0xf
	v_fmac_f32_dpp v206, v1, v194 row_newbcast:15 row_mask:0xf bank_mask:0xf
	v_fmac_f32_dpp v231, v4, v195 row_newbcast:0 row_mask:0xf bank_mask:0xf
	v_fmac_f32_dpp v5, v4, v196 row_newbcast:1 row_mask:0xf bank_mask:0xf
	v_fmac_f32_dpp v206, v4, v197 row_newbcast:2 row_mask:0xf bank_mask:0xf
	v_fmac_f32_dpp v231, v4, v198 row_newbcast:3 row_mask:0xf bank_mask:0xf
	v_fmac_f32_dpp v5, v4, v199 row_newbcast:4 row_mask:0xf bank_mask:0xf
	v_fmac_f32_dpp v206, v4, v200 row_newbcast:5 row_mask:0xf bank_mask:0xf
	v_fmac_f32_dpp v231, v4, v201 row_newbcast:6 row_mask:0xf bank_mask:0xf
	v_fmac_f32_dpp v5, v4, v202 row_newbcast:7 row_mask:0xf bank_mask:0xf
	v_fmac_f32_dpp v206, v4, v203 row_newbcast:8 row_mask:0xf bank_mask:0xf
	v_fmac_f32_dpp v231, v4, v204 row_newbcast:9 row_mask:0xf bank_mask:0xf
	v_fmac_f32_dpp v5, v4, v205 row_newbcast:10 row_mask:0xf bank_mask:0xf
	s_nop 0
	v_add_f32_e32 v206, v206, v5
	v_add_f32_e32 v206, v206, v231
	ds_read2_b32 v[0:1], v6 offset0:64 offset1:80
	ds_read_b32 v4, v157 offset:11648
	ds_read_b32 v5, v154 offset:23760
	s_waitcnt lgkmcnt(3)
	v_mov_b32_e32 v231, v16
	v_fmac_f32_dpp v207, v2, v8 row_newbcast:0 row_mask:0xf bank_mask:0xf
	v_mov_b32_e32 v208, v16
	v_fmac_f32_dpp v208, v2, v9 row_newbcast:1 row_mask:0xf bank_mask:0xf
	v_fmac_f32_dpp v231, v2, v10 row_newbcast:2 row_mask:0xf bank_mask:0xf
	v_fmac_f32_dpp v207, v2, v11 row_newbcast:3 row_mask:0xf bank_mask:0xf
	v_fmac_f32_dpp v208, v2, v12 row_newbcast:4 row_mask:0xf bank_mask:0xf
	v_fmac_f32_dpp v231, v2, v13 row_newbcast:5 row_mask:0xf bank_mask:0xf
	v_fmac_f32_dpp v207, v2, v14 row_newbcast:6 row_mask:0xf bank_mask:0xf
	v_fmac_f32_dpp v208, v2, v15 row_newbcast:7 row_mask:0xf bank_mask:0xf
	v_fmac_f32_dpp v231, v2, v17 row_newbcast:8 row_mask:0xf bank_mask:0xf
	v_fmac_f32_dpp v207, v2, v18 row_newbcast:9 row_mask:0xf bank_mask:0xf
	v_fmac_f32_dpp v208, v2, v19 row_newbcast:10 row_mask:0xf bank_mask:0xf
	v_fmac_f32_dpp v231, v2, v174 row_newbcast:11 row_mask:0xf bank_mask:0xf
	v_fmac_f32_dpp v207, v2, v175 row_newbcast:12 row_mask:0xf bank_mask:0xf
	v_fmac_f32_dpp v208, v2, v176 row_newbcast:13 row_mask:0xf bank_mask:0xf
	v_fmac_f32_dpp v231, v2, v177 row_newbcast:14 row_mask:0xf bank_mask:0xf
	v_fmac_f32_dpp v207, v2, v178 row_newbcast:15 row_mask:0xf bank_mask:0xf
	v_fmac_f32_dpp v208, v3, v179 row_newbcast:0 row_mask:0xf bank_mask:0xf
	v_fmac_f32_dpp v231, v3, v180 row_newbcast:1 row_mask:0xf bank_mask:0xf
	v_fmac_f32_dpp v207, v3, v181 row_newbcast:2 row_mask:0xf bank_mask:0xf
	v_fmac_f32_dpp v208, v3, v182 row_newbcast:3 row_mask:0xf bank_mask:0xf
	v_fmac_f32_dpp v231, v3, v183 row_newbcast:4 row_mask:0xf bank_mask:0xf
	v_fmac_f32_dpp v207, v3, v184 row_newbcast:5 row_mask:0xf bank_mask:0xf
	v_fmac_f32_dpp v208, v3, v185 row_newbcast:6 row_mask:0xf bank_mask:0xf
	v_fmac_f32_dpp v231, v3, v186 row_newbcast:7 row_mask:0xf bank_mask:0xf
	v_fmac_f32_dpp v207, v3, v187 row_newbcast:8 row_mask:0xf bank_mask:0xf
	v_fmac_f32_dpp v208, v3, v188 row_newbcast:9 row_mask:0xf bank_mask:0xf
	v_fmac_f32_dpp v231, v3, v189 row_newbcast:10 row_mask:0xf bank_mask:0xf
	v_fmac_f32_dpp v207, v3, v190 row_newbcast:11 row_mask:0xf bank_mask:0xf
	v_fmac_f32_dpp v208, v3, v191 row_newbcast:12 row_mask:0xf bank_mask:0xf
	v_fmac_f32_dpp v231, v3, v192 row_newbcast:13 row_mask:0xf bank_mask:0xf
	v_fmac_f32_dpp v207, v3, v193 row_newbcast:14 row_mask:0xf bank_mask:0xf
	v_fmac_f32_dpp v208, v3, v194 row_newbcast:15 row_mask:0xf bank_mask:0xf
	v_fmac_f32_dpp v231, v7, v195 row_newbcast:0 row_mask:0xf bank_mask:0xf
	v_fmac_f32_dpp v207, v7, v196 row_newbcast:1 row_mask:0xf bank_mask:0xf
	v_fmac_f32_dpp v208, v7, v197 row_newbcast:2 row_mask:0xf bank_mask:0xf
	v_fmac_f32_dpp v231, v7, v198 row_newbcast:3 row_mask:0xf bank_mask:0xf
	v_fmac_f32_dpp v207, v7, v199 row_newbcast:4 row_mask:0xf bank_mask:0xf
	v_fmac_f32_dpp v208, v7, v200 row_newbcast:5 row_mask:0xf bank_mask:0xf
	v_fmac_f32_dpp v231, v7, v201 row_newbcast:6 row_mask:0xf bank_mask:0xf
	v_fmac_f32_dpp v207, v7, v202 row_newbcast:7 row_mask:0xf bank_mask:0xf
	v_fmac_f32_dpp v208, v7, v203 row_newbcast:8 row_mask:0xf bank_mask:0xf
	v_fmac_f32_dpp v231, v7, v204 row_newbcast:9 row_mask:0xf bank_mask:0xf
	v_fmac_f32_dpp v207, v7, v205 row_newbcast:10 row_mask:0xf bank_mask:0xf
	v_fmac_f32_dpp v208, v7, v206 row_newbcast:11 row_mask:0xf bank_mask:0xf
	s_nop 0
	v_add_f32_e32 v207, v207, v208
	v_add_f32_e32 v207, v207, v231
	v_mov_b32_e32 v208, v16
	ds_read2_b32 v[2:3], v6 offset0:128 offset1:144
	ds_read_b32 v7, v157 offset:11904
	ds_read_b32 v209, v154 offset:24288
	s_waitcnt lgkmcnt(3)
; template <int J> __device__ __forceinline__ void macb(float& s, int Lq, float x) { asm volatile("v_fmac_f32_dpp %0, %1, %2 row_newbcast:%3 row_mask:0xf bank_mask:0xf" : "+v"(s) : "v"(Lq), "v"(x), "n"(J)); }
	v_mov_b32_e32 v231, v16
	v_fmac_f32_dpp v5, v0, v8 row_newbcast:0 row_mask:0xf bank_mask:0xf
	v_fmac_f32_dpp v208, v0, v9 row_newbcast:1 row_mask:0xf bank_mask:0xf
	v_fmac_f32_dpp v231, v0, v10 row_newbcast:2 row_mask:0xf bank_mask:0xf
	v_fmac_f32_dpp v5, v0, v11 row_newbcast:3 row_mask:0xf bank_mask:0xf
	v_fmac_f32_dpp v208, v0, v12 row_newbcast:4 row_mask:0xf bank_mask:0xf
	v_fmac_f32_dpp v231, v0, v13 row_newbcast:5 row_mask:0xf bank_mask:0xf
	v_fmac_f32_dpp v5, v0, v14 row_newbcast:6 row_mask:0xf bank_mask:0xf
	v_fmac_f32_dpp v208, v0, v15 row_newbcast:7 row_mask:0xf bank_mask:0xf
	v_fmac_f32_dpp v231, v0, v17 row_newbcast:8 row_mask:0xf bank_mask:0xf
	v_fmac_f32_dpp v5, v0, v18 row_newbcast:9 row_mask:0xf bank_mask:0xf
	v_fmac_f32_dpp v208, v0, v19 row_newbcast:10 row_mask:0xf bank_mask:0xf
	v_fmac_f32_dpp v231, v0, v174 row_newbcast:11 row_mask:0xf bank_mask:0xf
	v_fmac_f32_dpp v5, v0, v175 row_newbcast:12 row_mask:0xf bank_mask:0xf
	v_fmac_f32_dpp v208, v0, v176 row_newbcast:13 row_mask:0xf bank_mask:0xf
	v_fmac_f32_dpp v231, v0, v177 row_newbcast:14 row_mask:0xf bank_mask:0xf
	v_fmac_f32_dpp v5, v0, v178 row_newbcast:15 row_mask:0xf bank_mask:0xf
	v_fmac_f32_dpp v208, v1, v179 row_newbcast:0 row_mask:0xf bank_mask:0xf
	v_fmac_f32_dpp v231, v1, v180 row_newbcast:1 row_mask:0xf bank_mask:0xf
	v_fmac_f32_dpp v5, v1, v181 row_newbcast:2 row_mask:0xf bank_mask:0xf
	v_fmac_f32_dpp v208, v1, v182 row_newbcast:3 row_mask:0xf bank_mask:0xf
	v_fmac_f32_dpp v231, v1, v183 row_newbcast:4 row_mask:0xf bank_mask:0xf
	v_fmac_f32_dpp v5, v1, v184 row_newbcast:5 row_mask:0xf bank_mask:0xf
	v_fmac_f32_dpp v208, v1, v185 row_newbcast:6 row_mask:0xf bank_mask:0xf
	v_fmac_f32_dpp v231, v1, v186 row_newbcast:7 row_mask:0xf bank_mask:0xf
	v_fmac_f32_dpp v5, v1, v187 row_newbcast:8 row_mask:0xf bank_mask:0xf
	v_fmac_f32_dpp v208, v1, v188 row_newbcast:9 row_mask:0xf bank_mask:0xf
	v_fmac_f32_dpp v231, v1, v189 row_newbcast:10 row_mask:0xf bank_mask:0xf
	v_fmac_f32_dpp v5, v1, v190 row_newbcast:11 row_mask:0xf bank_mask:0xf
	v_fmac_f32_dpp v208, v1, v191 row_newbcast:12 row_mask:0xf bank_mask:0xf
	v_fmac_f32_dpp v231, v1, v192 row_newbcast:13 row_mask:0xf bank_mask:0xf
	v_fmac_f32_dpp v5, v1, v193 row_newbcast:14 row_mask:0xf bank_mask:0xf
	v_fmac_f32_dpp v208, v1, v194 row_newbcast:15 row_mask:0xf bank_mask:0xf
	v_fmac_f32_dpp v231, v4, v195 row_newbcast:0 row_mask:0xf bank_mask:0xf
	v_fmac_f32_dpp v5, v4, v196 row_newbcast:1 row_mask:0xf bank_mask:0xf
	v_fmac_f32_dpp v208, v4, v197 row_newbcast:2 row_mask:0xf bank_mask:0xf
	v_fmac_f32_dpp v231, v4, v198 row_newbcast:3 row_mask:0xf bank_mask:0xf
	v_fmac_f32_dpp v5, v4, v199 row_newbcast:4 row_mask:0xf bank_mask:0xf
	v_fmac_f32_dpp v208, v4, v200 row_newbcast:5 row_mask:0xf bank_mask:0xf
	v_fmac_f32_dpp v231, v4, v201 row_newbcast:6 row_mask:0xf bank_mask:0xf
	v_fmac_f32_dpp v5, v4, v202 row_newbcast:7 row_mask:0xf bank_mask:0xf
	v_fmac_f32_dpp v208, v4, v203 row_newbcast:8 row_mask:0xf bank_mask:0xf
	v_fmac_f32_dpp v231, v4, v204 row_newbcast:9 row_mask:0xf bank_mask:0xf
	v_fmac_f32_dpp v5, v4, v205 row_newbcast:10 row_mask:0xf bank_mask:0xf
	v_fmac_f32_dpp v208, v4, v206 row_newbcast:11 row_mask:0xf bank_mask:0xf
	v_fmac_f32_dpp v231, v4, v207 row_newbcast:12 row_mask:0xf bank_mask:0xf
	s_nop 0
	v_add_f32_e32 v208, v208, v5
	v_add_f32_e32 v208, v208, v231
	ds_read2_b32 v[0:1], v6 offset0:192 offset1:208
	ds_read_b32 v6, v157 offset:12160
	ds_read_b32 v210, v154 offset:24816
	s_waitcnt lgkmcnt(3)
	v_mov_b32_e32 v231, v16
	v_fmac_f32_dpp v209, v2, v8 row_newbcast:0 row_mask:0xf bank_mask:0xf
	v_mov_b32_e32 v4, v16
	v_fmac_f32_dpp v4, v2, v9 row_newbcast:1 row_mask:0xf bank_mask:0xf
	v_fmac_f32_dpp v231, v2, v10 row_newbcast:2 row_mask:0xf bank_mask:0xf
	v_fmac_f32_dpp v209, v2, v11 row_newbcast:3 row_mask:0xf bank_mask:0xf
	v_fmac_f32_dpp v4, v2, v12 row_newbcast:4 row_mask:0xf bank_mask:0xf
	v_fmac_f32_dpp v231, v2, v13 row_newbcast:5 row_mask:0xf bank_mask:0xf
	v_fmac_f32_dpp v209, v2, v14 row_newbcast:6 row_mask:0xf bank_mask:0xf
	v_fmac_f32_dpp v4, v2, v15 row_newbcast:7 row_mask:0xf bank_mask:0xf
	v_fmac_f32_dpp v231, v2, v17 row_newbcast:8 row_mask:0xf bank_mask:0xf
	v_fmac_f32_dpp v209, v2, v18 row_newbcast:9 row_mask:0xf bank_mask:0xf
	v_fmac_f32_dpp v4, v2, v19 row_newbcast:10 row_mask:0xf bank_mask:0xf
	v_fmac_f32_dpp v231, v2, v174 row_newbcast:11 row_mask:0xf bank_mask:0xf
	v_fmac_f32_dpp v209, v2, v175 row_newbcast:12 row_mask:0xf bank_mask:0xf
	v_fmac_f32_dpp v4, v2, v176 row_newbcast:13 row_mask:0xf bank_mask:0xf
	v_fmac_f32_dpp v231, v2, v177 row_newbcast:14 row_mask:0xf bank_mask:0xf
	v_fmac_f32_dpp v209, v2, v178 row_newbcast:15 row_mask:0xf bank_mask:0xf
	v_fmac_f32_dpp v4, v3, v179 row_newbcast:0 row_mask:0xf bank_mask:0xf
	v_fmac_f32_dpp v231, v3, v180 row_newbcast:1 row_mask:0xf bank_mask:0xf
	v_fmac_f32_dpp v209, v3, v181 row_newbcast:2 row_mask:0xf bank_mask:0xf
	v_fmac_f32_dpp v4, v3, v182 row_newbcast:3 row_mask:0xf bank_mask:0xf
	v_fmac_f32_dpp v231, v3, v183 row_newbcast:4 row_mask:0xf bank_mask:0xf
	v_fmac_f32_dpp v209, v3, v184 row_newbcast:5 row_mask:0xf bank_mask:0xf
	v_fmac_f32_dpp v4, v3, v185 row_newbcast:6 row_mask:0xf bank_mask:0xf
	v_fmac_f32_dpp v231, v3, v186 row_newbcast:7 row_mask:0xf bank_mask:0xf
	v_fmac_f32_dpp v209, v3, v187 row_newbcast:8 row_mask:0xf bank_mask:0xf
	v_fmac_f32_dpp v4, v3, v188 row_newbcast:9 row_mask:0xf bank_mask:0xf
	v_fmac_f32_dpp v231, v3, v189 row_newbcast:10 row_mask:0xf bank_mask:0xf
	v_fmac_f32_dpp v209, v3, v190 row_newbcast:11 row_mask:0xf bank_mask:0xf
	v_fmac_f32_dpp v4, v3, v191 row_newbcast:12 row_mask:0xf bank_mask:0xf
; template <int J> __device__ __forceinline__ void macb(float& s, int Lq, float x) { asm volatile("v_fmac_f32_dpp %0, %1, %2 row_newbcast:%3 row_mask:0xf bank_mask:0xf" : "+v"(s) : "v"(Lq), "v"(x), "n"(J)); }
	v_fmac_f32_dpp v231, v3, v192 row_newbcast:13 row_mask:0xf bank_mask:0xf
	v_fmac_f32_dpp v209, v3, v193 row_newbcast:14 row_mask:0xf bank_mask:0xf
	v_fmac_f32_dpp v4, v3, v194 row_newbcast:15 row_mask:0xf bank_mask:0xf
	v_fmac_f32_dpp v231, v7, v195 row_newbcast:0 row_mask:0xf bank_mask:0xf
	v_fmac_f32_dpp v209, v7, v196 row_newbcast:1 row_mask:0xf bank_mask:0xf
	v_fmac_f32_dpp v4, v7, v197 row_newbcast:2 row_mask:0xf bank_mask:0xf
	v_fmac_f32_dpp v231, v7, v198 row_newbcast:3 row_mask:0xf bank_mask:0xf
	v_fmac_f32_dpp v209, v7, v199 row_newbcast:4 row_mask:0xf bank_mask:0xf
	v_fmac_f32_dpp v4, v7, v200 row_newbcast:5 row_mask:0xf bank_mask:0xf
	v_fmac_f32_dpp v231, v7, v201 row_newbcast:6 row_mask:0xf bank_mask:0xf
	v_fmac_f32_dpp v209, v7, v202 row_newbcast:7 row_mask:0xf bank_mask:0xf
	v_fmac_f32_dpp v4, v7, v203 row_newbcast:8 row_mask:0xf bank_mask:0xf
	v_fmac_f32_dpp v231, v7, v204 row_newbcast:9 row_mask:0xf bank_mask:0xf
	v_fmac_f32_dpp v209, v7, v205 row_newbcast:10 row_mask:0xf bank_mask:0xf
	v_fmac_f32_dpp v4, v7, v206 row_newbcast:11 row_mask:0xf bank_mask:0xf
	v_fmac_f32_dpp v231, v7, v207 row_newbcast:12 row_mask:0xf bank_mask:0xf
	v_fmac_f32_dpp v209, v7, v208 row_newbcast:13 row_mask:0xf bank_mask:0xf
	s_nop 0
	v_add_f32_e32 v209, v209, v4
	v_add_f32_e32 v209, v209, v231
	v_add_u32_e32 v213, 0x3000, v157
	ds_read2_b32 v[4:5], v213 offset1:16
	ds_read_b32 v211, v157 offset:12416
	ds_read_b32 v212, v154 offset:25344
	s_waitcnt lgkmcnt(3)
	v_mov_b32_e32 v231, v16
	v_fmac_f32_dpp v210, v0, v8 row_newbcast:0 row_mask:0xf bank_mask:0xf
	v_mov_b32_e32 v2, v16
	v_fmac_f32_dpp v2, v0, v9 row_newbcast:1 row_mask:0xf bank_mask:0xf
	v_fmac_f32_dpp v231, v0, v10 row_newbcast:2 row_mask:0xf bank_mask:0xf
	v_fmac_f32_dpp v210, v0, v11 row_newbcast:3 row_mask:0xf bank_mask:0xf
	v_fmac_f32_dpp v2, v0, v12 row_newbcast:4 row_mask:0xf bank_mask:0xf
	v_fmac_f32_dpp v231, v0, v13 row_newbcast:5 row_mask:0xf bank_mask:0xf
	v_fmac_f32_dpp v210, v0, v14 row_newbcast:6 row_mask:0xf bank_mask:0xf
	v_fmac_f32_dpp v2, v0, v15 row_newbcast:7 row_mask:0xf bank_mask:0xf
	v_fmac_f32_dpp v231, v0, v17 row_newbcast:8 row_mask:0xf bank_mask:0xf
	v_fmac_f32_dpp v210, v0, v18 row_newbcast:9 row_mask:0xf bank_mask:0xf
	v_fmac_f32_dpp v2, v0, v19 row_newbcast:10 row_mask:0xf bank_mask:0xf
	v_fmac_f32_dpp v231, v0, v174 row_newbcast:11 row_mask:0xf bank_mask:0xf
	v_fmac_f32_dpp v210, v0, v175 row_newbcast:12 row_mask:0xf bank_mask:0xf
	v_fmac_f32_dpp v2, v0, v176 row_newbcast:13 row_mask:0xf bank_mask:0xf
	v_fmac_f32_dpp v231, v0, v177 row_newbcast:14 row_mask:0xf bank_mask:0xf
	v_fmac_f32_dpp v210, v0, v178 row_newbcast:15 row_mask:0xf bank_mask:0xf
	v_fmac_f32_dpp v2, v1, v179 row_newbcast:0 row_mask:0xf bank_mask:0xf
	v_fmac_f32_dpp v231, v1, v180 row_newbcast:1 row_mask:0xf bank_mask:0xf
	v_fmac_f32_dpp v210, v1, v181 row_newbcast:2 row_mask:0xf bank_mask:0xf
	v_fmac_f32_dpp v2, v1, v182 row_newbcast:3 row_mask:0xf bank_mask:0xf
	v_fmac_f32_dpp v231, v1, v183 row_newbcast:4 row_mask:0xf bank_mask:0xf
	v_fmac_f32_dpp v210, v1, v184 row_newbcast:5 row_mask:0xf bank_mask:0xf
	v_fmac_f32_dpp v2, v1, v185 row_newbcast:6 row_mask:0xf bank_mask:0xf
	v_fmac_f32_dpp v231, v1, v186 row_newbcast:7 row_mask:0xf bank_mask:0xf
	v_fmac_f32_dpp v210, v1, v187 row_newbcast:8 row_mask:0xf bank_mask:0xf
	v_fmac_f32_dpp v2, v1, v188 row_newbcast:9 row_mask:0xf bank_mask:0xf
	v_fmac_f32_dpp v231, v1, v189 row_newbcast:10 row_mask:0xf bank_mask:0xf
	v_fmac_f32_dpp v210, v1, v190 row_newbcast:11 row_mask:0xf bank_mask:0xf
	v_fmac_f32_dpp v2, v1, v191 row_newbcast:12 row_mask:0xf bank_mask:0xf
	v_fmac_f32_dpp v231, v1, v192 row_newbcast:13 row_mask:0xf bank_mask:0xf
	v_fmac_f32_dpp v210, v1, v193 row_newbcast:14 row_mask:0xf bank_mask:0xf
	v_fmac_f32_dpp v2, v1, v194 row_newbcast:15 row_mask:0xf bank_mask:0xf
	v_fmac_f32_dpp v231, v6, v195 row_newbcast:0 row_mask:0xf bank_mask:0xf
	v_fmac_f32_dpp v210, v6, v196 row_newbcast:1 row_mask:0xf bank_mask:0xf
	v_fmac_f32_dpp v2, v6, v197 row_newbcast:2 row_mask:0xf bank_mask:0xf
	v_fmac_f32_dpp v231, v6, v198 row_newbcast:3 row_mask:0xf bank_mask:0xf
	v_fmac_f32_dpp v210, v6, v199 row_newbcast:4 row_mask:0xf bank_mask:0xf
	v_fmac_f32_dpp v2, v6, v200 row_newbcast:5 row_mask:0xf bank_mask:0xf
	v_fmac_f32_dpp v231, v6, v201 row_newbcast:6 row_mask:0xf bank_mask:0xf
	v_fmac_f32_dpp v210, v6, v202 row_newbcast:7 row_mask:0xf bank_mask:0xf
	v_fmac_f32_dpp v2, v6, v203 row_newbcast:8 row_mask:0xf bank_mask:0xf
	v_fmac_f32_dpp v231, v6, v204 row_newbcast:9 row_mask:0xf bank_mask:0xf
	v_fmac_f32_dpp v210, v6, v205 row_newbcast:10 row_mask:0xf bank_mask:0xf
	v_fmac_f32_dpp v2, v6, v206 row_newbcast:11 row_mask:0xf bank_mask:0xf
	v_fmac_f32_dpp v231, v6, v207 row_newbcast:12 row_mask:0xf bank_mask:0xf
	v_fmac_f32_dpp v210, v6, v208 row_newbcast:13 row_mask:0xf bank_mask:0xf
	v_fmac_f32_dpp v2, v6, v209 row_newbcast:14 row_mask:0xf bank_mask:0xf
	s_nop 0
	v_add_f32_e32 v210, v2, v210
	v_add_f32_e32 v210, v210, v231
	v_mov_b32_e32 v0, v16
	ds_read2_b32 v[6:7], v213 offset0:64 offset1:80
	ds_read2_b32 v[2:3], v213 offset0:96 offset1:112
	ds_read_b32 v214, v154 offset:25872
	s_waitcnt lgkmcnt(3)
; template <int J> __device__ __forceinline__ void macb(float& s, int Lq, float x) { asm volatile("v_fmac_f32_dpp %0, %1, %2 row_newbcast:%3 row_mask:0xf bank_mask:0xf" : "+v"(s) : "v"(Lq), "v"(x), "n"(J)); }
	v_mov_b32_e32 v231, v16
	v_fmac_f32_dpp v212, v4, v8 row_newbcast:0 row_mask:0xf bank_mask:0xf
	v_fmac_f32_dpp v0, v4, v9 row_newbcast:1 row_mask:0xf bank_mask:0xf
	v_fmac_f32_dpp v231, v4, v10 row_newbcast:2 row_mask:0xf bank_mask:0xf
	v_fmac_f32_dpp v212, v4, v11 row_newbcast:3 row_mask:0xf bank_mask:0xf
	v_fmac_f32_dpp v0, v4, v12 row_newbcast:4 row_mask:0xf bank_mask:0xf
	v_fmac_f32_dpp v231, v4, v13 row_newbcast:5 row_mask:0xf bank_mask:0xf
	v_fmac_f32_dpp v212, v4, v14 row_newbcast:6 row_mask:0xf bank_mask:0xf
	v_fmac_f32_dpp v0, v4, v15 row_newbcast:7 row_mask:0xf bank_mask:0xf
	v_fmac_f32_dpp v231, v4, v17 row_newbcast:8 row_mask:0xf bank_mask:0xf
	v_fmac_f32_dpp v212, v4, v18 row_newbcast:9 row_mask:0xf bank_mask:0xf
	v_fmac_f32_dpp v0, v4, v19 row_newbcast:10 row_mask:0xf bank_mask:0xf
	v_fmac_f32_dpp v231, v4, v174 row_newbcast:11 row_mask:0xf bank_mask:0xf
	v_fmac_f32_dpp v212, v4, v175 row_newbcast:12 row_mask:0xf bank_mask:0xf
	v_fmac_f32_dpp v0, v4, v176 row_newbcast:13 row_mask:0xf bank_mask:0xf
	v_fmac_f32_dpp v231, v4, v177 row_newbcast:14 row_mask:0xf bank_mask:0xf
	v_fmac_f32_dpp v212, v4, v178 row_newbcast:15 row_mask:0xf bank_mask:0xf
	v_fmac_f32_dpp v0, v5, v179 row_newbcast:0 row_mask:0xf bank_mask:0xf
	v_fmac_f32_dpp v231, v5, v180 row_newbcast:1 row_mask:0xf bank_mask:0xf
	v_fmac_f32_dpp v212, v5, v181 row_newbcast:2 row_mask:0xf bank_mask:0xf
	v_fmac_f32_dpp v0, v5, v182 row_newbcast:3 row_mask:0xf bank_mask:0xf
	v_fmac_f32_dpp v231, v5, v183 row_newbcast:4 row_mask:0xf bank_mask:0xf
	v_fmac_f32_dpp v212, v5, v184 row_newbcast:5 row_mask:0xf bank_mask:0xf
	v_fmac_f32_dpp v0, v5, v185 row_newbcast:6 row_mask:0xf bank_mask:0xf
	v_fmac_f32_dpp v231, v5, v186 row_newbcast:7 row_mask:0xf bank_mask:0xf
	v_fmac_f32_dpp v212, v5, v187 row_newbcast:8 row_mask:0xf bank_mask:0xf
	v_fmac_f32_dpp v0, v5, v188 row_newbcast:9 row_mask:0xf bank_mask:0xf
	v_fmac_f32_dpp v231, v5, v189 row_newbcast:10 row_mask:0xf bank_mask:0xf
	v_fmac_f32_dpp v212, v5, v190 row_newbcast:11 row_mask:0xf bank_mask:0xf
	v_fmac_f32_dpp v0, v5, v191 row_newbcast:12 row_mask:0xf bank_mask:0xf
	v_fmac_f32_dpp v231, v5, v192 row_newbcast:13 row_mask:0xf bank_mask:0xf
	v_fmac_f32_dpp v212, v5, v193 row_newbcast:14 row_mask:0xf bank_mask:0xf
	v_fmac_f32_dpp v0, v5, v194 row_newbcast:15 row_mask:0xf bank_mask:0xf
	v_fmac_f32_dpp v231, v211, v195 row_newbcast:0 row_mask:0xf bank_mask:0xf
	v_fmac_f32_dpp v212, v211, v196 row_newbcast:1 row_mask:0xf bank_mask:0xf
	v_fmac_f32_dpp v0, v211, v197 row_newbcast:2 row_mask:0xf bank_mask:0xf
	v_fmac_f32_dpp v231, v211, v198 row_newbcast:3 row_mask:0xf bank_mask:0xf
	v_fmac_f32_dpp v212, v211, v199 row_newbcast:4 row_mask:0xf bank_mask:0xf
	v_fmac_f32_dpp v0, v211, v200 row_newbcast:5 row_mask:0xf bank_mask:0xf
	v_fmac_f32_dpp v231, v211, v201 row_newbcast:6 row_mask:0xf bank_mask:0xf
	v_fmac_f32_dpp v212, v211, v202 row_newbcast:7 row_mask:0xf bank_mask:0xf
	v_fmac_f32_dpp v0, v211, v203 row_newbcast:8 row_mask:0xf bank_mask:0xf
	v_fmac_f32_dpp v231, v211, v204 row_newbcast:9 row_mask:0xf bank_mask:0xf
	v_fmac_f32_dpp v212, v211, v205 row_newbcast:10 row_mask:0xf bank_mask:0xf
	v_fmac_f32_dpp v0, v211, v206 row_newbcast:11 row_mask:0xf bank_mask:0xf
	v_fmac_f32_dpp v231, v211, v207 row_newbcast:12 row_mask:0xf bank_mask:0xf
	v_fmac_f32_dpp v212, v211, v208 row_newbcast:13 row_mask:0xf bank_mask:0xf
	v_fmac_f32_dpp v0, v211, v209 row_newbcast:14 row_mask:0xf bank_mask:0xf
	v_fmac_f32_dpp v231, v211, v210 row_newbcast:15 row_mask:0xf bank_mask:0xf
	s_nop 0
	v_add_f32_e32 v211, v212, v0
	v_add_f32_e32 v211, v211, v231
	v_mov_b32_e32 v212, v16
	ds_read2_b32 v[4:5], v213 offset0:128 offset1:144
	ds_read2_b32 v[0:1], v213 offset0:160 offset1:176
	ds_read_b32 v215, v154 offset:26400
	s_waitcnt lgkmcnt(3)
	v_mov_b32_e32 v231, v16
	v_fmac_f32_dpp v214, v6, v8 row_newbcast:0 row_mask:0xf bank_mask:0xf
	v_fmac_f32_dpp v212, v6, v9 row_newbcast:1 row_mask:0xf bank_mask:0xf
	v_fmac_f32_dpp v231, v6, v10 row_newbcast:2 row_mask:0xf bank_mask:0xf
	v_fmac_f32_dpp v214, v6, v11 row_newbcast:3 row_mask:0xf bank_mask:0xf
	v_fmac_f32_dpp v212, v6, v12 row_newbcast:4 row_mask:0xf bank_mask:0xf
	v_fmac_f32_dpp v231, v6, v13 row_newbcast:5 row_mask:0xf bank_mask:0xf
	v_fmac_f32_dpp v214, v6, v14 row_newbcast:6 row_mask:0xf bank_mask:0xf
	v_fmac_f32_dpp v212, v6, v15 row_newbcast:7 row_mask:0xf bank_mask:0xf
	v_fmac_f32_dpp v231, v6, v17 row_newbcast:8 row_mask:0xf bank_mask:0xf
	v_fmac_f32_dpp v214, v6, v18 row_newbcast:9 row_mask:0xf bank_mask:0xf
	v_fmac_f32_dpp v212, v6, v19 row_newbcast:10 row_mask:0xf bank_mask:0xf
	v_fmac_f32_dpp v231, v6, v174 row_newbcast:11 row_mask:0xf bank_mask:0xf
	v_fmac_f32_dpp v214, v6, v175 row_newbcast:12 row_mask:0xf bank_mask:0xf
	v_fmac_f32_dpp v212, v6, v176 row_newbcast:13 row_mask:0xf bank_mask:0xf
	v_fmac_f32_dpp v231, v6, v177 row_newbcast:14 row_mask:0xf bank_mask:0xf
	v_fmac_f32_dpp v214, v6, v178 row_newbcast:15 row_mask:0xf bank_mask:0xf
	v_fmac_f32_dpp v212, v7, v179 row_newbcast:0 row_mask:0xf bank_mask:0xf
	v_fmac_f32_dpp v231, v7, v180 row_newbcast:1 row_mask:0xf bank_mask:0xf
	v_fmac_f32_dpp v214, v7, v181 row_newbcast:2 row_mask:0xf bank_mask:0xf
	v_fmac_f32_dpp v212, v7, v182 row_newbcast:3 row_mask:0xf bank_mask:0xf
	v_fmac_f32_dpp v231, v7, v183 row_newbcast:4 row_mask:0xf bank_mask:0xf
	v_fmac_f32_dpp v214, v7, v184 row_newbcast:5 row_mask:0xf bank_mask:0xf
	v_fmac_f32_dpp v212, v7, v185 row_newbcast:6 row_mask:0xf bank_mask:0xf
	v_fmac_f32_dpp v231, v7, v186 row_newbcast:7 row_mask:0xf bank_mask:0xf
	v_fmac_f32_dpp v214, v7, v187 row_newbcast:8 row_mask:0xf bank_mask:0xf
; template <int J> __device__ __forceinline__ void macb(float& s, int Lq, float x) { asm volatile("v_fmac_f32_dpp %0, %1, %2 row_newbcast:%3 row_mask:0xf bank_mask:0xf" : "+v"(s) : "v"(Lq), "v"(x), "n"(J)); }
	v_fmac_f32_dpp v212, v7, v188 row_newbcast:9 row_mask:0xf bank_mask:0xf
	v_fmac_f32_dpp v231, v7, v189 row_newbcast:10 row_mask:0xf bank_mask:0xf
	v_fmac_f32_dpp v214, v7, v190 row_newbcast:11 row_mask:0xf bank_mask:0xf
	v_fmac_f32_dpp v212, v7, v191 row_newbcast:12 row_mask:0xf bank_mask:0xf
	v_fmac_f32_dpp v231, v7, v192 row_newbcast:13 row_mask:0xf bank_mask:0xf
	v_fmac_f32_dpp v214, v7, v193 row_newbcast:14 row_mask:0xf bank_mask:0xf
	v_fmac_f32_dpp v212, v7, v194 row_newbcast:15 row_mask:0xf bank_mask:0xf
	v_fmac_f32_dpp v231, v2, v195 row_newbcast:0 row_mask:0xf bank_mask:0xf
	v_fmac_f32_dpp v214, v2, v196 row_newbcast:1 row_mask:0xf bank_mask:0xf
	v_fmac_f32_dpp v212, v2, v197 row_newbcast:2 row_mask:0xf bank_mask:0xf
	v_fmac_f32_dpp v231, v2, v198 row_newbcast:3 row_mask:0xf bank_mask:0xf
	v_fmac_f32_dpp v214, v2, v199 row_newbcast:4 row_mask:0xf bank_mask:0xf
	v_fmac_f32_dpp v212, v2, v200 row_newbcast:5 row_mask:0xf bank_mask:0xf
	v_fmac_f32_dpp v231, v2, v201 row_newbcast:6 row_mask:0xf bank_mask:0xf
	v_fmac_f32_dpp v214, v2, v202 row_newbcast:7 row_mask:0xf bank_mask:0xf
	v_fmac_f32_dpp v212, v2, v203 row_newbcast:8 row_mask:0xf bank_mask:0xf
	v_fmac_f32_dpp v231, v2, v204 row_newbcast:9 row_mask:0xf bank_mask:0xf
	v_fmac_f32_dpp v214, v2, v205 row_newbcast:10 row_mask:0xf bank_mask:0xf
	v_fmac_f32_dpp v212, v2, v206 row_newbcast:11 row_mask:0xf bank_mask:0xf
	v_fmac_f32_dpp v231, v2, v207 row_newbcast:12 row_mask:0xf bank_mask:0xf
	v_fmac_f32_dpp v214, v2, v208 row_newbcast:13 row_mask:0xf bank_mask:0xf
	v_fmac_f32_dpp v212, v2, v209 row_newbcast:14 row_mask:0xf bank_mask:0xf
	v_fmac_f32_dpp v231, v2, v210 row_newbcast:15 row_mask:0xf bank_mask:0xf
	v_fmac_f32_dpp v214, v3, v211 row_newbcast:0 row_mask:0xf bank_mask:0xf
	s_nop 0
	v_add_f32_e32 v212, v212, v214
	v_add_f32_e32 v212, v212, v231
	ds_read2_b32 v[6:7], v213 offset0:192 offset1:208
	ds_read2_b32 v[2:3], v213 offset0:224 offset1:240
	ds_read_b32 v214, v154 offset:26928
	v_mov_b32_e32 v213, v16
	s_waitcnt lgkmcnt(3)
	v_mov_b32_e32 v231, v16
	v_fmac_f32_dpp v215, v4, v8 row_newbcast:0 row_mask:0xf bank_mask:0xf
	v_fmac_f32_dpp v213, v4, v9 row_newbcast:1 row_mask:0xf bank_mask:0xf
	v_fmac_f32_dpp v231, v4, v10 row_newbcast:2 row_mask:0xf bank_mask:0xf
	v_fmac_f32_dpp v215, v4, v11 row_newbcast:3 row_mask:0xf bank_mask:0xf
	v_fmac_f32_dpp v213, v4, v12 row_newbcast:4 row_mask:0xf bank_mask:0xf
	v_fmac_f32_dpp v231, v4, v13 row_newbcast:5 row_mask:0xf bank_mask:0xf
	v_fmac_f32_dpp v215, v4, v14 row_newbcast:6 row_mask:0xf bank_mask:0xf
	v_fmac_f32_dpp v213, v4, v15 row_newbcast:7 row_mask:0xf bank_mask:0xf
	v_fmac_f32_dpp v231, v4, v17 row_newbcast:8 row_mask:0xf bank_mask:0xf
	v_fmac_f32_dpp v215, v4, v18 row_newbcast:9 row_mask:0xf bank_mask:0xf
	v_fmac_f32_dpp v213, v4, v19 row_newbcast:10 row_mask:0xf bank_mask:0xf
	v_fmac_f32_dpp v231, v4, v174 row_newbcast:11 row_mask:0xf bank_mask:0xf
	v_fmac_f32_dpp v215, v4, v175 row_newbcast:12 row_mask:0xf bank_mask:0xf
	v_fmac_f32_dpp v213, v4, v176 row_newbcast:13 row_mask:0xf bank_mask:0xf
	v_fmac_f32_dpp v231, v4, v177 row_newbcast:14 row_mask:0xf bank_mask:0xf
	v_fmac_f32_dpp v215, v4, v178 row_newbcast:15 row_mask:0xf bank_mask:0xf
	v_fmac_f32_dpp v213, v5, v179 row_newbcast:0 row_mask:0xf bank_mask:0xf
	v_fmac_f32_dpp v231, v5, v180 row_newbcast:1 row_mask:0xf bank_mask:0xf
	v_fmac_f32_dpp v215, v5, v181 row_newbcast:2 row_mask:0xf bank_mask:0xf
	v_fmac_f32_dpp v213, v5, v182 row_newbcast:3 row_mask:0xf bank_mask:0xf
	v_fmac_f32_dpp v231, v5, v183 row_newbcast:4 row_mask:0xf bank_mask:0xf
	v_fmac_f32_dpp v215, v5, v184 row_newbcast:5 row_mask:0xf bank_mask:0xf
	v_fmac_f32_dpp v213, v5, v185 row_newbcast:6 row_mask:0xf bank_mask:0xf
	v_fmac_f32_dpp v231, v5, v186 row_newbcast:7 row_mask:0xf bank_mask:0xf
	v_fmac_f32_dpp v215, v5, v187 row_newbcast:8 row_mask:0xf bank_mask:0xf
	v_fmac_f32_dpp v213, v5, v188 row_newbcast:9 row_mask:0xf bank_mask:0xf
	v_fmac_f32_dpp v231, v5, v189 row_newbcast:10 row_mask:0xf bank_mask:0xf
	v_fmac_f32_dpp v215, v5, v190 row_newbcast:11 row_mask:0xf bank_mask:0xf
	v_fmac_f32_dpp v213, v5, v191 row_newbcast:12 row_mask:0xf bank_mask:0xf
	v_fmac_f32_dpp v231, v5, v192 row_newbcast:13 row_mask:0xf bank_mask:0xf
	v_fmac_f32_dpp v215, v5, v193 row_newbcast:14 row_mask:0xf bank_mask:0xf
	v_fmac_f32_dpp v213, v5, v194 row_newbcast:15 row_mask:0xf bank_mask:0xf
	v_fmac_f32_dpp v231, v0, v195 row_newbcast:0 row_mask:0xf bank_mask:0xf
	v_fmac_f32_dpp v215, v0, v196 row_newbcast:1 row_mask:0xf bank_mask:0xf
	v_fmac_f32_dpp v213, v0, v197 row_newbcast:2 row_mask:0xf bank_mask:0xf
	v_fmac_f32_dpp v231, v0, v198 row_newbcast:3 row_mask:0xf bank_mask:0xf
	v_fmac_f32_dpp v215, v0, v199 row_newbcast:4 row_mask:0xf bank_mask:0xf
	v_fmac_f32_dpp v213, v0, v200 row_newbcast:5 row_mask:0xf bank_mask:0xf
	v_fmac_f32_dpp v231, v0, v201 row_newbcast:6 row_mask:0xf bank_mask:0xf
	v_fmac_f32_dpp v215, v0, v202 row_newbcast:7 row_mask:0xf bank_mask:0xf
	v_fmac_f32_dpp v213, v0, v203 row_newbcast:8 row_mask:0xf bank_mask:0xf
	v_fmac_f32_dpp v231, v0, v204 row_newbcast:9 row_mask:0xf bank_mask:0xf
	v_fmac_f32_dpp v215, v0, v205 row_newbcast:10 row_mask:0xf bank_mask:0xf
	v_fmac_f32_dpp v213, v0, v206 row_newbcast:11 row_mask:0xf bank_mask:0xf
	v_fmac_f32_dpp v231, v0, v207 row_newbcast:12 row_mask:0xf bank_mask:0xf
	v_fmac_f32_dpp v215, v0, v208 row_newbcast:13 row_mask:0xf bank_mask:0xf
	v_fmac_f32_dpp v213, v0, v209 row_newbcast:14 row_mask:0xf bank_mask:0xf
	v_fmac_f32_dpp v231, v0, v210 row_newbcast:15 row_mask:0xf bank_mask:0xf
	v_fmac_f32_dpp v215, v1, v211 row_newbcast:0 row_mask:0xf bank_mask:0xf
	v_fmac_f32_dpp v213, v1, v212 row_newbcast:1 row_mask:0xf bank_mask:0xf
	s_nop 0
	v_add_f32_e32 v213, v215, v213
	v_add_f32_e32 v213, v213, v231
	v_add_u32_e32 v217, 0x3400, v157
	ds_read2_b32 v[4:5], v217 offset1:16
	ds_read2_b32 v[0:1], v217 offset0:32 offset1:48
	ds_read_b32 v215, v154 offset:27456
	s_waitcnt lgkmcnt(3)
; template <int J> __device__ __forceinline__ void macb(float& s, int Lq, float x) { asm volatile("v_fmac_f32_dpp %0, %1, %2 row_newbcast:%3 row_mask:0xf bank_mask:0xf" : "+v"(s) : "v"(Lq), "v"(x), "n"(J)); }
	v_mov_b32_e32 v231, v16
	v_fmac_f32_dpp v214, v6, v8 row_newbcast:0 row_mask:0xf bank_mask:0xf
	v_mov_b32_e32 v216, v16
	v_fmac_f32_dpp v216, v6, v9 row_newbcast:1 row_mask:0xf bank_mask:0xf
	v_fmac_f32_dpp v231, v6, v10 row_newbcast:2 row_mask:0xf bank_mask:0xf
	v_fmac_f32_dpp v214, v6, v11 row_newbcast:3 row_mask:0xf bank_mask:0xf
	v_fmac_f32_dpp v216, v6, v12 row_newbcast:4 row_mask:0xf bank_mask:0xf
	v_fmac_f32_dpp v231, v6, v13 row_newbcast:5 row_mask:0xf bank_mask:0xf
	v_fmac_f32_dpp v214, v6, v14 row_newbcast:6 row_mask:0xf bank_mask:0xf
	v_fmac_f32_dpp v216, v6, v15 row_newbcast:7 row_mask:0xf bank_mask:0xf
	v_fmac_f32_dpp v231, v6, v17 row_newbcast:8 row_mask:0xf bank_mask:0xf
	v_fmac_f32_dpp v214, v6, v18 row_newbcast:9 row_mask:0xf bank_mask:0xf
	v_fmac_f32_dpp v216, v6, v19 row_newbcast:10 row_mask:0xf bank_mask:0xf
	v_fmac_f32_dpp v231, v6, v174 row_newbcast:11 row_mask:0xf bank_mask:0xf
	v_fmac_f32_dpp v214, v6, v175 row_newbcast:12 row_mask:0xf bank_mask:0xf
	v_fmac_f32_dpp v216, v6, v176 row_newbcast:13 row_mask:0xf bank_mask:0xf
	v_fmac_f32_dpp v231, v6, v177 row_newbcast:14 row_mask:0xf bank_mask:0xf
	v_fmac_f32_dpp v214, v6, v178 row_newbcast:15 row_mask:0xf bank_mask:0xf
	v_fmac_f32_dpp v216, v7, v179 row_newbcast:0 row_mask:0xf bank_mask:0xf
	v_fmac_f32_dpp v231, v7, v180 row_newbcast:1 row_mask:0xf bank_mask:0xf
	v_fmac_f32_dpp v214, v7, v181 row_newbcast:2 row_mask:0xf bank_mask:0xf
	v_fmac_f32_dpp v216, v7, v182 row_newbcast:3 row_mask:0xf bank_mask:0xf
	v_fmac_f32_dpp v231, v7, v183 row_newbcast:4 row_mask:0xf bank_mask:0xf
	v_fmac_f32_dpp v214, v7, v184 row_newbcast:5 row_mask:0xf bank_mask:0xf
	v_fmac_f32_dpp v216, v7, v185 row_newbcast:6 row_mask:0xf bank_mask:0xf
	v_fmac_f32_dpp v231, v7, v186 row_newbcast:7 row_mask:0xf bank_mask:0xf
	v_fmac_f32_dpp v214, v7, v187 row_newbcast:8 row_mask:0xf bank_mask:0xf
	v_fmac_f32_dpp v216, v7, v188 row_newbcast:9 row_mask:0xf bank_mask:0xf
	v_fmac_f32_dpp v231, v7, v189 row_newbcast:10 row_mask:0xf bank_mask:0xf
	v_fmac_f32_dpp v214, v7, v190 row_newbcast:11 row_mask:0xf bank_mask:0xf
	v_fmac_f32_dpp v216, v7, v191 row_newbcast:12 row_mask:0xf bank_mask:0xf
	v_fmac_f32_dpp v231, v7, v192 row_newbcast:13 row_mask:0xf bank_mask:0xf
	v_fmac_f32_dpp v214, v7, v193 row_newbcast:14 row_mask:0xf bank_mask:0xf
	v_fmac_f32_dpp v216, v7, v194 row_newbcast:15 row_mask:0xf bank_mask:0xf
	v_fmac_f32_dpp v231, v2, v195 row_newbcast:0 row_mask:0xf bank_mask:0xf
	v_fmac_f32_dpp v214, v2, v196 row_newbcast:1 row_mask:0xf bank_mask:0xf
	v_fmac_f32_dpp v216, v2, v197 row_newbcast:2 row_mask:0xf bank_mask:0xf
	v_fmac_f32_dpp v231, v2, v198 row_newbcast:3 row_mask:0xf bank_mask:0xf
	v_fmac_f32_dpp v214, v2, v199 row_newbcast:4 row_mask:0xf bank_mask:0xf
	v_fmac_f32_dpp v216, v2, v200 row_newbcast:5 row_mask:0xf bank_mask:0xf
	v_fmac_f32_dpp v231, v2, v201 row_newbcast:6 row_mask:0xf bank_mask:0xf
	v_fmac_f32_dpp v214, v2, v202 row_newbcast:7 row_mask:0xf bank_mask:0xf
	v_fmac_f32_dpp v216, v2, v203 row_newbcast:8 row_mask:0xf bank_mask:0xf
	v_fmac_f32_dpp v231, v2, v204 row_newbcast:9 row_mask:0xf bank_mask:0xf
	v_fmac_f32_dpp v214, v2, v205 row_newbcast:10 row_mask:0xf bank_mask:0xf
	v_fmac_f32_dpp v216, v2, v206 row_newbcast:11 row_mask:0xf bank_mask:0xf
	v_fmac_f32_dpp v231, v2, v207 row_newbcast:12 row_mask:0xf bank_mask:0xf
	v_fmac_f32_dpp v214, v2, v208 row_newbcast:13 row_mask:0xf bank_mask:0xf
	v_fmac_f32_dpp v216, v2, v209 row_newbcast:14 row_mask:0xf bank_mask:0xf
	v_fmac_f32_dpp v231, v2, v210 row_newbcast:15 row_mask:0xf bank_mask:0xf
	v_fmac_f32_dpp v214, v3, v211 row_newbcast:0 row_mask:0xf bank_mask:0xf
	v_fmac_f32_dpp v216, v3, v212 row_newbcast:1 row_mask:0xf bank_mask:0xf
	v_fmac_f32_dpp v231, v3, v213 row_newbcast:2 row_mask:0xf bank_mask:0xf
	s_nop 0
	v_add_f32_e32 v214, v216, v214
	v_add_f32_e32 v214, v214, v231
	ds_read2_b32 v[6:7], v217 offset0:64 offset1:80
	ds_read2_b32 v[2:3], v217 offset0:96 offset1:112
	ds_read_b32 v216, v154 offset:27984
	s_waitcnt lgkmcnt(3)
	v_mov_b32_e32 v231, v16
	v_fmac_f32_dpp v215, v4, v8 row_newbcast:0 row_mask:0xf bank_mask:0xf
	v_mov_b32_e32 v218, v16
	v_fmac_f32_dpp v218, v4, v9 row_newbcast:1 row_mask:0xf bank_mask:0xf
	v_fmac_f32_dpp v231, v4, v10 row_newbcast:2 row_mask:0xf bank_mask:0xf
	v_fmac_f32_dpp v215, v4, v11 row_newbcast:3 row_mask:0xf bank_mask:0xf
	v_fmac_f32_dpp v218, v4, v12 row_newbcast:4 row_mask:0xf bank_mask:0xf
	v_fmac_f32_dpp v231, v4, v13 row_newbcast:5 row_mask:0xf bank_mask:0xf
	v_fmac_f32_dpp v215, v4, v14 row_newbcast:6 row_mask:0xf bank_mask:0xf
	v_fmac_f32_dpp v218, v4, v15 row_newbcast:7 row_mask:0xf bank_mask:0xf
	v_fmac_f32_dpp v231, v4, v17 row_newbcast:8 row_mask:0xf bank_mask:0xf
	v_fmac_f32_dpp v215, v4, v18 row_newbcast:9 row_mask:0xf bank_mask:0xf
	v_fmac_f32_dpp v218, v4, v19 row_newbcast:10 row_mask:0xf bank_mask:0xf
	v_fmac_f32_dpp v231, v4, v174 row_newbcast:11 row_mask:0xf bank_mask:0xf
	v_fmac_f32_dpp v215, v4, v175 row_newbcast:12 row_mask:0xf bank_mask:0xf
	v_fmac_f32_dpp v218, v4, v176 row_newbcast:13 row_mask:0xf bank_mask:0xf
	v_fmac_f32_dpp v231, v4, v177 row_newbcast:14 row_mask:0xf bank_mask:0xf
	v_fmac_f32_dpp v215, v4, v178 row_newbcast:15 row_mask:0xf bank_mask:0xf
	v_fmac_f32_dpp v218, v5, v179 row_newbcast:0 row_mask:0xf bank_mask:0xf
	v_fmac_f32_dpp v231, v5, v180 row_newbcast:1 row_mask:0xf bank_mask:0xf
	v_fmac_f32_dpp v215, v5, v181 row_newbcast:2 row_mask:0xf bank_mask:0xf
	v_fmac_f32_dpp v218, v5, v182 row_newbcast:3 row_mask:0xf bank_mask:0xf
	v_fmac_f32_dpp v231, v5, v183 row_newbcast:4 row_mask:0xf bank_mask:0xf
	v_fmac_f32_dpp v215, v5, v184 row_newbcast:5 row_mask:0xf bank_mask:0xf
; template <int J> __device__ __forceinline__ void macb(float& s, int Lq, float x) { asm volatile("v_fmac_f32_dpp %0, %1, %2 row_newbcast:%3 row_mask:0xf bank_mask:0xf" : "+v"(s) : "v"(Lq), "v"(x), "n"(J)); }
	v_fmac_f32_dpp v218, v5, v185 row_newbcast:6 row_mask:0xf bank_mask:0xf
	v_fmac_f32_dpp v231, v5, v186 row_newbcast:7 row_mask:0xf bank_mask:0xf
	v_fmac_f32_dpp v215, v5, v187 row_newbcast:8 row_mask:0xf bank_mask:0xf
	v_fmac_f32_dpp v218, v5, v188 row_newbcast:9 row_mask:0xf bank_mask:0xf
	v_fmac_f32_dpp v231, v5, v189 row_newbcast:10 row_mask:0xf bank_mask:0xf
	v_fmac_f32_dpp v215, v5, v190 row_newbcast:11 row_mask:0xf bank_mask:0xf
	v_fmac_f32_dpp v218, v5, v191 row_newbcast:12 row_mask:0xf bank_mask:0xf
	v_fmac_f32_dpp v231, v5, v192 row_newbcast:13 row_mask:0xf bank_mask:0xf
	v_fmac_f32_dpp v215, v5, v193 row_newbcast:14 row_mask:0xf bank_mask:0xf
	v_fmac_f32_dpp v218, v5, v194 row_newbcast:15 row_mask:0xf bank_mask:0xf
	v_fmac_f32_dpp v231, v0, v195 row_newbcast:0 row_mask:0xf bank_mask:0xf
	v_fmac_f32_dpp v215, v0, v196 row_newbcast:1 row_mask:0xf bank_mask:0xf
	v_fmac_f32_dpp v218, v0, v197 row_newbcast:2 row_mask:0xf bank_mask:0xf
	v_fmac_f32_dpp v231, v0, v198 row_newbcast:3 row_mask:0xf bank_mask:0xf
	v_fmac_f32_dpp v215, v0, v199 row_newbcast:4 row_mask:0xf bank_mask:0xf
	v_fmac_f32_dpp v218, v0, v200 row_newbcast:5 row_mask:0xf bank_mask:0xf
	v_fmac_f32_dpp v231, v0, v201 row_newbcast:6 row_mask:0xf bank_mask:0xf
	v_fmac_f32_dpp v215, v0, v202 row_newbcast:7 row_mask:0xf bank_mask:0xf
	v_fmac_f32_dpp v218, v0, v203 row_newbcast:8 row_mask:0xf bank_mask:0xf
	v_fmac_f32_dpp v231, v0, v204 row_newbcast:9 row_mask:0xf bank_mask:0xf
	v_fmac_f32_dpp v215, v0, v205 row_newbcast:10 row_mask:0xf bank_mask:0xf
	v_fmac_f32_dpp v218, v0, v206 row_newbcast:11 row_mask:0xf bank_mask:0xf
	v_fmac_f32_dpp v231, v0, v207 row_newbcast:12 row_mask:0xf bank_mask:0xf
	v_fmac_f32_dpp v215, v0, v208 row_newbcast:13 row_mask:0xf bank_mask:0xf
	v_fmac_f32_dpp v218, v0, v209 row_newbcast:14 row_mask:0xf bank_mask:0xf
	v_fmac_f32_dpp v231, v0, v210 row_newbcast:15 row_mask:0xf bank_mask:0xf
	v_fmac_f32_dpp v215, v1, v211 row_newbcast:0 row_mask:0xf bank_mask:0xf
	v_fmac_f32_dpp v218, v1, v212 row_newbcast:1 row_mask:0xf bank_mask:0xf
	v_fmac_f32_dpp v231, v1, v213 row_newbcast:2 row_mask:0xf bank_mask:0xf
	v_fmac_f32_dpp v215, v1, v214 row_newbcast:3 row_mask:0xf bank_mask:0xf
	s_nop 0
	v_add_f32_e32 v215, v215, v218
	v_add_f32_e32 v215, v215, v231
	ds_read2_b32 v[4:5], v217 offset0:128 offset1:144
	ds_read2_b32 v[0:1], v217 offset0:160 offset1:176
	ds_read_b32 v218, v154 offset:28512
	s_waitcnt lgkmcnt(3)
	v_mov_b32_e32 v231, v16
	v_fmac_f32_dpp v216, v6, v8 row_newbcast:0 row_mask:0xf bank_mask:0xf
	v_mov_b32_e32 v219, v16
	v_fmac_f32_dpp v219, v6, v9 row_newbcast:1 row_mask:0xf bank_mask:0xf
	v_fmac_f32_dpp v231, v6, v10 row_newbcast:2 row_mask:0xf bank_mask:0xf
	v_fmac_f32_dpp v216, v6, v11 row_newbcast:3 row_mask:0xf bank_mask:0xf
	v_fmac_f32_dpp v219, v6, v12 row_newbcast:4 row_mask:0xf bank_mask:0xf
	v_fmac_f32_dpp v231, v6, v13 row_newbcast:5 row_mask:0xf bank_mask:0xf
	v_fmac_f32_dpp v216, v6, v14 row_newbcast:6 row_mask:0xf bank_mask:0xf
	v_fmac_f32_dpp v219, v6, v15 row_newbcast:7 row_mask:0xf bank_mask:0xf
	v_fmac_f32_dpp v231, v6, v17 row_newbcast:8 row_mask:0xf bank_mask:0xf
	v_fmac_f32_dpp v216, v6, v18 row_newbcast:9 row_mask:0xf bank_mask:0xf
	v_fmac_f32_dpp v219, v6, v19 row_newbcast:10 row_mask:0xf bank_mask:0xf
	v_fmac_f32_dpp v231, v6, v174 row_newbcast:11 row_mask:0xf bank_mask:0xf
	v_fmac_f32_dpp v216, v6, v175 row_newbcast:12 row_mask:0xf bank_mask:0xf
	v_fmac_f32_dpp v219, v6, v176 row_newbcast:13 row_mask:0xf bank_mask:0xf
	v_fmac_f32_dpp v231, v6, v177 row_newbcast:14 row_mask:0xf bank_mask:0xf
	v_fmac_f32_dpp v216, v6, v178 row_newbcast:15 row_mask:0xf bank_mask:0xf
	v_fmac_f32_dpp v219, v7, v179 row_newbcast:0 row_mask:0xf bank_mask:0xf
	v_fmac_f32_dpp v231, v7, v180 row_newbcast:1 row_mask:0xf bank_mask:0xf
	v_fmac_f32_dpp v216, v7, v181 row_newbcast:2 row_mask:0xf bank_mask:0xf
	v_fmac_f32_dpp v219, v7, v182 row_newbcast:3 row_mask:0xf bank_mask:0xf
	v_fmac_f32_dpp v231, v7, v183 row_newbcast:4 row_mask:0xf bank_mask:0xf
	v_fmac_f32_dpp v216, v7, v184 row_newbcast:5 row_mask:0xf bank_mask:0xf
	v_fmac_f32_dpp v219, v7, v185 row_newbcast:6 row_mask:0xf bank_mask:0xf
	v_fmac_f32_dpp v231, v7, v186 row_newbcast:7 row_mask:0xf bank_mask:0xf
	v_fmac_f32_dpp v216, v7, v187 row_newbcast:8 row_mask:0xf bank_mask:0xf
	v_fmac_f32_dpp v219, v7, v188 row_newbcast:9 row_mask:0xf bank_mask:0xf
	v_fmac_f32_dpp v231, v7, v189 row_newbcast:10 row_mask:0xf bank_mask:0xf
	v_fmac_f32_dpp v216, v7, v190 row_newbcast:11 row_mask:0xf bank_mask:0xf
	v_fmac_f32_dpp v219, v7, v191 row_newbcast:12 row_mask:0xf bank_mask:0xf
	v_fmac_f32_dpp v231, v7, v192 row_newbcast:13 row_mask:0xf bank_mask:0xf
	v_fmac_f32_dpp v216, v7, v193 row_newbcast:14 row_mask:0xf bank_mask:0xf
	v_fmac_f32_dpp v219, v7, v194 row_newbcast:15 row_mask:0xf bank_mask:0xf
	v_fmac_f32_dpp v231, v2, v195 row_newbcast:0 row_mask:0xf bank_mask:0xf
	v_fmac_f32_dpp v216, v2, v196 row_newbcast:1 row_mask:0xf bank_mask:0xf
	v_fmac_f32_dpp v219, v2, v197 row_newbcast:2 row_mask:0xf bank_mask:0xf
	v_fmac_f32_dpp v231, v2, v198 row_newbcast:3 row_mask:0xf bank_mask:0xf
	v_fmac_f32_dpp v216, v2, v199 row_newbcast:4 row_mask:0xf bank_mask:0xf
	v_fmac_f32_dpp v219, v2, v200 row_newbcast:5 row_mask:0xf bank_mask:0xf
	v_fmac_f32_dpp v231, v2, v201 row_newbcast:6 row_mask:0xf bank_mask:0xf
	v_fmac_f32_dpp v216, v2, v202 row_newbcast:7 row_mask:0xf bank_mask:0xf
	v_fmac_f32_dpp v219, v2, v203 row_newbcast:8 row_mask:0xf bank_mask:0xf
	v_fmac_f32_dpp v231, v2, v204 row_newbcast:9 row_mask:0xf bank_mask:0xf
	v_fmac_f32_dpp v216, v2, v205 row_newbcast:10 row_mask:0xf bank_mask:0xf
	v_fmac_f32_dpp v219, v2, v206 row_newbcast:11 row_mask:0xf bank_mask:0xf
	v_fmac_f32_dpp v231, v2, v207 row_newbcast:12 row_mask:0xf bank_mask:0xf
	v_fmac_f32_dpp v216, v2, v208 row_newbcast:13 row_mask:0xf bank_mask:0xf
	v_fmac_f32_dpp v219, v2, v209 row_newbcast:14 row_mask:0xf bank_mask:0xf
	v_fmac_f32_dpp v231, v2, v210 row_newbcast:15 row_mask:0xf bank_mask:0xf
	v_fmac_f32_dpp v216, v3, v211 row_newbcast:0 row_mask:0xf bank_mask:0xf
	v_fmac_f32_dpp v219, v3, v212 row_newbcast:1 row_mask:0xf bank_mask:0xf
	v_fmac_f32_dpp v231, v3, v213 row_newbcast:2 row_mask:0xf bank_mask:0xf
	v_fmac_f32_dpp v216, v3, v214 row_newbcast:3 row_mask:0xf bank_mask:0xf
	v_fmac_f32_dpp v219, v3, v215 row_newbcast:4 row_mask:0xf bank_mask:0xf
	s_nop 0
	v_add_f32_e32 v216, v219, v216
	v_add_f32_e32 v216, v216, v231
	ds_read2_b32 v[6:7], v217 offset0:192 offset1:208
	ds_read2_b32 v[2:3], v217 offset0:224 offset1:240
	ds_read_b32 v219, v154 offset:29040
	v_mov_b32_e32 v217, v16
	s_waitcnt lgkmcnt(3)
; template <int J> __device__ __forceinline__ void macb(float& s, int Lq, float x) { asm volatile("v_fmac_f32_dpp %0, %1, %2 row_newbcast:%3 row_mask:0xf bank_mask:0xf" : "+v"(s) : "v"(Lq), "v"(x), "n"(J)); }
	v_mov_b32_e32 v231, v16
	v_fmac_f32_dpp v218, v4, v8 row_newbcast:0 row_mask:0xf bank_mask:0xf
	v_fmac_f32_dpp v217, v4, v9 row_newbcast:1 row_mask:0xf bank_mask:0xf
	v_fmac_f32_dpp v231, v4, v10 row_newbcast:2 row_mask:0xf bank_mask:0xf
	v_fmac_f32_dpp v218, v4, v11 row_newbcast:3 row_mask:0xf bank_mask:0xf
	v_fmac_f32_dpp v217, v4, v12 row_newbcast:4 row_mask:0xf bank_mask:0xf
	v_fmac_f32_dpp v231, v4, v13 row_newbcast:5 row_mask:0xf bank_mask:0xf
	v_fmac_f32_dpp v218, v4, v14 row_newbcast:6 row_mask:0xf bank_mask:0xf
	v_fmac_f32_dpp v217, v4, v15 row_newbcast:7 row_mask:0xf bank_mask:0xf
	v_fmac_f32_dpp v231, v4, v17 row_newbcast:8 row_mask:0xf bank_mask:0xf
	v_fmac_f32_dpp v218, v4, v18 row_newbcast:9 row_mask:0xf bank_mask:0xf
	v_fmac_f32_dpp v217, v4, v19 row_newbcast:10 row_mask:0xf bank_mask:0xf
	v_fmac_f32_dpp v231, v4, v174 row_newbcast:11 row_mask:0xf bank_mask:0xf
	v_fmac_f32_dpp v218, v4, v175 row_newbcast:12 row_mask:0xf bank_mask:0xf
	v_fmac_f32_dpp v217, v4, v176 row_newbcast:13 row_mask:0xf bank_mask:0xf
	v_fmac_f32_dpp v231, v4, v177 row_newbcast:14 row_mask:0xf bank_mask:0xf
	v_fmac_f32_dpp v218, v4, v178 row_newbcast:15 row_mask:0xf bank_mask:0xf
	v_fmac_f32_dpp v217, v5, v179 row_newbcast:0 row_mask:0xf bank_mask:0xf
	v_fmac_f32_dpp v231, v5, v180 row_newbcast:1 row_mask:0xf bank_mask:0xf
	v_fmac_f32_dpp v218, v5, v181 row_newbcast:2 row_mask:0xf bank_mask:0xf
	v_fmac_f32_dpp v217, v5, v182 row_newbcast:3 row_mask:0xf bank_mask:0xf
	v_fmac_f32_dpp v231, v5, v183 row_newbcast:4 row_mask:0xf bank_mask:0xf
	v_fmac_f32_dpp v218, v5, v184 row_newbcast:5 row_mask:0xf bank_mask:0xf
	v_fmac_f32_dpp v217, v5, v185 row_newbcast:6 row_mask:0xf bank_mask:0xf
	v_fmac_f32_dpp v231, v5, v186 row_newbcast:7 row_mask:0xf bank_mask:0xf
	v_fmac_f32_dpp v218, v5, v187 row_newbcast:8 row_mask:0xf bank_mask:0xf
	v_fmac_f32_dpp v217, v5, v188 row_newbcast:9 row_mask:0xf bank_mask:0xf
	v_fmac_f32_dpp v231, v5, v189 row_newbcast:10 row_mask:0xf bank_mask:0xf
	v_fmac_f32_dpp v218, v5, v190 row_newbcast:11 row_mask:0xf bank_mask:0xf
	v_fmac_f32_dpp v217, v5, v191 row_newbcast:12 row_mask:0xf bank_mask:0xf
	v_fmac_f32_dpp v231, v5, v192 row_newbcast:13 row_mask:0xf bank_mask:0xf
	v_fmac_f32_dpp v218, v5, v193 row_newbcast:14 row_mask:0xf bank_mask:0xf
	v_fmac_f32_dpp v217, v5, v194 row_newbcast:15 row_mask:0xf bank_mask:0xf
	v_fmac_f32_dpp v231, v0, v195 row_newbcast:0 row_mask:0xf bank_mask:0xf
	v_fmac_f32_dpp v218, v0, v196 row_newbcast:1 row_mask:0xf bank_mask:0xf
	v_fmac_f32_dpp v217, v0, v197 row_newbcast:2 row_mask:0xf bank_mask:0xf
	v_fmac_f32_dpp v231, v0, v198 row_newbcast:3 row_mask:0xf bank_mask:0xf
	v_fmac_f32_dpp v218, v0, v199 row_newbcast:4 row_mask:0xf bank_mask:0xf
	v_fmac_f32_dpp v217, v0, v200 row_newbcast:5 row_mask:0xf bank_mask:0xf
	v_fmac_f32_dpp v231, v0, v201 row_newbcast:6 row_mask:0xf bank_mask:0xf
	v_fmac_f32_dpp v218, v0, v202 row_newbcast:7 row_mask:0xf bank_mask:0xf
	v_fmac_f32_dpp v217, v0, v203 row_newbcast:8 row_mask:0xf bank_mask:0xf
	v_fmac_f32_dpp v231, v0, v204 row_newbcast:9 row_mask:0xf bank_mask:0xf
	v_fmac_f32_dpp v218, v0, v205 row_newbcast:10 row_mask:0xf bank_mask:0xf
	v_fmac_f32_dpp v217, v0, v206 row_newbcast:11 row_mask:0xf bank_mask:0xf
	v_fmac_f32_dpp v231, v0, v207 row_newbcast:12 row_mask:0xf bank_mask:0xf
	v_fmac_f32_dpp v218, v0, v208 row_newbcast:13 row_mask:0xf bank_mask:0xf
	v_fmac_f32_dpp v217, v0, v209 row_newbcast:14 row_mask:0xf bank_mask:0xf
	v_fmac_f32_dpp v231, v0, v210 row_newbcast:15 row_mask:0xf bank_mask:0xf
	v_fmac_f32_dpp v218, v1, v211 row_newbcast:0 row_mask:0xf bank_mask:0xf
	v_fmac_f32_dpp v217, v1, v212 row_newbcast:1 row_mask:0xf bank_mask:0xf
	v_fmac_f32_dpp v231, v1, v213 row_newbcast:2 row_mask:0xf bank_mask:0xf
	v_fmac_f32_dpp v218, v1, v214 row_newbcast:3 row_mask:0xf bank_mask:0xf
	v_fmac_f32_dpp v217, v1, v215 row_newbcast:4 row_mask:0xf bank_mask:0xf
	v_fmac_f32_dpp v231, v1, v216 row_newbcast:5 row_mask:0xf bank_mask:0xf
	s_nop 0
	v_add_f32_e32 v217, v218, v217
	v_add_f32_e32 v217, v217, v231
	v_add_u32_e32 v224, 0x3800, v157
	v_mov_b32_e32 v218, v16
	ds_read2_b32 v[4:5], v224 offset1:16
	ds_read2_b32 v[0:1], v224 offset0:32 offset1:48
	ds_read_b32 v221, v154 offset:29568
	s_waitcnt lgkmcnt(3)
; template <int J> __device__ __forceinline__ void macb(float& s, int Lq, float x) { asm volatile("v_fmac_f32_dpp %0, %1, %2 row_newbcast:%3 row_mask:0xf bank_mask:0xf" : "+v"(s) : "v"(Lq), "v"(x), "n"(J)); }
	v_mov_b32_e32 v231, v16
	v_fmac_f32_dpp v219, v6, v8 row_newbcast:0 row_mask:0xf bank_mask:0xf
	v_fmac_f32_dpp v218, v6, v9 row_newbcast:1 row_mask:0xf bank_mask:0xf
	v_fmac_f32_dpp v231, v6, v10 row_newbcast:2 row_mask:0xf bank_mask:0xf
	v_fmac_f32_dpp v219, v6, v11 row_newbcast:3 row_mask:0xf bank_mask:0xf
	v_fmac_f32_dpp v218, v6, v12 row_newbcast:4 row_mask:0xf bank_mask:0xf
	v_fmac_f32_dpp v231, v6, v13 row_newbcast:5 row_mask:0xf bank_mask:0xf
	v_fmac_f32_dpp v219, v6, v14 row_newbcast:6 row_mask:0xf bank_mask:0xf
	v_fmac_f32_dpp v218, v6, v15 row_newbcast:7 row_mask:0xf bank_mask:0xf
	v_fmac_f32_dpp v231, v6, v17 row_newbcast:8 row_mask:0xf bank_mask:0xf
	v_fmac_f32_dpp v219, v6, v18 row_newbcast:9 row_mask:0xf bank_mask:0xf
	v_fmac_f32_dpp v218, v6, v19 row_newbcast:10 row_mask:0xf bank_mask:0xf
	v_fmac_f32_dpp v231, v6, v174 row_newbcast:11 row_mask:0xf bank_mask:0xf
	v_fmac_f32_dpp v219, v6, v175 row_newbcast:12 row_mask:0xf bank_mask:0xf
	v_fmac_f32_dpp v218, v6, v176 row_newbcast:13 row_mask:0xf bank_mask:0xf
	v_fmac_f32_dpp v231, v6, v177 row_newbcast:14 row_mask:0xf bank_mask:0xf
	v_fmac_f32_dpp v219, v6, v178 row_newbcast:15 row_mask:0xf bank_mask:0xf
	v_fmac_f32_dpp v218, v7, v179 row_newbcast:0 row_mask:0xf bank_mask:0xf
	v_fmac_f32_dpp v231, v7, v180 row_newbcast:1 row_mask:0xf bank_mask:0xf
	v_fmac_f32_dpp v219, v7, v181 row_newbcast:2 row_mask:0xf bank_mask:0xf
	v_fmac_f32_dpp v218, v7, v182 row_newbcast:3 row_mask:0xf bank_mask:0xf
	v_fmac_f32_dpp v231, v7, v183 row_newbcast:4 row_mask:0xf bank_mask:0xf
	v_fmac_f32_dpp v219, v7, v184 row_newbcast:5 row_mask:0xf bank_mask:0xf
	v_fmac_f32_dpp v218, v7, v185 row_newbcast:6 row_mask:0xf bank_mask:0xf
	v_fmac_f32_dpp v231, v7, v186 row_newbcast:7 row_mask:0xf bank_mask:0xf
	v_fmac_f32_dpp v219, v7, v187 row_newbcast:8 row_mask:0xf bank_mask:0xf
	v_fmac_f32_dpp v218, v7, v188 row_newbcast:9 row_mask:0xf bank_mask:0xf
	v_fmac_f32_dpp v231, v7, v189 row_newbcast:10 row_mask:0xf bank_mask:0xf
	v_fmac_f32_dpp v219, v7, v190 row_newbcast:11 row_mask:0xf bank_mask:0xf
	v_fmac_f32_dpp v218, v7, v191 row_newbcast:12 row_mask:0xf bank_mask:0xf
	v_fmac_f32_dpp v231, v7, v192 row_newbcast:13 row_mask:0xf bank_mask:0xf
	v_fmac_f32_dpp v219, v7, v193 row_newbcast:14 row_mask:0xf bank_mask:0xf
	v_fmac_f32_dpp v218, v7, v194 row_newbcast:15 row_mask:0xf bank_mask:0xf
	v_fmac_f32_dpp v231, v2, v195 row_newbcast:0 row_mask:0xf bank_mask:0xf
	v_fmac_f32_dpp v219, v2, v196 row_newbcast:1 row_mask:0xf bank_mask:0xf
	v_fmac_f32_dpp v218, v2, v197 row_newbcast:2 row_mask:0xf bank_mask:0xf
	v_fmac_f32_dpp v231, v2, v198 row_newbcast:3 row_mask:0xf bank_mask:0xf
	v_fmac_f32_dpp v219, v2, v199 row_newbcast:4 row_mask:0xf bank_mask:0xf
	v_fmac_f32_dpp v218, v2, v200 row_newbcast:5 row_mask:0xf bank_mask:0xf
	v_fmac_f32_dpp v231, v2, v201 row_newbcast:6 row_mask:0xf bank_mask:0xf
	v_fmac_f32_dpp v219, v2, v202 row_newbcast:7 row_mask:0xf bank_mask:0xf
	v_fmac_f32_dpp v218, v2, v203 row_newbcast:8 row_mask:0xf bank_mask:0xf
	v_fmac_f32_dpp v231, v2, v204 row_newbcast:9 row_mask:0xf bank_mask:0xf
	v_fmac_f32_dpp v219, v2, v205 row_newbcast:10 row_mask:0xf bank_mask:0xf
	v_fmac_f32_dpp v218, v2, v206 row_newbcast:11 row_mask:0xf bank_mask:0xf
	v_fmac_f32_dpp v231, v2, v207 row_newbcast:12 row_mask:0xf bank_mask:0xf
	v_fmac_f32_dpp v219, v2, v208 row_newbcast:13 row_mask:0xf bank_mask:0xf
	v_fmac_f32_dpp v218, v2, v209 row_newbcast:14 row_mask:0xf bank_mask:0xf
	v_fmac_f32_dpp v231, v2, v210 row_newbcast:15 row_mask:0xf bank_mask:0xf
	v_fmac_f32_dpp v219, v3, v211 row_newbcast:0 row_mask:0xf bank_mask:0xf
	v_fmac_f32_dpp v218, v3, v212 row_newbcast:1 row_mask:0xf bank_mask:0xf
	v_fmac_f32_dpp v231, v3, v213 row_newbcast:2 row_mask:0xf bank_mask:0xf
	v_fmac_f32_dpp v219, v3, v214 row_newbcast:3 row_mask:0xf bank_mask:0xf
	v_fmac_f32_dpp v218, v3, v215 row_newbcast:4 row_mask:0xf bank_mask:0xf
	v_fmac_f32_dpp v231, v3, v216 row_newbcast:5 row_mask:0xf bank_mask:0xf
	v_fmac_f32_dpp v219, v3, v217 row_newbcast:6 row_mask:0xf bank_mask:0xf
	s_nop 0
	v_add_f32_e32 v218, v218, v219
	v_add_f32_e32 v218, v218, v231
	v_mov_b32_e32 v219, v16
	ds_read2_b32 v[6:7], v224 offset0:64 offset1:80
	ds_read2_b32 v[2:3], v224 offset0:96 offset1:112
	ds_read_b32 v225, v154 offset:30096
	s_waitcnt lgkmcnt(3)
; template <int J> __device__ __forceinline__ void macb(float& s, int Lq, float x) { asm volatile("v_fmac_f32_dpp %0, %1, %2 row_newbcast:%3 row_mask:0xf bank_mask:0xf" : "+v"(s) : "v"(Lq), "v"(x), "n"(J)); }
	v_mov_b32_e32 v231, v16
	v_fmac_f32_dpp v221, v4, v8 row_newbcast:0 row_mask:0xf bank_mask:0xf
	v_fmac_f32_dpp v219, v4, v9 row_newbcast:1 row_mask:0xf bank_mask:0xf
	v_fmac_f32_dpp v231, v4, v10 row_newbcast:2 row_mask:0xf bank_mask:0xf
	v_fmac_f32_dpp v221, v4, v11 row_newbcast:3 row_mask:0xf bank_mask:0xf
	v_fmac_f32_dpp v219, v4, v12 row_newbcast:4 row_mask:0xf bank_mask:0xf
	v_fmac_f32_dpp v231, v4, v13 row_newbcast:5 row_mask:0xf bank_mask:0xf
	v_fmac_f32_dpp v221, v4, v14 row_newbcast:6 row_mask:0xf bank_mask:0xf
	v_fmac_f32_dpp v219, v4, v15 row_newbcast:7 row_mask:0xf bank_mask:0xf
	v_fmac_f32_dpp v231, v4, v17 row_newbcast:8 row_mask:0xf bank_mask:0xf
	v_fmac_f32_dpp v221, v4, v18 row_newbcast:9 row_mask:0xf bank_mask:0xf
	v_fmac_f32_dpp v219, v4, v19 row_newbcast:10 row_mask:0xf bank_mask:0xf
	v_fmac_f32_dpp v231, v4, v174 row_newbcast:11 row_mask:0xf bank_mask:0xf
	v_fmac_f32_dpp v221, v4, v175 row_newbcast:12 row_mask:0xf bank_mask:0xf
	v_fmac_f32_dpp v219, v4, v176 row_newbcast:13 row_mask:0xf bank_mask:0xf
	v_fmac_f32_dpp v231, v4, v177 row_newbcast:14 row_mask:0xf bank_mask:0xf
	v_fmac_f32_dpp v221, v4, v178 row_newbcast:15 row_mask:0xf bank_mask:0xf
	v_fmac_f32_dpp v219, v5, v179 row_newbcast:0 row_mask:0xf bank_mask:0xf
	v_fmac_f32_dpp v231, v5, v180 row_newbcast:1 row_mask:0xf bank_mask:0xf
	v_fmac_f32_dpp v221, v5, v181 row_newbcast:2 row_mask:0xf bank_mask:0xf
	v_fmac_f32_dpp v219, v5, v182 row_newbcast:3 row_mask:0xf bank_mask:0xf
	v_fmac_f32_dpp v231, v5, v183 row_newbcast:4 row_mask:0xf bank_mask:0xf
	v_fmac_f32_dpp v221, v5, v184 row_newbcast:5 row_mask:0xf bank_mask:0xf
	v_fmac_f32_dpp v219, v5, v185 row_newbcast:6 row_mask:0xf bank_mask:0xf
	v_fmac_f32_dpp v231, v5, v186 row_newbcast:7 row_mask:0xf bank_mask:0xf
	v_fmac_f32_dpp v221, v5, v187 row_newbcast:8 row_mask:0xf bank_mask:0xf
	v_fmac_f32_dpp v219, v5, v188 row_newbcast:9 row_mask:0xf bank_mask:0xf
	v_fmac_f32_dpp v231, v5, v189 row_newbcast:10 row_mask:0xf bank_mask:0xf
	v_fmac_f32_dpp v221, v5, v190 row_newbcast:11 row_mask:0xf bank_mask:0xf
	v_fmac_f32_dpp v219, v5, v191 row_newbcast:12 row_mask:0xf bank_mask:0xf
	v_fmac_f32_dpp v231, v5, v192 row_newbcast:13 row_mask:0xf bank_mask:0xf
	v_fmac_f32_dpp v221, v5, v193 row_newbcast:14 row_mask:0xf bank_mask:0xf
	v_fmac_f32_dpp v219, v5, v194 row_newbcast:15 row_mask:0xf bank_mask:0xf
	v_fmac_f32_dpp v231, v0, v195 row_newbcast:0 row_mask:0xf bank_mask:0xf
	v_fmac_f32_dpp v221, v0, v196 row_newbcast:1 row_mask:0xf bank_mask:0xf
	v_fmac_f32_dpp v219, v0, v197 row_newbcast:2 row_mask:0xf bank_mask:0xf
	v_fmac_f32_dpp v231, v0, v198 row_newbcast:3 row_mask:0xf bank_mask:0xf
	v_fmac_f32_dpp v221, v0, v199 row_newbcast:4 row_mask:0xf bank_mask:0xf
	v_fmac_f32_dpp v219, v0, v200 row_newbcast:5 row_mask:0xf bank_mask:0xf
	v_fmac_f32_dpp v231, v0, v201 row_newbcast:6 row_mask:0xf bank_mask:0xf
	v_fmac_f32_dpp v221, v0, v202 row_newbcast:7 row_mask:0xf bank_mask:0xf
	v_fmac_f32_dpp v219, v0, v203 row_newbcast:8 row_mask:0xf bank_mask:0xf
	v_fmac_f32_dpp v231, v0, v204 row_newbcast:9 row_mask:0xf bank_mask:0xf
	v_fmac_f32_dpp v221, v0, v205 row_newbcast:10 row_mask:0xf bank_mask:0xf
	v_fmac_f32_dpp v219, v0, v206 row_newbcast:11 row_mask:0xf bank_mask:0xf
	v_fmac_f32_dpp v231, v0, v207 row_newbcast:12 row_mask:0xf bank_mask:0xf
	v_fmac_f32_dpp v221, v0, v208 row_newbcast:13 row_mask:0xf bank_mask:0xf
	v_fmac_f32_dpp v219, v0, v209 row_newbcast:14 row_mask:0xf bank_mask:0xf
	v_fmac_f32_dpp v231, v0, v210 row_newbcast:15 row_mask:0xf bank_mask:0xf
	v_fmac_f32_dpp v221, v1, v211 row_newbcast:0 row_mask:0xf bank_mask:0xf
	v_fmac_f32_dpp v219, v1, v212 row_newbcast:1 row_mask:0xf bank_mask:0xf
	v_fmac_f32_dpp v231, v1, v213 row_newbcast:2 row_mask:0xf bank_mask:0xf
	v_fmac_f32_dpp v221, v1, v214 row_newbcast:3 row_mask:0xf bank_mask:0xf
	v_fmac_f32_dpp v219, v1, v215 row_newbcast:4 row_mask:0xf bank_mask:0xf
	v_fmac_f32_dpp v231, v1, v216 row_newbcast:5 row_mask:0xf bank_mask:0xf
	v_fmac_f32_dpp v221, v1, v217 row_newbcast:6 row_mask:0xf bank_mask:0xf
	v_fmac_f32_dpp v219, v1, v218 row_newbcast:7 row_mask:0xf bank_mask:0xf
	s_nop 0
	v_add_f32_e32 v219, v221, v219
	v_add_f32_e32 v219, v219, v231
	v_mov_b32_e32 v221, v16
	ds_read2_b32 v[4:5], v224 offset0:128 offset1:144
	ds_read2_b32 v[0:1], v224 offset0:160 offset1:176
	ds_read_b32 v226, v154 offset:30624
	s_waitcnt lgkmcnt(3)
; template <int J> __device__ __forceinline__ void macb(float& s, int Lq, float x) { asm volatile("v_fmac_f32_dpp %0, %1, %2 row_newbcast:%3 row_mask:0xf bank_mask:0xf" : "+v"(s) : "v"(Lq), "v"(x), "n"(J)); }
	v_mov_b32_e32 v231, v16
	v_fmac_f32_dpp v225, v6, v8 row_newbcast:0 row_mask:0xf bank_mask:0xf
	v_fmac_f32_dpp v221, v6, v9 row_newbcast:1 row_mask:0xf bank_mask:0xf
	v_fmac_f32_dpp v231, v6, v10 row_newbcast:2 row_mask:0xf bank_mask:0xf
	v_fmac_f32_dpp v225, v6, v11 row_newbcast:3 row_mask:0xf bank_mask:0xf
	v_fmac_f32_dpp v221, v6, v12 row_newbcast:4 row_mask:0xf bank_mask:0xf
	v_fmac_f32_dpp v231, v6, v13 row_newbcast:5 row_mask:0xf bank_mask:0xf
	v_fmac_f32_dpp v225, v6, v14 row_newbcast:6 row_mask:0xf bank_mask:0xf
	v_fmac_f32_dpp v221, v6, v15 row_newbcast:7 row_mask:0xf bank_mask:0xf
	v_fmac_f32_dpp v231, v6, v17 row_newbcast:8 row_mask:0xf bank_mask:0xf
	v_fmac_f32_dpp v225, v6, v18 row_newbcast:9 row_mask:0xf bank_mask:0xf
	v_fmac_f32_dpp v221, v6, v19 row_newbcast:10 row_mask:0xf bank_mask:0xf
	v_fmac_f32_dpp v231, v6, v174 row_newbcast:11 row_mask:0xf bank_mask:0xf
	v_fmac_f32_dpp v225, v6, v175 row_newbcast:12 row_mask:0xf bank_mask:0xf
	v_fmac_f32_dpp v221, v6, v176 row_newbcast:13 row_mask:0xf bank_mask:0xf
	v_fmac_f32_dpp v231, v6, v177 row_newbcast:14 row_mask:0xf bank_mask:0xf
	v_fmac_f32_dpp v225, v6, v178 row_newbcast:15 row_mask:0xf bank_mask:0xf
	v_fmac_f32_dpp v221, v7, v179 row_newbcast:0 row_mask:0xf bank_mask:0xf
	v_fmac_f32_dpp v231, v7, v180 row_newbcast:1 row_mask:0xf bank_mask:0xf
	v_fmac_f32_dpp v225, v7, v181 row_newbcast:2 row_mask:0xf bank_mask:0xf
	v_fmac_f32_dpp v221, v7, v182 row_newbcast:3 row_mask:0xf bank_mask:0xf
	v_fmac_f32_dpp v231, v7, v183 row_newbcast:4 row_mask:0xf bank_mask:0xf
	v_fmac_f32_dpp v225, v7, v184 row_newbcast:5 row_mask:0xf bank_mask:0xf
	v_fmac_f32_dpp v221, v7, v185 row_newbcast:6 row_mask:0xf bank_mask:0xf
	v_fmac_f32_dpp v231, v7, v186 row_newbcast:7 row_mask:0xf bank_mask:0xf
	v_fmac_f32_dpp v225, v7, v187 row_newbcast:8 row_mask:0xf bank_mask:0xf
	v_fmac_f32_dpp v221, v7, v188 row_newbcast:9 row_mask:0xf bank_mask:0xf
	v_fmac_f32_dpp v231, v7, v189 row_newbcast:10 row_mask:0xf bank_mask:0xf
	v_fmac_f32_dpp v225, v7, v190 row_newbcast:11 row_mask:0xf bank_mask:0xf
	v_fmac_f32_dpp v221, v7, v191 row_newbcast:12 row_mask:0xf bank_mask:0xf
	v_fmac_f32_dpp v231, v7, v192 row_newbcast:13 row_mask:0xf bank_mask:0xf
	v_fmac_f32_dpp v225, v7, v193 row_newbcast:14 row_mask:0xf bank_mask:0xf
	v_fmac_f32_dpp v221, v7, v194 row_newbcast:15 row_mask:0xf bank_mask:0xf
	v_fmac_f32_dpp v231, v2, v195 row_newbcast:0 row_mask:0xf bank_mask:0xf
	v_fmac_f32_dpp v225, v2, v196 row_newbcast:1 row_mask:0xf bank_mask:0xf
	v_fmac_f32_dpp v221, v2, v197 row_newbcast:2 row_mask:0xf bank_mask:0xf
	v_fmac_f32_dpp v231, v2, v198 row_newbcast:3 row_mask:0xf bank_mask:0xf
	v_fmac_f32_dpp v225, v2, v199 row_newbcast:4 row_mask:0xf bank_mask:0xf
	v_fmac_f32_dpp v221, v2, v200 row_newbcast:5 row_mask:0xf bank_mask:0xf
	v_fmac_f32_dpp v231, v2, v201 row_newbcast:6 row_mask:0xf bank_mask:0xf
	v_fmac_f32_dpp v225, v2, v202 row_newbcast:7 row_mask:0xf bank_mask:0xf
	v_fmac_f32_dpp v221, v2, v203 row_newbcast:8 row_mask:0xf bank_mask:0xf
	v_fmac_f32_dpp v231, v2, v204 row_newbcast:9 row_mask:0xf bank_mask:0xf
	v_fmac_f32_dpp v225, v2, v205 row_newbcast:10 row_mask:0xf bank_mask:0xf
	v_fmac_f32_dpp v221, v2, v206 row_newbcast:11 row_mask:0xf bank_mask:0xf
	v_fmac_f32_dpp v231, v2, v207 row_newbcast:12 row_mask:0xf bank_mask:0xf
	v_fmac_f32_dpp v225, v2, v208 row_newbcast:13 row_mask:0xf bank_mask:0xf
	v_fmac_f32_dpp v221, v2, v209 row_newbcast:14 row_mask:0xf bank_mask:0xf
	v_fmac_f32_dpp v231, v2, v210 row_newbcast:15 row_mask:0xf bank_mask:0xf
	v_fmac_f32_dpp v225, v3, v211 row_newbcast:0 row_mask:0xf bank_mask:0xf
	v_fmac_f32_dpp v221, v3, v212 row_newbcast:1 row_mask:0xf bank_mask:0xf
	v_fmac_f32_dpp v231, v3, v213 row_newbcast:2 row_mask:0xf bank_mask:0xf
	v_fmac_f32_dpp v225, v3, v214 row_newbcast:3 row_mask:0xf bank_mask:0xf
	v_fmac_f32_dpp v221, v3, v215 row_newbcast:4 row_mask:0xf bank_mask:0xf
	v_fmac_f32_dpp v231, v3, v216 row_newbcast:5 row_mask:0xf bank_mask:0xf
	v_fmac_f32_dpp v225, v3, v217 row_newbcast:6 row_mask:0xf bank_mask:0xf
	v_fmac_f32_dpp v221, v3, v218 row_newbcast:7 row_mask:0xf bank_mask:0xf
	v_fmac_f32_dpp v231, v3, v219 row_newbcast:8 row_mask:0xf bank_mask:0xf
	s_nop 0
	v_add_f32_e32 v221, v221, v225
	v_add_f32_e32 v221, v221, v231
	ds_read2_b32 v[6:7], v224 offset0:192 offset1:208
	ds_read2_b32 v[2:3], v224 offset0:224 offset1:240
	ds_read_b32 v225, v154 offset:31152
	v_mov_b32_e32 v224, v16
	s_waitcnt lgkmcnt(3)
; template <int J> __device__ __forceinline__ void macb(float& s, int Lq, float x) { asm volatile("v_fmac_f32_dpp %0, %1, %2 row_newbcast:%3 row_mask:0xf bank_mask:0xf" : "+v"(s) : "v"(Lq), "v"(x), "n"(J)); }
	v_mov_b32_e32 v231, v16
	v_fmac_f32_dpp v226, v4, v8 row_newbcast:0 row_mask:0xf bank_mask:0xf
	v_fmac_f32_dpp v224, v4, v9 row_newbcast:1 row_mask:0xf bank_mask:0xf
	v_fmac_f32_dpp v231, v4, v10 row_newbcast:2 row_mask:0xf bank_mask:0xf
	v_fmac_f32_dpp v226, v4, v11 row_newbcast:3 row_mask:0xf bank_mask:0xf
	v_fmac_f32_dpp v224, v4, v12 row_newbcast:4 row_mask:0xf bank_mask:0xf
	v_fmac_f32_dpp v231, v4, v13 row_newbcast:5 row_mask:0xf bank_mask:0xf
	v_fmac_f32_dpp v226, v4, v14 row_newbcast:6 row_mask:0xf bank_mask:0xf
	v_fmac_f32_dpp v224, v4, v15 row_newbcast:7 row_mask:0xf bank_mask:0xf
	v_fmac_f32_dpp v231, v4, v17 row_newbcast:8 row_mask:0xf bank_mask:0xf
	v_fmac_f32_dpp v226, v4, v18 row_newbcast:9 row_mask:0xf bank_mask:0xf
	v_fmac_f32_dpp v224, v4, v19 row_newbcast:10 row_mask:0xf bank_mask:0xf
	v_fmac_f32_dpp v231, v4, v174 row_newbcast:11 row_mask:0xf bank_mask:0xf
	v_fmac_f32_dpp v226, v4, v175 row_newbcast:12 row_mask:0xf bank_mask:0xf
	v_fmac_f32_dpp v224, v4, v176 row_newbcast:13 row_mask:0xf bank_mask:0xf
	v_fmac_f32_dpp v231, v4, v177 row_newbcast:14 row_mask:0xf bank_mask:0xf
	v_fmac_f32_dpp v226, v4, v178 row_newbcast:15 row_mask:0xf bank_mask:0xf
	v_fmac_f32_dpp v224, v5, v179 row_newbcast:0 row_mask:0xf bank_mask:0xf
	v_fmac_f32_dpp v231, v5, v180 row_newbcast:1 row_mask:0xf bank_mask:0xf
	v_fmac_f32_dpp v226, v5, v181 row_newbcast:2 row_mask:0xf bank_mask:0xf
	v_fmac_f32_dpp v224, v5, v182 row_newbcast:3 row_mask:0xf bank_mask:0xf
	v_fmac_f32_dpp v231, v5, v183 row_newbcast:4 row_mask:0xf bank_mask:0xf
	v_fmac_f32_dpp v226, v5, v184 row_newbcast:5 row_mask:0xf bank_mask:0xf
	v_fmac_f32_dpp v224, v5, v185 row_newbcast:6 row_mask:0xf bank_mask:0xf
	v_fmac_f32_dpp v231, v5, v186 row_newbcast:7 row_mask:0xf bank_mask:0xf
	v_fmac_f32_dpp v226, v5, v187 row_newbcast:8 row_mask:0xf bank_mask:0xf
	v_fmac_f32_dpp v224, v5, v188 row_newbcast:9 row_mask:0xf bank_mask:0xf
	v_fmac_f32_dpp v231, v5, v189 row_newbcast:10 row_mask:0xf bank_mask:0xf
	v_fmac_f32_dpp v226, v5, v190 row_newbcast:11 row_mask:0xf bank_mask:0xf
	v_fmac_f32_dpp v224, v5, v191 row_newbcast:12 row_mask:0xf bank_mask:0xf
	v_fmac_f32_dpp v231, v5, v192 row_newbcast:13 row_mask:0xf bank_mask:0xf
	v_fmac_f32_dpp v226, v5, v193 row_newbcast:14 row_mask:0xf bank_mask:0xf
	v_fmac_f32_dpp v224, v5, v194 row_newbcast:15 row_mask:0xf bank_mask:0xf
	v_fmac_f32_dpp v231, v0, v195 row_newbcast:0 row_mask:0xf bank_mask:0xf
	v_fmac_f32_dpp v226, v0, v196 row_newbcast:1 row_mask:0xf bank_mask:0xf
	v_fmac_f32_dpp v224, v0, v197 row_newbcast:2 row_mask:0xf bank_mask:0xf
	v_fmac_f32_dpp v231, v0, v198 row_newbcast:3 row_mask:0xf bank_mask:0xf
	v_fmac_f32_dpp v226, v0, v199 row_newbcast:4 row_mask:0xf bank_mask:0xf
	v_fmac_f32_dpp v224, v0, v200 row_newbcast:5 row_mask:0xf bank_mask:0xf
	v_fmac_f32_dpp v231, v0, v201 row_newbcast:6 row_mask:0xf bank_mask:0xf
	v_fmac_f32_dpp v226, v0, v202 row_newbcast:7 row_mask:0xf bank_mask:0xf
	v_fmac_f32_dpp v224, v0, v203 row_newbcast:8 row_mask:0xf bank_mask:0xf
	v_fmac_f32_dpp v231, v0, v204 row_newbcast:9 row_mask:0xf bank_mask:0xf
	v_fmac_f32_dpp v226, v0, v205 row_newbcast:10 row_mask:0xf bank_mask:0xf
	v_fmac_f32_dpp v224, v0, v206 row_newbcast:11 row_mask:0xf bank_mask:0xf
	v_fmac_f32_dpp v231, v0, v207 row_newbcast:12 row_mask:0xf bank_mask:0xf
	v_fmac_f32_dpp v226, v0, v208 row_newbcast:13 row_mask:0xf bank_mask:0xf
	v_fmac_f32_dpp v224, v0, v209 row_newbcast:14 row_mask:0xf bank_mask:0xf
	v_fmac_f32_dpp v231, v0, v210 row_newbcast:15 row_mask:0xf bank_mask:0xf
	v_fmac_f32_dpp v226, v1, v211 row_newbcast:0 row_mask:0xf bank_mask:0xf
	v_fmac_f32_dpp v224, v1, v212 row_newbcast:1 row_mask:0xf bank_mask:0xf
	v_fmac_f32_dpp v231, v1, v213 row_newbcast:2 row_mask:0xf bank_mask:0xf
	v_fmac_f32_dpp v226, v1, v214 row_newbcast:3 row_mask:0xf bank_mask:0xf
	v_fmac_f32_dpp v224, v1, v215 row_newbcast:4 row_mask:0xf bank_mask:0xf
	v_fmac_f32_dpp v231, v1, v216 row_newbcast:5 row_mask:0xf bank_mask:0xf
	v_fmac_f32_dpp v226, v1, v217 row_newbcast:6 row_mask:0xf bank_mask:0xf
	v_fmac_f32_dpp v224, v1, v218 row_newbcast:7 row_mask:0xf bank_mask:0xf
	v_fmac_f32_dpp v231, v1, v219 row_newbcast:8 row_mask:0xf bank_mask:0xf
	v_fmac_f32_dpp v226, v1, v221 row_newbcast:9 row_mask:0xf bank_mask:0xf
	s_nop 0
	v_add_f32_e32 v224, v226, v224
	v_add_f32_e32 v224, v224, v231
	v_add_u32_e32 v227, 0x3c00, v157
	ds_read2_b32 v[4:5], v227 offset1:16
	ds_read2_b32 v[0:1], v227 offset0:32 offset1:48
	ds_read_b32 v226, v154 offset:31680
	s_waitcnt lgkmcnt(3)
; template <int J> __device__ __forceinline__ void macb(float& s, int Lq, float x) { asm volatile("v_fmac_f32_dpp %0, %1, %2 row_newbcast:%3 row_mask:0xf bank_mask:0xf" : "+v"(s) : "v"(Lq), "v"(x), "n"(J)); }
	v_mov_b32_e32 v231, v16
	v_fmac_f32_dpp v225, v6, v8 row_newbcast:0 row_mask:0xf bank_mask:0xf
	v_mov_b32_e32 v228, v16
	v_fmac_f32_dpp v228, v6, v9 row_newbcast:1 row_mask:0xf bank_mask:0xf
	v_fmac_f32_dpp v231, v6, v10 row_newbcast:2 row_mask:0xf bank_mask:0xf
	v_fmac_f32_dpp v225, v6, v11 row_newbcast:3 row_mask:0xf bank_mask:0xf
	v_fmac_f32_dpp v228, v6, v12 row_newbcast:4 row_mask:0xf bank_mask:0xf
	v_fmac_f32_dpp v231, v6, v13 row_newbcast:5 row_mask:0xf bank_mask:0xf
	v_fmac_f32_dpp v225, v6, v14 row_newbcast:6 row_mask:0xf bank_mask:0xf
	v_fmac_f32_dpp v228, v6, v15 row_newbcast:7 row_mask:0xf bank_mask:0xf
	v_fmac_f32_dpp v231, v6, v17 row_newbcast:8 row_mask:0xf bank_mask:0xf
	v_fmac_f32_dpp v225, v6, v18 row_newbcast:9 row_mask:0xf bank_mask:0xf
	v_fmac_f32_dpp v228, v6, v19 row_newbcast:10 row_mask:0xf bank_mask:0xf
	v_fmac_f32_dpp v231, v6, v174 row_newbcast:11 row_mask:0xf bank_mask:0xf
	v_fmac_f32_dpp v225, v6, v175 row_newbcast:12 row_mask:0xf bank_mask:0xf
	v_fmac_f32_dpp v228, v6, v176 row_newbcast:13 row_mask:0xf bank_mask:0xf
	v_fmac_f32_dpp v231, v6, v177 row_newbcast:14 row_mask:0xf bank_mask:0xf
	v_fmac_f32_dpp v225, v6, v178 row_newbcast:15 row_mask:0xf bank_mask:0xf
	v_fmac_f32_dpp v228, v7, v179 row_newbcast:0 row_mask:0xf bank_mask:0xf
	v_fmac_f32_dpp v231, v7, v180 row_newbcast:1 row_mask:0xf bank_mask:0xf
	v_fmac_f32_dpp v225, v7, v181 row_newbcast:2 row_mask:0xf bank_mask:0xf
	v_fmac_f32_dpp v228, v7, v182 row_newbcast:3 row_mask:0xf bank_mask:0xf
	v_fmac_f32_dpp v231, v7, v183 row_newbcast:4 row_mask:0xf bank_mask:0xf
	v_fmac_f32_dpp v225, v7, v184 row_newbcast:5 row_mask:0xf bank_mask:0xf
	v_fmac_f32_dpp v228, v7, v185 row_newbcast:6 row_mask:0xf bank_mask:0xf
	v_fmac_f32_dpp v231, v7, v186 row_newbcast:7 row_mask:0xf bank_mask:0xf
	v_fmac_f32_dpp v225, v7, v187 row_newbcast:8 row_mask:0xf bank_mask:0xf
	v_fmac_f32_dpp v228, v7, v188 row_newbcast:9 row_mask:0xf bank_mask:0xf
	v_fmac_f32_dpp v231, v7, v189 row_newbcast:10 row_mask:0xf bank_mask:0xf
	v_fmac_f32_dpp v225, v7, v190 row_newbcast:11 row_mask:0xf bank_mask:0xf
	v_fmac_f32_dpp v228, v7, v191 row_newbcast:12 row_mask:0xf bank_mask:0xf
	v_fmac_f32_dpp v231, v7, v192 row_newbcast:13 row_mask:0xf bank_mask:0xf
	v_fmac_f32_dpp v225, v7, v193 row_newbcast:14 row_mask:0xf bank_mask:0xf
	v_fmac_f32_dpp v228, v7, v194 row_newbcast:15 row_mask:0xf bank_mask:0xf
	v_fmac_f32_dpp v231, v2, v195 row_newbcast:0 row_mask:0xf bank_mask:0xf
	v_fmac_f32_dpp v225, v2, v196 row_newbcast:1 row_mask:0xf bank_mask:0xf
	v_fmac_f32_dpp v228, v2, v197 row_newbcast:2 row_mask:0xf bank_mask:0xf
	v_fmac_f32_dpp v231, v2, v198 row_newbcast:3 row_mask:0xf bank_mask:0xf
	v_fmac_f32_dpp v225, v2, v199 row_newbcast:4 row_mask:0xf bank_mask:0xf
	v_fmac_f32_dpp v228, v2, v200 row_newbcast:5 row_mask:0xf bank_mask:0xf
	v_fmac_f32_dpp v231, v2, v201 row_newbcast:6 row_mask:0xf bank_mask:0xf
	v_fmac_f32_dpp v225, v2, v202 row_newbcast:7 row_mask:0xf bank_mask:0xf
	v_fmac_f32_dpp v228, v2, v203 row_newbcast:8 row_mask:0xf bank_mask:0xf
	v_fmac_f32_dpp v231, v2, v204 row_newbcast:9 row_mask:0xf bank_mask:0xf
	v_fmac_f32_dpp v225, v2, v205 row_newbcast:10 row_mask:0xf bank_mask:0xf
	v_fmac_f32_dpp v228, v2, v206 row_newbcast:11 row_mask:0xf bank_mask:0xf
	v_fmac_f32_dpp v231, v2, v207 row_newbcast:12 row_mask:0xf bank_mask:0xf
	v_fmac_f32_dpp v225, v2, v208 row_newbcast:13 row_mask:0xf bank_mask:0xf
	v_fmac_f32_dpp v228, v2, v209 row_newbcast:14 row_mask:0xf bank_mask:0xf
	v_fmac_f32_dpp v231, v2, v210 row_newbcast:15 row_mask:0xf bank_mask:0xf
	v_fmac_f32_dpp v225, v3, v211 row_newbcast:0 row_mask:0xf bank_mask:0xf
	v_fmac_f32_dpp v228, v3, v212 row_newbcast:1 row_mask:0xf bank_mask:0xf
	v_fmac_f32_dpp v231, v3, v213 row_newbcast:2 row_mask:0xf bank_mask:0xf
	v_fmac_f32_dpp v225, v3, v214 row_newbcast:3 row_mask:0xf bank_mask:0xf
	v_fmac_f32_dpp v228, v3, v215 row_newbcast:4 row_mask:0xf bank_mask:0xf
	v_fmac_f32_dpp v231, v3, v216 row_newbcast:5 row_mask:0xf bank_mask:0xf
	v_fmac_f32_dpp v225, v3, v217 row_newbcast:6 row_mask:0xf bank_mask:0xf
	v_fmac_f32_dpp v228, v3, v218 row_newbcast:7 row_mask:0xf bank_mask:0xf
	v_fmac_f32_dpp v231, v3, v219 row_newbcast:8 row_mask:0xf bank_mask:0xf
	v_fmac_f32_dpp v225, v3, v221 row_newbcast:9 row_mask:0xf bank_mask:0xf
	v_fmac_f32_dpp v228, v3, v224 row_newbcast:10 row_mask:0xf bank_mask:0xf
	s_nop 0
	v_add_f32_e32 v225, v228, v225
	v_add_f32_e32 v225, v225, v231
	ds_read2_b32 v[6:7], v227 offset0:64 offset1:80
	ds_read2_b32 v[2:3], v227 offset0:96 offset1:112
	ds_read_b32 v228, v154 offset:32208
	s_waitcnt lgkmcnt(3)
; template <int J> __device__ __forceinline__ void macb(float& s, int Lq, float x) { asm volatile("v_fmac_f32_dpp %0, %1, %2 row_newbcast:%3 row_mask:0xf bank_mask:0xf" : "+v"(s) : "v"(Lq), "v"(x), "n"(J)); }
	v_mov_b32_e32 v231, v16
	v_fmac_f32_dpp v226, v4, v8 row_newbcast:0 row_mask:0xf bank_mask:0xf
	v_mov_b32_e32 v229, v16
	v_fmac_f32_dpp v229, v4, v9 row_newbcast:1 row_mask:0xf bank_mask:0xf
	v_fmac_f32_dpp v231, v4, v10 row_newbcast:2 row_mask:0xf bank_mask:0xf
	v_fmac_f32_dpp v226, v4, v11 row_newbcast:3 row_mask:0xf bank_mask:0xf
	v_fmac_f32_dpp v229, v4, v12 row_newbcast:4 row_mask:0xf bank_mask:0xf
	v_fmac_f32_dpp v231, v4, v13 row_newbcast:5 row_mask:0xf bank_mask:0xf
	v_fmac_f32_dpp v226, v4, v14 row_newbcast:6 row_mask:0xf bank_mask:0xf
	v_fmac_f32_dpp v229, v4, v15 row_newbcast:7 row_mask:0xf bank_mask:0xf
	v_fmac_f32_dpp v231, v4, v17 row_newbcast:8 row_mask:0xf bank_mask:0xf
	v_fmac_f32_dpp v226, v4, v18 row_newbcast:9 row_mask:0xf bank_mask:0xf
	v_fmac_f32_dpp v229, v4, v19 row_newbcast:10 row_mask:0xf bank_mask:0xf
	v_fmac_f32_dpp v231, v4, v174 row_newbcast:11 row_mask:0xf bank_mask:0xf
	v_fmac_f32_dpp v226, v4, v175 row_newbcast:12 row_mask:0xf bank_mask:0xf
	v_fmac_f32_dpp v229, v4, v176 row_newbcast:13 row_mask:0xf bank_mask:0xf
	v_fmac_f32_dpp v231, v4, v177 row_newbcast:14 row_mask:0xf bank_mask:0xf
	v_fmac_f32_dpp v226, v4, v178 row_newbcast:15 row_mask:0xf bank_mask:0xf
	v_fmac_f32_dpp v229, v5, v179 row_newbcast:0 row_mask:0xf bank_mask:0xf
	v_fmac_f32_dpp v231, v5, v180 row_newbcast:1 row_mask:0xf bank_mask:0xf
	v_fmac_f32_dpp v226, v5, v181 row_newbcast:2 row_mask:0xf bank_mask:0xf
	v_fmac_f32_dpp v229, v5, v182 row_newbcast:3 row_mask:0xf bank_mask:0xf
	v_fmac_f32_dpp v231, v5, v183 row_newbcast:4 row_mask:0xf bank_mask:0xf
	v_fmac_f32_dpp v226, v5, v184 row_newbcast:5 row_mask:0xf bank_mask:0xf
	v_fmac_f32_dpp v229, v5, v185 row_newbcast:6 row_mask:0xf bank_mask:0xf
	v_fmac_f32_dpp v231, v5, v186 row_newbcast:7 row_mask:0xf bank_mask:0xf
	v_fmac_f32_dpp v226, v5, v187 row_newbcast:8 row_mask:0xf bank_mask:0xf
	v_fmac_f32_dpp v229, v5, v188 row_newbcast:9 row_mask:0xf bank_mask:0xf
	v_fmac_f32_dpp v231, v5, v189 row_newbcast:10 row_mask:0xf bank_mask:0xf
	v_fmac_f32_dpp v226, v5, v190 row_newbcast:11 row_mask:0xf bank_mask:0xf
	v_fmac_f32_dpp v229, v5, v191 row_newbcast:12 row_mask:0xf bank_mask:0xf
	v_fmac_f32_dpp v231, v5, v192 row_newbcast:13 row_mask:0xf bank_mask:0xf
	v_fmac_f32_dpp v226, v5, v193 row_newbcast:14 row_mask:0xf bank_mask:0xf
	v_fmac_f32_dpp v229, v5, v194 row_newbcast:15 row_mask:0xf bank_mask:0xf
	v_fmac_f32_dpp v231, v0, v195 row_newbcast:0 row_mask:0xf bank_mask:0xf
	v_fmac_f32_dpp v226, v0, v196 row_newbcast:1 row_mask:0xf bank_mask:0xf
	v_fmac_f32_dpp v229, v0, v197 row_newbcast:2 row_mask:0xf bank_mask:0xf
	v_fmac_f32_dpp v231, v0, v198 row_newbcast:3 row_mask:0xf bank_mask:0xf
	v_fmac_f32_dpp v226, v0, v199 row_newbcast:4 row_mask:0xf bank_mask:0xf
	v_fmac_f32_dpp v229, v0, v200 row_newbcast:5 row_mask:0xf bank_mask:0xf
	v_fmac_f32_dpp v231, v0, v201 row_newbcast:6 row_mask:0xf bank_mask:0xf
	v_fmac_f32_dpp v226, v0, v202 row_newbcast:7 row_mask:0xf bank_mask:0xf
	v_fmac_f32_dpp v229, v0, v203 row_newbcast:8 row_mask:0xf bank_mask:0xf
	v_fmac_f32_dpp v231, v0, v204 row_newbcast:9 row_mask:0xf bank_mask:0xf
	v_fmac_f32_dpp v226, v0, v205 row_newbcast:10 row_mask:0xf bank_mask:0xf
	v_fmac_f32_dpp v229, v0, v206 row_newbcast:11 row_mask:0xf bank_mask:0xf
	v_fmac_f32_dpp v231, v0, v207 row_newbcast:12 row_mask:0xf bank_mask:0xf
	v_fmac_f32_dpp v226, v0, v208 row_newbcast:13 row_mask:0xf bank_mask:0xf
	v_fmac_f32_dpp v229, v0, v209 row_newbcast:14 row_mask:0xf bank_mask:0xf
	v_fmac_f32_dpp v231, v0, v210 row_newbcast:15 row_mask:0xf bank_mask:0xf
	v_fmac_f32_dpp v226, v1, v211 row_newbcast:0 row_mask:0xf bank_mask:0xf
	v_fmac_f32_dpp v229, v1, v212 row_newbcast:1 row_mask:0xf bank_mask:0xf
	v_fmac_f32_dpp v231, v1, v213 row_newbcast:2 row_mask:0xf bank_mask:0xf
	v_fmac_f32_dpp v226, v1, v214 row_newbcast:3 row_mask:0xf bank_mask:0xf
	v_fmac_f32_dpp v229, v1, v215 row_newbcast:4 row_mask:0xf bank_mask:0xf
	v_fmac_f32_dpp v231, v1, v216 row_newbcast:5 row_mask:0xf bank_mask:0xf
	v_fmac_f32_dpp v226, v1, v217 row_newbcast:6 row_mask:0xf bank_mask:0xf
	v_fmac_f32_dpp v229, v1, v218 row_newbcast:7 row_mask:0xf bank_mask:0xf
	v_fmac_f32_dpp v231, v1, v219 row_newbcast:8 row_mask:0xf bank_mask:0xf
	v_fmac_f32_dpp v226, v1, v221 row_newbcast:9 row_mask:0xf bank_mask:0xf
	v_fmac_f32_dpp v229, v1, v224 row_newbcast:10 row_mask:0xf bank_mask:0xf
	v_fmac_f32_dpp v231, v1, v225 row_newbcast:11 row_mask:0xf bank_mask:0xf
	s_nop 0
	v_add_f32_e32 v226, v226, v229
	v_add_f32_e32 v226, v226, v231
	ds_read2_b32 v[4:5], v227 offset0:128 offset1:144
	ds_read2_b32 v[0:1], v227 offset0:160 offset1:176
	ds_read_b32 v229, v154 offset:32736
	s_waitcnt lgkmcnt(3)
; template <int J> __device__ __forceinline__ void macb(float& s, int Lq, float x) { asm volatile("v_fmac_f32_dpp %0, %1, %2 row_newbcast:%3 row_mask:0xf bank_mask:0xf" : "+v"(s) : "v"(Lq), "v"(x), "n"(J)); }
	v_mov_b32_e32 v231, v16
	v_fmac_f32_dpp v228, v6, v8 row_newbcast:0 row_mask:0xf bank_mask:0xf
	v_mov_b32_e32 v230, v16
	v_fmac_f32_dpp v230, v6, v9 row_newbcast:1 row_mask:0xf bank_mask:0xf
	v_fmac_f32_dpp v231, v6, v10 row_newbcast:2 row_mask:0xf bank_mask:0xf
	v_fmac_f32_dpp v228, v6, v11 row_newbcast:3 row_mask:0xf bank_mask:0xf
	v_fmac_f32_dpp v230, v6, v12 row_newbcast:4 row_mask:0xf bank_mask:0xf
	v_fmac_f32_dpp v231, v6, v13 row_newbcast:5 row_mask:0xf bank_mask:0xf
	v_fmac_f32_dpp v228, v6, v14 row_newbcast:6 row_mask:0xf bank_mask:0xf
	v_fmac_f32_dpp v230, v6, v15 row_newbcast:7 row_mask:0xf bank_mask:0xf
	v_fmac_f32_dpp v231, v6, v17 row_newbcast:8 row_mask:0xf bank_mask:0xf
	v_fmac_f32_dpp v228, v6, v18 row_newbcast:9 row_mask:0xf bank_mask:0xf
	v_fmac_f32_dpp v230, v6, v19 row_newbcast:10 row_mask:0xf bank_mask:0xf
	v_fmac_f32_dpp v231, v6, v174 row_newbcast:11 row_mask:0xf bank_mask:0xf
	v_fmac_f32_dpp v228, v6, v175 row_newbcast:12 row_mask:0xf bank_mask:0xf
	v_fmac_f32_dpp v230, v6, v176 row_newbcast:13 row_mask:0xf bank_mask:0xf
	v_fmac_f32_dpp v231, v6, v177 row_newbcast:14 row_mask:0xf bank_mask:0xf
	v_fmac_f32_dpp v228, v6, v178 row_newbcast:15 row_mask:0xf bank_mask:0xf
	v_fmac_f32_dpp v230, v7, v179 row_newbcast:0 row_mask:0xf bank_mask:0xf
	v_fmac_f32_dpp v231, v7, v180 row_newbcast:1 row_mask:0xf bank_mask:0xf
	v_fmac_f32_dpp v228, v7, v181 row_newbcast:2 row_mask:0xf bank_mask:0xf
	v_fmac_f32_dpp v230, v7, v182 row_newbcast:3 row_mask:0xf bank_mask:0xf
	v_fmac_f32_dpp v231, v7, v183 row_newbcast:4 row_mask:0xf bank_mask:0xf
	v_fmac_f32_dpp v228, v7, v184 row_newbcast:5 row_mask:0xf bank_mask:0xf
	v_fmac_f32_dpp v230, v7, v185 row_newbcast:6 row_mask:0xf bank_mask:0xf
	v_fmac_f32_dpp v231, v7, v186 row_newbcast:7 row_mask:0xf bank_mask:0xf
	v_fmac_f32_dpp v228, v7, v187 row_newbcast:8 row_mask:0xf bank_mask:0xf
	v_fmac_f32_dpp v230, v7, v188 row_newbcast:9 row_mask:0xf bank_mask:0xf
	v_fmac_f32_dpp v231, v7, v189 row_newbcast:10 row_mask:0xf bank_mask:0xf
	v_fmac_f32_dpp v228, v7, v190 row_newbcast:11 row_mask:0xf bank_mask:0xf
	v_fmac_f32_dpp v230, v7, v191 row_newbcast:12 row_mask:0xf bank_mask:0xf
	v_fmac_f32_dpp v231, v7, v192 row_newbcast:13 row_mask:0xf bank_mask:0xf
	v_fmac_f32_dpp v228, v7, v193 row_newbcast:14 row_mask:0xf bank_mask:0xf
	v_fmac_f32_dpp v230, v7, v194 row_newbcast:15 row_mask:0xf bank_mask:0xf
	v_fmac_f32_dpp v231, v2, v195 row_newbcast:0 row_mask:0xf bank_mask:0xf
	v_fmac_f32_dpp v228, v2, v196 row_newbcast:1 row_mask:0xf bank_mask:0xf
	v_fmac_f32_dpp v230, v2, v197 row_newbcast:2 row_mask:0xf bank_mask:0xf
	v_fmac_f32_dpp v231, v2, v198 row_newbcast:3 row_mask:0xf bank_mask:0xf
	v_fmac_f32_dpp v228, v2, v199 row_newbcast:4 row_mask:0xf bank_mask:0xf
	v_fmac_f32_dpp v230, v2, v200 row_newbcast:5 row_mask:0xf bank_mask:0xf
	v_fmac_f32_dpp v231, v2, v201 row_newbcast:6 row_mask:0xf bank_mask:0xf
	v_fmac_f32_dpp v228, v2, v202 row_newbcast:7 row_mask:0xf bank_mask:0xf
	v_fmac_f32_dpp v230, v2, v203 row_newbcast:8 row_mask:0xf bank_mask:0xf
	v_fmac_f32_dpp v231, v2, v204 row_newbcast:9 row_mask:0xf bank_mask:0xf
	v_fmac_f32_dpp v228, v2, v205 row_newbcast:10 row_mask:0xf bank_mask:0xf
	v_fmac_f32_dpp v230, v2, v206 row_newbcast:11 row_mask:0xf bank_mask:0xf
	v_fmac_f32_dpp v231, v2, v207 row_newbcast:12 row_mask:0xf bank_mask:0xf
	v_fmac_f32_dpp v228, v2, v208 row_newbcast:13 row_mask:0xf bank_mask:0xf
	v_fmac_f32_dpp v230, v2, v209 row_newbcast:14 row_mask:0xf bank_mask:0xf
	v_fmac_f32_dpp v231, v2, v210 row_newbcast:15 row_mask:0xf bank_mask:0xf
	v_fmac_f32_dpp v228, v3, v211 row_newbcast:0 row_mask:0xf bank_mask:0xf
	v_fmac_f32_dpp v230, v3, v212 row_newbcast:1 row_mask:0xf bank_mask:0xf
	v_fmac_f32_dpp v231, v3, v213 row_newbcast:2 row_mask:0xf bank_mask:0xf
	v_fmac_f32_dpp v228, v3, v214 row_newbcast:3 row_mask:0xf bank_mask:0xf
	v_fmac_f32_dpp v230, v3, v215 row_newbcast:4 row_mask:0xf bank_mask:0xf
	v_fmac_f32_dpp v231, v3, v216 row_newbcast:5 row_mask:0xf bank_mask:0xf
	v_fmac_f32_dpp v228, v3, v217 row_newbcast:6 row_mask:0xf bank_mask:0xf
	v_fmac_f32_dpp v230, v3, v218 row_newbcast:7 row_mask:0xf bank_mask:0xf
	v_fmac_f32_dpp v231, v3, v219 row_newbcast:8 row_mask:0xf bank_mask:0xf
	v_fmac_f32_dpp v228, v3, v221 row_newbcast:9 row_mask:0xf bank_mask:0xf
	v_fmac_f32_dpp v230, v3, v224 row_newbcast:10 row_mask:0xf bank_mask:0xf
	v_fmac_f32_dpp v231, v3, v225 row_newbcast:11 row_mask:0xf bank_mask:0xf
	v_fmac_f32_dpp v228, v3, v226 row_newbcast:12 row_mask:0xf bank_mask:0xf
	s_nop 0
	v_add_f32_e32 v228, v230, v228
	v_add_f32_e32 v228, v228, v231
	v_mov_b32_e32 v230, v16
	ds_read2_b32 v[6:7], v227 offset0:192 offset1:208
	ds_read2_b32 v[2:3], v227 offset0:224 offset1:240
	ds_read_b32 v227, v154 offset:33264
	s_waitcnt lgkmcnt(3)
; template <int J> __device__ __forceinline__ void macb(float& s, int Lq, float x) { asm volatile("v_fmac_f32_dpp %0, %1, %2 row_newbcast:%3 row_mask:0xf bank_mask:0xf" : "+v"(s) : "v"(Lq), "v"(x), "n"(J)); }
	v_mov_b32_e32 v231, v16
	v_fmac_f32_dpp v229, v4, v8 row_newbcast:0 row_mask:0xf bank_mask:0xf
	v_fmac_f32_dpp v230, v4, v9 row_newbcast:1 row_mask:0xf bank_mask:0xf
	v_fmac_f32_dpp v231, v4, v10 row_newbcast:2 row_mask:0xf bank_mask:0xf
	v_fmac_f32_dpp v229, v4, v11 row_newbcast:3 row_mask:0xf bank_mask:0xf
	v_fmac_f32_dpp v230, v4, v12 row_newbcast:4 row_mask:0xf bank_mask:0xf
	v_fmac_f32_dpp v231, v4, v13 row_newbcast:5 row_mask:0xf bank_mask:0xf
	v_fmac_f32_dpp v229, v4, v14 row_newbcast:6 row_mask:0xf bank_mask:0xf
	v_fmac_f32_dpp v230, v4, v15 row_newbcast:7 row_mask:0xf bank_mask:0xf
	v_fmac_f32_dpp v231, v4, v17 row_newbcast:8 row_mask:0xf bank_mask:0xf
	v_fmac_f32_dpp v229, v4, v18 row_newbcast:9 row_mask:0xf bank_mask:0xf
	v_fmac_f32_dpp v230, v4, v19 row_newbcast:10 row_mask:0xf bank_mask:0xf
	v_fmac_f32_dpp v231, v4, v174 row_newbcast:11 row_mask:0xf bank_mask:0xf
	v_fmac_f32_dpp v229, v4, v175 row_newbcast:12 row_mask:0xf bank_mask:0xf
	v_fmac_f32_dpp v230, v4, v176 row_newbcast:13 row_mask:0xf bank_mask:0xf
	v_fmac_f32_dpp v231, v4, v177 row_newbcast:14 row_mask:0xf bank_mask:0xf
	v_fmac_f32_dpp v229, v4, v178 row_newbcast:15 row_mask:0xf bank_mask:0xf
	v_fmac_f32_dpp v230, v5, v179 row_newbcast:0 row_mask:0xf bank_mask:0xf
	v_fmac_f32_dpp v231, v5, v180 row_newbcast:1 row_mask:0xf bank_mask:0xf
	v_fmac_f32_dpp v229, v5, v181 row_newbcast:2 row_mask:0xf bank_mask:0xf
	v_fmac_f32_dpp v230, v5, v182 row_newbcast:3 row_mask:0xf bank_mask:0xf
	v_fmac_f32_dpp v231, v5, v183 row_newbcast:4 row_mask:0xf bank_mask:0xf
	v_fmac_f32_dpp v229, v5, v184 row_newbcast:5 row_mask:0xf bank_mask:0xf
	v_fmac_f32_dpp v230, v5, v185 row_newbcast:6 row_mask:0xf bank_mask:0xf
	v_fmac_f32_dpp v231, v5, v186 row_newbcast:7 row_mask:0xf bank_mask:0xf
	v_fmac_f32_dpp v229, v5, v187 row_newbcast:8 row_mask:0xf bank_mask:0xf
	v_fmac_f32_dpp v230, v5, v188 row_newbcast:9 row_mask:0xf bank_mask:0xf
	v_fmac_f32_dpp v231, v5, v189 row_newbcast:10 row_mask:0xf bank_mask:0xf
	v_fmac_f32_dpp v229, v5, v190 row_newbcast:11 row_mask:0xf bank_mask:0xf
	v_fmac_f32_dpp v230, v5, v191 row_newbcast:12 row_mask:0xf bank_mask:0xf
	v_fmac_f32_dpp v231, v5, v192 row_newbcast:13 row_mask:0xf bank_mask:0xf
	v_fmac_f32_dpp v229, v5, v193 row_newbcast:14 row_mask:0xf bank_mask:0xf
	v_fmac_f32_dpp v230, v5, v194 row_newbcast:15 row_mask:0xf bank_mask:0xf
	v_fmac_f32_dpp v231, v0, v195 row_newbcast:0 row_mask:0xf bank_mask:0xf
	v_fmac_f32_dpp v229, v0, v196 row_newbcast:1 row_mask:0xf bank_mask:0xf
	v_fmac_f32_dpp v230, v0, v197 row_newbcast:2 row_mask:0xf bank_mask:0xf
	v_fmac_f32_dpp v231, v0, v198 row_newbcast:3 row_mask:0xf bank_mask:0xf
	v_fmac_f32_dpp v229, v0, v199 row_newbcast:4 row_mask:0xf bank_mask:0xf
	v_fmac_f32_dpp v230, v0, v200 row_newbcast:5 row_mask:0xf bank_mask:0xf
	v_fmac_f32_dpp v231, v0, v201 row_newbcast:6 row_mask:0xf bank_mask:0xf
	v_fmac_f32_dpp v229, v0, v202 row_newbcast:7 row_mask:0xf bank_mask:0xf
	v_fmac_f32_dpp v230, v0, v203 row_newbcast:8 row_mask:0xf bank_mask:0xf
	v_fmac_f32_dpp v231, v0, v204 row_newbcast:9 row_mask:0xf bank_mask:0xf
	v_fmac_f32_dpp v229, v0, v205 row_newbcast:10 row_mask:0xf bank_mask:0xf
	v_fmac_f32_dpp v230, v0, v206 row_newbcast:11 row_mask:0xf bank_mask:0xf
	v_fmac_f32_dpp v231, v0, v207 row_newbcast:12 row_mask:0xf bank_mask:0xf
	v_fmac_f32_dpp v229, v0, v208 row_newbcast:13 row_mask:0xf bank_mask:0xf
	v_fmac_f32_dpp v230, v0, v209 row_newbcast:14 row_mask:0xf bank_mask:0xf
	v_fmac_f32_dpp v231, v0, v210 row_newbcast:15 row_mask:0xf bank_mask:0xf
	v_fmac_f32_dpp v229, v1, v211 row_newbcast:0 row_mask:0xf bank_mask:0xf
	v_fmac_f32_dpp v230, v1, v212 row_newbcast:1 row_mask:0xf bank_mask:0xf
	v_fmac_f32_dpp v231, v1, v213 row_newbcast:2 row_mask:0xf bank_mask:0xf
	v_fmac_f32_dpp v229, v1, v214 row_newbcast:3 row_mask:0xf bank_mask:0xf
	v_fmac_f32_dpp v230, v1, v215 row_newbcast:4 row_mask:0xf bank_mask:0xf
	v_fmac_f32_dpp v231, v1, v216 row_newbcast:5 row_mask:0xf bank_mask:0xf
	v_fmac_f32_dpp v229, v1, v217 row_newbcast:6 row_mask:0xf bank_mask:0xf
	v_fmac_f32_dpp v230, v1, v218 row_newbcast:7 row_mask:0xf bank_mask:0xf
	v_fmac_f32_dpp v231, v1, v219 row_newbcast:8 row_mask:0xf bank_mask:0xf
	v_fmac_f32_dpp v229, v1, v221 row_newbcast:9 row_mask:0xf bank_mask:0xf
	v_fmac_f32_dpp v230, v1, v224 row_newbcast:10 row_mask:0xf bank_mask:0xf
	v_fmac_f32_dpp v231, v1, v225 row_newbcast:11 row_mask:0xf bank_mask:0xf
	v_fmac_f32_dpp v229, v1, v226 row_newbcast:12 row_mask:0xf bank_mask:0xf
	v_fmac_f32_dpp v230, v1, v228 row_newbcast:13 row_mask:0xf bank_mask:0xf
	s_nop 0
	v_add_f32_e32 v0, v229, v230
	v_add_f32_e32 v0, v0, v231
	v_mov_b32_e32 v1, v16
	s_waitcnt lgkmcnt(0)
; template <int J> __device__ __forceinline__ void macb(float& s, int Lq, float x) { asm volatile("v_fmac_f32_dpp %0, %1, %2 row_newbcast:%3 row_mask:0xf bank_mask:0xf" : "+v"(s) : "v"(Lq), "v"(x), "n"(J)); }
	v_mov_b32_e32 v231, v16
	v_fmac_f32_dpp v227, v6, v8 row_newbcast:0 row_mask:0xf bank_mask:0xf
	v_fmac_f32_dpp v1, v6, v9 row_newbcast:1 row_mask:0xf bank_mask:0xf
	v_fmac_f32_dpp v231, v6, v10 row_newbcast:2 row_mask:0xf bank_mask:0xf
	v_fmac_f32_dpp v227, v6, v11 row_newbcast:3 row_mask:0xf bank_mask:0xf
	v_fmac_f32_dpp v1, v6, v12 row_newbcast:4 row_mask:0xf bank_mask:0xf
	v_fmac_f32_dpp v231, v6, v13 row_newbcast:5 row_mask:0xf bank_mask:0xf
	v_fmac_f32_dpp v227, v6, v14 row_newbcast:6 row_mask:0xf bank_mask:0xf
	v_fmac_f32_dpp v1, v6, v15 row_newbcast:7 row_mask:0xf bank_mask:0xf
	v_fmac_f32_dpp v231, v6, v17 row_newbcast:8 row_mask:0xf bank_mask:0xf
	v_fmac_f32_dpp v227, v6, v18 row_newbcast:9 row_mask:0xf bank_mask:0xf
	v_fmac_f32_dpp v1, v6, v19 row_newbcast:10 row_mask:0xf bank_mask:0xf
	v_fmac_f32_dpp v231, v6, v174 row_newbcast:11 row_mask:0xf bank_mask:0xf
	v_fmac_f32_dpp v227, v6, v175 row_newbcast:12 row_mask:0xf bank_mask:0xf
	v_fmac_f32_dpp v1, v6, v176 row_newbcast:13 row_mask:0xf bank_mask:0xf
	v_fmac_f32_dpp v231, v6, v177 row_newbcast:14 row_mask:0xf bank_mask:0xf
	v_fmac_f32_dpp v227, v6, v178 row_newbcast:15 row_mask:0xf bank_mask:0xf
	v_fmac_f32_dpp v1, v7, v179 row_newbcast:0 row_mask:0xf bank_mask:0xf
	v_fmac_f32_dpp v231, v7, v180 row_newbcast:1 row_mask:0xf bank_mask:0xf
	v_fmac_f32_dpp v227, v7, v181 row_newbcast:2 row_mask:0xf bank_mask:0xf
	v_fmac_f32_dpp v1, v7, v182 row_newbcast:3 row_mask:0xf bank_mask:0xf
	v_fmac_f32_dpp v231, v7, v183 row_newbcast:4 row_mask:0xf bank_mask:0xf
	v_fmac_f32_dpp v227, v7, v184 row_newbcast:5 row_mask:0xf bank_mask:0xf
	v_fmac_f32_dpp v1, v7, v185 row_newbcast:6 row_mask:0xf bank_mask:0xf
	v_fmac_f32_dpp v231, v7, v186 row_newbcast:7 row_mask:0xf bank_mask:0xf
	v_fmac_f32_dpp v227, v7, v187 row_newbcast:8 row_mask:0xf bank_mask:0xf
	v_fmac_f32_dpp v1, v7, v188 row_newbcast:9 row_mask:0xf bank_mask:0xf
	v_fmac_f32_dpp v231, v7, v189 row_newbcast:10 row_mask:0xf bank_mask:0xf
	v_fmac_f32_dpp v227, v7, v190 row_newbcast:11 row_mask:0xf bank_mask:0xf
	v_fmac_f32_dpp v1, v7, v191 row_newbcast:12 row_mask:0xf bank_mask:0xf
	v_fmac_f32_dpp v231, v7, v192 row_newbcast:13 row_mask:0xf bank_mask:0xf
	v_fmac_f32_dpp v227, v7, v193 row_newbcast:14 row_mask:0xf bank_mask:0xf
	v_fmac_f32_dpp v1, v7, v194 row_newbcast:15 row_mask:0xf bank_mask:0xf
	v_fmac_f32_dpp v231, v2, v195 row_newbcast:0 row_mask:0xf bank_mask:0xf
	v_fmac_f32_dpp v227, v2, v196 row_newbcast:1 row_mask:0xf bank_mask:0xf
	v_fmac_f32_dpp v1, v2, v197 row_newbcast:2 row_mask:0xf bank_mask:0xf
	v_fmac_f32_dpp v231, v2, v198 row_newbcast:3 row_mask:0xf bank_mask:0xf
	v_fmac_f32_dpp v227, v2, v199 row_newbcast:4 row_mask:0xf bank_mask:0xf
	v_fmac_f32_dpp v1, v2, v200 row_newbcast:5 row_mask:0xf bank_mask:0xf
	v_fmac_f32_dpp v231, v2, v201 row_newbcast:6 row_mask:0xf bank_mask:0xf
	v_fmac_f32_dpp v227, v2, v202 row_newbcast:7 row_mask:0xf bank_mask:0xf
	v_fmac_f32_dpp v1, v2, v203 row_newbcast:8 row_mask:0xf bank_mask:0xf
	v_fmac_f32_dpp v231, v2, v204 row_newbcast:9 row_mask:0xf bank_mask:0xf
	v_fmac_f32_dpp v227, v2, v205 row_newbcast:10 row_mask:0xf bank_mask:0xf
	v_fmac_f32_dpp v1, v2, v206 row_newbcast:11 row_mask:0xf bank_mask:0xf
	v_fmac_f32_dpp v231, v2, v207 row_newbcast:12 row_mask:0xf bank_mask:0xf
	v_fmac_f32_dpp v227, v2, v208 row_newbcast:13 row_mask:0xf bank_mask:0xf
	v_fmac_f32_dpp v1, v2, v209 row_newbcast:14 row_mask:0xf bank_mask:0xf
	v_fmac_f32_dpp v231, v2, v210 row_newbcast:15 row_mask:0xf bank_mask:0xf
	v_fmac_f32_dpp v227, v3, v211 row_newbcast:0 row_mask:0xf bank_mask:0xf
	v_fmac_f32_dpp v1, v3, v212 row_newbcast:1 row_mask:0xf bank_mask:0xf
; __device__ __forceinline__ void gdn_prep_item(const Params& p, unsigned char* lds, int item, u32x4 (&raw)[3][2][4], float& gpre, float& bpre, int next_item) {
;     ...
; #pragma unroll
;         for (int i = 0; i < 64; ++i) base[i * RS] = xs[i];
	v_fmac_f32_dpp v231, v3, v213 row_newbcast:2 row_mask:0xf bank_mask:0xf
	v_fmac_f32_dpp v227, v3, v214 row_newbcast:3 row_mask:0xf bank_mask:0xf
	v_fmac_f32_dpp v1, v3, v215 row_newbcast:4 row_mask:0xf bank_mask:0xf
	v_fmac_f32_dpp v231, v3, v216 row_newbcast:5 row_mask:0xf bank_mask:0xf
	v_fmac_f32_dpp v227, v3, v217 row_newbcast:6 row_mask:0xf bank_mask:0xf
	v_fmac_f32_dpp v1, v3, v218 row_newbcast:7 row_mask:0xf bank_mask:0xf
	v_fmac_f32_dpp v231, v3, v219 row_newbcast:8 row_mask:0xf bank_mask:0xf
	v_fmac_f32_dpp v227, v3, v221 row_newbcast:9 row_mask:0xf bank_mask:0xf
	v_fmac_f32_dpp v1, v3, v224 row_newbcast:10 row_mask:0xf bank_mask:0xf
	v_fmac_f32_dpp v231, v3, v225 row_newbcast:11 row_mask:0xf bank_mask:0xf
	v_fmac_f32_dpp v227, v3, v226 row_newbcast:12 row_mask:0xf bank_mask:0xf
	v_fmac_f32_dpp v1, v3, v228 row_newbcast:13 row_mask:0xf bank_mask:0xf
	v_fmac_f32_dpp v231, v3, v0 row_newbcast:14 row_mask:0xf bank_mask:0xf
	s_nop 0
	v_add_f32_e32 v1, v1, v227
	v_add_f32_e32 v1, v1, v231
	v_add_u32_e32 v2, 0x400, v154
	ds_write2_b32 v2, v10, v11 offset0:8 offset1:140
	v_add_u32_e32 v2, 0x800, v154
	ds_write2_b32 v2, v12, v13 offset0:16 offset1:148
	v_add_u32_e32 v2, 0xc00, v154
	ds_write2_b32 v2, v14, v15 offset0:24 offset1:156
	v_add_u32_e32 v2, 0x1000, v154
	ds_write2_b32 v2, v17, v18 offset0:32 offset1:164
	v_add_u32_e32 v2, 0x1400, v154
	ds_write2_b32 v2, v19, v174 offset0:40 offset1:172
	v_add_u32_e32 v2, 0x1800, v154
	ds_write2_b32 v2, v175, v176 offset0:48 offset1:180
	v_add_u32_e32 v2, 0x1c00, v154
	ds_write2_b32 v2, v177, v178 offset0:56 offset1:188
	v_add_u32_e32 v2, 0x2000, v154
	ds_write2_b32 v2, v179, v180 offset0:64 offset1:196
	v_add_u32_e32 v2, 0x2400, v154
	ds_write2_b32 v2, v181, v182 offset0:72 offset1:204
	v_add_u32_e32 v2, 0x2800, v154
	ds_write2_b32 v2, v183, v184 offset0:80 offset1:212
	v_add_u32_e32 v2, 0x2c00, v154
	ds_write2_b32 v2, v185, v186 offset0:88 offset1:220
	v_add_u32_e32 v2, 0x3000, v154
	ds_write2_b32 v2, v187, v188 offset0:96 offset1:228
	v_add_u32_e32 v2, 0x3400, v154
	ds_write2_b32 v2, v189, v190 offset0:104 offset1:236
	v_add_u32_e32 v2, 0x3800, v154
	ds_write2_b32 v2, v191, v192 offset0:112 offset1:244
	v_add_u32_e32 v2, 0x3c00, v154
	ds_write2_b32 v2, v193, v194 offset0:120 offset1:252
	v_add_u32_e32 v2, 0x4200, v154
	ds_write2_b32 v2, v195, v196 offset1:132
	v_add_u32_e32 v2, 0x4600, v154
	ds_write2_b32 v2, v197, v198 offset0:8 offset1:140
	v_add_u32_e32 v2, 0x4a00, v154
	ds_write2_b32 v2, v199, v200 offset0:16 offset1:148
	v_add_u32_e32 v2, 0x4e00, v154
	ds_write2_b32 v2, v201, v202 offset0:24 offset1:156
	v_add_u32_e32 v2, 0x5200, v154
	ds_write2_b32 v2, v203, v204 offset0:32 offset1:164
	v_add_u32_e32 v2, 0x5600, v154
	ds_write2_b32 v2, v205, v206 offset0:40 offset1:172
	v_add_u32_e32 v2, 0x5a00, v154
	ds_write2_b32 v2, v207, v208 offset0:48 offset1:180
	v_add_u32_e32 v2, 0x5e00, v154
	ds_write2_b32 v2, v209, v210 offset0:56 offset1:188
	v_add_u32_e32 v2, 0x6200, v154
	ds_write2_b32 v2, v211, v212 offset0:64 offset1:196
	v_add_u32_e32 v2, 0x6600, v154
	ds_write2_b32 v2, v213, v214 offset0:72 offset1:204
	v_add_u32_e32 v2, 0x6a00, v154
	ds_write2_b32 v2, v215, v216 offset0:80 offset1:212
	v_add_u32_e32 v2, 0x6e00, v154
	ds_write2_b32 v2, v217, v218 offset0:88 offset1:220
	v_add_u32_e32 v2, 0x7200, v154
	ds_write2_b32 v2, v219, v221 offset0:96 offset1:228
	v_add_u32_e32 v2, 0x7600, v154
	ds_write2_b32 v2, v224, v225 offset0:104 offset1:236
	v_add_u32_e32 v2, 0x7a00, v154
	ds_write2_b32 v2, v226, v228 offset0:112 offset1:244
	v_add_u32_e32 v2, 0x7e00, v154
	ds_write2_b32 v154, v8, v9 offset1:132
	ds_write2_b32 v2, v0, v1 offset0:120 offset1:252
	s_branch .LBB0_102
